# K-loop: first two phase waits after an epilogue relaxed to vmcnt(8+stores) via per-wave flag (GU and W_in), on top of fused-epilogue load hoist
# speedup vs baseline: 1.0085x; 1.0085x over previous
.LBB0_64:
	s_mov_b64 s[12:13], 0x80
	s_add_i32 m0, s29, 0x18000
	v_lshl_add_u64 v[6:7], v[6:7], 0, s[12:13]
	s_waitcnt vmcnt(2)
	s_barrier
	global_load_lds_dwordx4 v[6:7], off
	v_lshl_add_u64 v[6:7], v[8:9], 0, s[12:13]
	s_add_i32 m0, s29, 0x1a000
	s_add_i32 s36, s29, 0x8000
	global_load_lds_dwordx4 v[6:7], off
	v_lshl_add_u64 v[6:7], v[10:11], 0, s[12:13]
	s_mov_b32 m0, s36
	s_add_i32 s37, s29, 0xa000
	global_load_lds_dwordx4 v[6:7], off
	v_lshl_add_u64 v[6:7], v[12:13], 0, s[12:13]
	s_mov_b32 m0, s37
	s_mov_b64 s[14:15], 0x40080
	global_load_lds_dwordx4 v[6:7], off
	v_lshl_add_u64 v[6:7], v[2:3], 0, s[14:15]
	s_add_i32 m0, s29, 0x1c000
	v_lshl_add_u64 v[8:9], v[6:7], 0, v[136:137]
	global_load_lds_dwordx4 v[8:9], off
	v_lshl_add_u64 v[6:7], v[6:7], 0, v[140:141]
	s_add_i32 m0, s29, 0x1e000
	s_mov_b64 s[16:17], 0xd000000
	global_load_lds_dwordx4 v[6:7], off
	v_lshl_add_u64 v[142:143], v[4:5], 0, s[16:17]
	v_lshrrev_b32_e32 v5, 1, v14
	v_and_b32_e32 v5, 24, v5
	v_and_b32_e32 v4, 15, v14
	v_lshlrev_b32_e32 v6, 1, v5
	v_lshl_or_b32 v166, s6, 6, v4
	v_lshl_or_b32 v4, v4, 6, v6
	v_lshlrev_b32_e32 v6, 2, v14
	s_lshl_b32 s5, s5, 5
	s_lshl_b32 s6, s6, 13
	v_and_b32_e32 v6, 32, v6
	s_and_b32 s5, s5, 0x60
	v_bitop3_b32 v7, v4, s6, v6 bitop3:0xde
	s_lshl_b32 s6, s5, 7
	v_bitop3_b32 v167, v4, s6, v6 bitop3:0xde
	v_lshlrev_b32_e32 v4, 14, v18
	v_and_b32_e32 v4, 0xffff8000, v4
	v_or_b32_e32 v169, s5, v5
	v_lshl_add_u32 v4, v19, 11, v4
	v_and_b32_e32 v5, 1, v18
	v_lshl_or_b32 v4, v5, 6, v4
	v_lshl_add_u32 v144, v20, 1, v4
	v_lshlrev_b32_e32 v4, 14, v15
	v_and_b32_e32 v4, 0xffff8000, v4
	s_waitcnt vmcnt(6)
	s_cmpk_lt_u32 s4, 0x100
	v_lshl_add_u32 v4, v16, 11, v4
	v_and_b32_e32 v5, 1, v15
	s_cselect_b64 s[16:17], -1, 0
	s_add_i32 s4, 0, 0x21c00
	v_lshl_or_b32 v4, v5, 6, v4
	s_mov_b32 s20, 0xfffc0080
	s_mov_b32 s48, 0
	s_ashr_i32 s38, s68, 31
	v_lshl_add_u32 v168, v166, 4, s4
	v_mov_b32_e32 v145, v137
	v_lshl_add_u32 v146, v17, 1, v4
	v_mov_b32_e32 v147, v137
	v_mov_b64_e32 v[148:149], 0xb00
	v_mov_b64_e32 v[150:151], 0xaff
	s_movk_i32 s39, 0x161
	s_mov_b64 s[18:19], 0x100
	s_mov_b32 s21, -1
	s_add_i32 s42, 0, 0x10000
	s_add_i32 s43, 0, 0x14000
	v_add_u32_e32 v170, 0, v7
	s_movk_i32 s44, 0x1600
	v_mov_b32_e32 v171, 0x358637bd
	s_mov_b32 s45, 0x800000
	s_mov_b32 s46, 0
	s_barrier
	s_mov_b32 s100, 0
	s_branch .LBB0_67

.LBB0_70:
	v_add_u32_e32 v186, s42, v167
	v_add_u32_e32 v202, s43, v167
	ds_read_b128 v[172:175], v186
	ds_read_b128 v[178:181], v186 offset:1024
	ds_read_b128 v[182:185], v186 offset:2048
	ds_read_b128 v[186:189], v186 offset:3072
	ds_read_b128 v[190:193], v202
	ds_read_b128 v[194:197], v202 offset:1024
	ds_read_b128 v[198:201], v202 offset:2048
	ds_read_b128 v[202:205], v202 offset:3072
	v_lshl_add_u64 v[206:207], v[162:163], 0, s[20:21]
	v_cndmask_b32_e64 v239, v207, v157, s[6:7]
	v_cndmask_b32_e64 v238, v206, v156, s[6:7]
	v_cndmask_b32_e64 v241, v161, v159, s[6:7]
	v_cndmask_b32_e64 v240, v160, v158, s[6:7]
	v_lshl_add_u64 v[242:243], v[162:163], 0, v[146:147]
	s_add_i32 m0, s29, 0xc000
	ds_read_b128 v[206:209], v170
	ds_read_b128 v[210:213], v170 offset:1024
	ds_read_b128 v[214:217], v170 offset:2048
	ds_read_b128 v[218:221], v170 offset:3072
	ds_read_b128 v[222:225], v170 offset:4096
	ds_read_b128 v[226:229], v170 offset:5120
	ds_read_b128 v[230:233], v170 offset:6144
	ds_read_b128 v[234:237], v170 offset:7168
	global_load_lds_dwordx4 v[242:243], off
	v_lshl_add_u64 v[242:243], v[162:163], 0, v[144:145]
	s_add_i32 m0, s29, 0xe000
	s_nop 0
	global_load_lds_dwordx4 v[242:243], off
	s_cmp_eq_u32 s100, 0
	s_cbranch_scc1 .Lgw8_3627_0
	s_waitcnt vmcnt(16)
	s_branch .Lgwd_3627_0
.Lgw8_3627_0:
	s_waitcnt vmcnt(8)
.Lgwd_3627_0:
	s_waitcnt lgkmcnt(0)
	s_barrier
	s_setprio 1
	s_waitcnt lgkmcnt(0)
	v_mfma_f32_16x16x32_bf16 v[124:127], v[172:175], v[206:209], v[124:127]
	v_mfma_f32_16x16x32_bf16 v[116:119], v[182:185], v[206:209], v[116:119]
	v_mfma_f32_16x16x32_bf16 v[108:111], v[172:175], v[214:217], v[108:111]
	v_mfma_f32_16x16x32_bf16 v[100:103], v[182:185], v[214:217], v[100:103]
	v_mfma_f32_16x16x32_bf16 v[92:95], v[172:175], v[222:225], v[92:95]
	v_mfma_f32_16x16x32_bf16 v[84:87], v[182:185], v[222:225], v[84:87]
	v_mfma_f32_16x16x32_bf16 v[76:79], v[172:175], v[230:233], v[76:79]
	v_mfma_f32_16x16x32_bf16 v[68:71], v[182:185], v[230:233], v[68:71]
	v_mfma_f32_16x16x32_bf16 v[124:127], v[178:181], v[210:213], v[124:127]
	v_mfma_f32_16x16x32_bf16 v[116:119], v[186:189], v[210:213], v[116:119]
	v_mfma_f32_16x16x32_bf16 v[108:111], v[178:181], v[218:221], v[108:111]
	v_mfma_f32_16x16x32_bf16 v[100:103], v[186:189], v[218:221], v[100:103]
	v_mfma_f32_16x16x32_bf16 v[92:95], v[178:181], v[226:229], v[92:95]
	v_mfma_f32_16x16x32_bf16 v[84:87], v[186:189], v[226:229], v[84:87]
	v_mfma_f32_16x16x32_bf16 v[76:79], v[178:181], v[234:237], v[76:79]
	v_mfma_f32_16x16x32_bf16 v[68:71], v[186:189], v[234:237], v[68:71]
	s_setprio 0
	s_setprio 1
	v_mfma_f32_16x16x32_bf16 v[120:123], v[190:193], v[206:209], v[120:123]
	v_mfma_f32_16x16x32_bf16 v[112:115], v[198:201], v[206:209], v[112:115]
	v_mfma_f32_16x16x32_bf16 v[104:107], v[190:193], v[214:217], v[104:107]
	v_mfma_f32_16x16x32_bf16 v[96:99], v[198:201], v[214:217], v[96:99]
	v_mfma_f32_16x16x32_bf16 v[88:91], v[190:193], v[222:225], v[88:91]
	v_mfma_f32_16x16x32_bf16 v[80:83], v[198:201], v[222:225], v[80:83]
	v_mfma_f32_16x16x32_bf16 v[72:75], v[190:193], v[230:233], v[72:75]
	v_mfma_f32_16x16x32_bf16 v[64:67], v[198:201], v[230:233], v[64:67]
	v_mfma_f32_16x16x32_bf16 v[120:123], v[194:197], v[210:213], v[120:123]
	v_mfma_f32_16x16x32_bf16 v[112:115], v[202:205], v[210:213], v[112:115]
	v_mfma_f32_16x16x32_bf16 v[104:107], v[194:197], v[218:221], v[104:107]
	v_mfma_f32_16x16x32_bf16 v[96:99], v[202:205], v[218:221], v[96:99]
	v_mfma_f32_16x16x32_bf16 v[88:91], v[194:197], v[226:229], v[88:91]
	v_mfma_f32_16x16x32_bf16 v[80:83], v[202:205], v[226:229], v[80:83]
	v_mfma_f32_16x16x32_bf16 v[72:75], v[194:197], v[234:237], v[72:75]
	v_mfma_f32_16x16x32_bf16 v[64:67], v[202:205], v[234:237], v[64:67]
	s_setprio 0
	s_barrier
	s_add_i32 s6, s42, s3
	v_lshl_add_u64 v[242:243], v[240:241], 0, v[136:137]
	s_mov_b32 m0, s6
	ds_read_b128 v[206:209], v170 offset:16384
	ds_read_b128 v[210:213], v170 offset:17408
	ds_read_b128 v[214:217], v170 offset:18432
	ds_read_b128 v[218:221], v170 offset:19456
	ds_read_b128 v[222:225], v170 offset:20480
	ds_read_b128 v[226:229], v170 offset:21504
	ds_read_b128 v[230:233], v170 offset:22528
	ds_read_b128 v[234:237], v170 offset:23552
	global_load_lds_dwordx4 v[242:243], off
	v_lshl_add_u64 v[244:245], v[240:241], 0, v[140:141]
	s_add_i32 m0, s6, 0x2000
	v_lshl_add_u64 v[246:247], v[240:241], 0, s[8:9]
	s_add_i32 s6, s43, s3
	global_load_lds_dwordx4 v[244:245], off
	v_lshl_add_u64 v[248:249], v[246:247], 0, v[136:137]
	s_mov_b32 m0, s6
	v_lshl_add_u64 v[246:247], v[246:247], 0, v[140:141]
	global_load_lds_dwordx4 v[248:249], off
	s_add_i32 m0, s6, 0x2000
	v_lshl_add_u64 v[248:249], v[238:239], 0, v[138:139]
	global_load_lds_dwordx4 v[246:247], off
	v_lshl_add_u64 v[246:247], v[238:239], 0, v[134:135]
	s_mov_b32 m0, s29
	s_nop 0
	global_load_lds_dwordx4 v[246:247], off
	s_mov_b32 m0, s31
	s_nop 0
	global_load_lds_dwordx4 v[248:249], off
	s_cmp_eq_u32 s100, 0
	s_cbranch_scc1 .Lgw8_3627_1
	s_waitcnt vmcnt(16)
	s_mov_b32 s100, 0
	s_branch .Lgwd_3627_1

.Lgwd_3627_1:
	s_waitcnt lgkmcnt(0)
	s_barrier
	s_setprio 1
	s_waitcnt lgkmcnt(0)
	v_mfma_f32_16x16x32_bf16 v[60:63], v[172:175], v[206:209], v[60:63]
	v_mfma_f32_16x16x32_bf16 v[52:55], v[182:185], v[206:209], v[52:55]
	v_mfma_f32_16x16x32_bf16 v[44:47], v[172:175], v[214:217], v[44:47]
	v_mfma_f32_16x16x32_bf16 v[36:39], v[182:185], v[214:217], v[36:39]
	v_mfma_f32_16x16x32_bf16 v[28:31], v[172:175], v[222:225], v[28:31]
	v_mfma_f32_16x16x32_bf16 v[20:23], v[182:185], v[222:225], v[20:23]
	v_mfma_f32_16x16x32_bf16 v[12:15], v[172:175], v[230:233], v[12:15]
	v_mfma_f32_16x16x32_bf16 v[4:7], v[182:185], v[230:233], v[4:7]
	v_mfma_f32_16x16x32_bf16 v[60:63], v[178:181], v[210:213], v[60:63]
	v_mfma_f32_16x16x32_bf16 v[52:55], v[186:189], v[210:213], v[52:55]
	v_mfma_f32_16x16x32_bf16 v[44:47], v[178:181], v[218:221], v[44:47]
	v_mfma_f32_16x16x32_bf16 v[36:39], v[186:189], v[218:221], v[36:39]
	v_mfma_f32_16x16x32_bf16 v[28:31], v[178:181], v[226:229], v[28:31]
	v_mfma_f32_16x16x32_bf16 v[20:23], v[186:189], v[226:229], v[20:23]
	v_mfma_f32_16x16x32_bf16 v[12:15], v[178:181], v[234:237], v[12:15]
	v_mfma_f32_16x16x32_bf16 v[4:7], v[186:189], v[234:237], v[4:7]
	s_setprio 0
	s_setprio 1
	v_mfma_f32_16x16x32_bf16 v[56:59], v[190:193], v[206:209], v[56:59]
	v_mfma_f32_16x16x32_bf16 v[48:51], v[198:201], v[206:209], v[48:51]
	v_mfma_f32_16x16x32_bf16 v[40:43], v[190:193], v[214:217], v[40:43]
	v_mfma_f32_16x16x32_bf16 v[32:35], v[198:201], v[214:217], v[32:35]
	v_mfma_f32_16x16x32_bf16 v[24:27], v[190:193], v[222:225], v[24:27]
	v_mfma_f32_16x16x32_bf16 v[16:19], v[198:201], v[222:225], v[16:19]
	v_mfma_f32_16x16x32_bf16 v[8:11], v[190:193], v[230:233], v[8:11]
	v_mfma_f32_16x16x32_bf16 v[0:3], v[198:201], v[230:233], v[0:3]
	v_mfma_f32_16x16x32_bf16 v[56:59], v[194:197], v[210:213], v[56:59]
	v_mfma_f32_16x16x32_bf16 v[48:51], v[202:205], v[210:213], v[48:51]
	v_mfma_f32_16x16x32_bf16 v[40:43], v[194:197], v[218:221], v[40:43]
	v_mfma_f32_16x16x32_bf16 v[32:35], v[202:205], v[218:221], v[32:35]
	v_mfma_f32_16x16x32_bf16 v[24:27], v[194:197], v[226:229], v[24:27]
	v_mfma_f32_16x16x32_bf16 v[16:19], v[202:205], v[226:229], v[16:19]
	v_mfma_f32_16x16x32_bf16 v[8:11], v[194:197], v[234:237], v[8:11]
	v_mfma_f32_16x16x32_bf16 v[0:3], v[202:205], v[234:237], v[0:3]
	s_setprio 0
	s_barrier
	s_add_i32 s6, 0, 0x18000
	s_add_i32 s7, 0, 0x1c000
	v_add_u32_e32 v186, s6, v167
	v_add_u32_e32 v202, s7, v167
	ds_read_b128 v[172:175], v186
	ds_read_b128 v[178:181], v186 offset:1024
	ds_read_b128 v[182:185], v186 offset:2048
	ds_read_b128 v[186:189], v186 offset:3072
	ds_read_b128 v[190:193], v202
	ds_read_b128 v[194:197], v202 offset:1024
	ds_read_b128 v[198:201], v202 offset:2048
	ds_read_b128 v[202:205], v202 offset:3072
	v_lshl_add_u64 v[238:239], v[238:239], 0, s[8:9]
	s_mov_b32 m0, s34
	v_lshl_add_u64 v[250:251], v[238:239], 0, v[134:135]
	ds_read_b128 v[206:209], v170 offset:32768
	ds_read_b128 v[210:213], v170 offset:33792
	ds_read_b128 v[214:217], v170 offset:34816
	ds_read_b128 v[218:221], v170 offset:35840
	ds_read_b128 v[222:225], v170 offset:36864
	ds_read_b128 v[226:229], v170 offset:37888
	ds_read_b128 v[230:233], v170 offset:38912
	ds_read_b128 v[234:237], v170 offset:39936
	global_load_lds_dwordx4 v[250:251], off
	v_lshl_add_u64 v[238:239], v[238:239], 0, v[138:139]
	s_mov_b32 m0, s35
	s_nop 0
	global_load_lds_dwordx4 v[238:239], off
	s_waitcnt vmcnt(8)
	s_waitcnt lgkmcnt(0)
	s_barrier
	s_setprio 1
	s_waitcnt lgkmcnt(0)
	v_mfma_f32_16x16x32_bf16 v[124:127], v[172:175], v[206:209], v[124:127]
	v_mfma_f32_16x16x32_bf16 v[116:119], v[182:185], v[206:209], v[116:119]
	v_mfma_f32_16x16x32_bf16 v[108:111], v[172:175], v[214:217], v[108:111]
	v_mfma_f32_16x16x32_bf16 v[100:103], v[182:185], v[214:217], v[100:103]
	v_mfma_f32_16x16x32_bf16 v[92:95], v[172:175], v[222:225], v[92:95]
	v_mfma_f32_16x16x32_bf16 v[84:87], v[182:185], v[222:225], v[84:87]
	v_mfma_f32_16x16x32_bf16 v[76:79], v[172:175], v[230:233], v[76:79]
	v_mfma_f32_16x16x32_bf16 v[68:71], v[182:185], v[230:233], v[68:71]
	v_mfma_f32_16x16x32_bf16 v[124:127], v[178:181], v[210:213], v[124:127]
	v_mfma_f32_16x16x32_bf16 v[116:119], v[186:189], v[210:213], v[116:119]
	v_mfma_f32_16x16x32_bf16 v[108:111], v[178:181], v[218:221], v[108:111]
	v_mfma_f32_16x16x32_bf16 v[100:103], v[186:189], v[218:221], v[100:103]
	v_mfma_f32_16x16x32_bf16 v[92:95], v[178:181], v[226:229], v[92:95]
	v_mfma_f32_16x16x32_bf16 v[84:87], v[186:189], v[226:229], v[84:87]
	v_mfma_f32_16x16x32_bf16 v[76:79], v[178:181], v[234:237], v[76:79]
	v_mfma_f32_16x16x32_bf16 v[68:71], v[186:189], v[234:237], v[68:71]
	s_setprio 0
	s_setprio 1
	v_mfma_f32_16x16x32_bf16 v[120:123], v[190:193], v[206:209], v[120:123]
	v_mfma_f32_16x16x32_bf16 v[112:115], v[198:201], v[206:209], v[112:115]
	v_mfma_f32_16x16x32_bf16 v[104:107], v[190:193], v[214:217], v[104:107]
	v_mfma_f32_16x16x32_bf16 v[96:99], v[198:201], v[214:217], v[96:99]
	v_mfma_f32_16x16x32_bf16 v[88:91], v[190:193], v[222:225], v[88:91]
	v_mfma_f32_16x16x32_bf16 v[80:83], v[198:201], v[222:225], v[80:83]
	v_mfma_f32_16x16x32_bf16 v[72:75], v[190:193], v[230:233], v[72:75]
	v_mfma_f32_16x16x32_bf16 v[64:67], v[198:201], v[230:233], v[64:67]
	v_mfma_f32_16x16x32_bf16 v[120:123], v[194:197], v[210:213], v[120:123]
	v_mfma_f32_16x16x32_bf16 v[112:115], v[202:205], v[210:213], v[112:115]
	v_mfma_f32_16x16x32_bf16 v[104:107], v[194:197], v[218:221], v[104:107]
	v_mfma_f32_16x16x32_bf16 v[96:99], v[202:205], v[218:221], v[96:99]
	v_mfma_f32_16x16x32_bf16 v[88:91], v[194:197], v[226:229], v[88:91]
	v_mfma_f32_16x16x32_bf16 v[80:83], v[202:205], v[226:229], v[80:83]
	v_mfma_f32_16x16x32_bf16 v[72:75], v[194:197], v[234:237], v[72:75]
	v_mfma_f32_16x16x32_bf16 v[64:67], v[202:205], v[234:237], v[64:67]
	s_setprio 0
	s_barrier
	s_add_i32 s6, s6, s3
	v_lshl_add_u64 v[238:239], v[242:243], 0, s[12:13]
	s_mov_b32 m0, s6
	ds_read_b128 v[206:209], v170 offset:49152
	ds_read_b128 v[210:213], v170 offset:50176
	ds_read_b128 v[214:217], v170 offset:51200
	ds_read_b128 v[218:221], v170 offset:52224
	ds_read_b128 v[222:225], v170 offset:53248
	ds_read_b128 v[226:229], v170 offset:54272
	ds_read_b128 v[230:233], v170 offset:55296
	ds_read_b128 v[234:237], v170 offset:56320
	global_load_lds_dwordx4 v[238:239], off
	v_lshl_add_u64 v[238:239], v[244:245], 0, s[12:13]
	s_add_i32 m0, s6, 0x2000
	s_add_i32 s6, s7, s3
	global_load_lds_dwordx4 v[238:239], off
	v_lshl_add_u64 v[238:239], v[240:241], 0, s[14:15]
	v_lshl_add_u64 v[240:241], v[238:239], 0, v[136:137]
	s_mov_b32 m0, s6
	v_lshl_add_u64 v[238:239], v[238:239], 0, v[140:141]
	global_load_lds_dwordx4 v[240:241], off
	s_add_i32 m0, s6, 0x2000
	s_nop 0
	global_load_lds_dwordx4 v[238:239], off
	v_lshl_add_u64 v[238:239], v[246:247], 0, s[12:13]
	s_mov_b32 m0, s36
	s_nop 0
	global_load_lds_dwordx4 v[238:239], off
	v_lshl_add_u64 v[238:239], v[248:249], 0, s[12:13]
	s_mov_b32 m0, s37
	s_nop 0
	global_load_lds_dwordx4 v[238:239], off
	s_waitcnt vmcnt(8)
	s_waitcnt lgkmcnt(0)
	s_barrier
	s_setprio 1
	s_waitcnt lgkmcnt(0)
	v_mfma_f32_16x16x32_bf16 v[60:63], v[172:175], v[206:209], v[60:63]
	v_mfma_f32_16x16x32_bf16 v[52:55], v[182:185], v[206:209], v[52:55]
	v_mfma_f32_16x16x32_bf16 v[44:47], v[172:175], v[214:217], v[44:47]
	v_mfma_f32_16x16x32_bf16 v[36:39], v[182:185], v[214:217], v[36:39]
	v_mfma_f32_16x16x32_bf16 v[28:31], v[172:175], v[222:225], v[28:31]
	v_mfma_f32_16x16x32_bf16 v[20:23], v[182:185], v[222:225], v[20:23]
	v_mfma_f32_16x16x32_bf16 v[12:15], v[172:175], v[230:233], v[12:15]
	v_mfma_f32_16x16x32_bf16 v[4:7], v[182:185], v[230:233], v[4:7]
	v_mfma_f32_16x16x32_bf16 v[60:63], v[178:181], v[210:213], v[60:63]
	v_mfma_f32_16x16x32_bf16 v[52:55], v[186:189], v[210:213], v[52:55]
	v_mfma_f32_16x16x32_bf16 v[44:47], v[178:181], v[218:221], v[44:47]
	v_mfma_f32_16x16x32_bf16 v[36:39], v[186:189], v[218:221], v[36:39]
	v_mfma_f32_16x16x32_bf16 v[28:31], v[178:181], v[226:229], v[28:31]
	v_mfma_f32_16x16x32_bf16 v[20:23], v[186:189], v[226:229], v[20:23]
	v_mfma_f32_16x16x32_bf16 v[12:15], v[178:181], v[234:237], v[12:15]
	v_mfma_f32_16x16x32_bf16 v[4:7], v[186:189], v[234:237], v[4:7]
	s_setprio 0
	s_setprio 1
	v_mfma_f32_16x16x32_bf16 v[56:59], v[190:193], v[206:209], v[56:59]
	v_mfma_f32_16x16x32_bf16 v[48:51], v[198:201], v[206:209], v[48:51]
	v_mfma_f32_16x16x32_bf16 v[40:43], v[190:193], v[214:217], v[40:43]
	v_mfma_f32_16x16x32_bf16 v[32:35], v[198:201], v[214:217], v[32:35]
	v_mfma_f32_16x16x32_bf16 v[24:27], v[190:193], v[222:225], v[24:27]
	v_mfma_f32_16x16x32_bf16 v[16:19], v[198:201], v[222:225], v[16:19]
	v_mfma_f32_16x16x32_bf16 v[8:11], v[190:193], v[230:233], v[8:11]
	v_mfma_f32_16x16x32_bf16 v[0:3], v[198:201], v[230:233], v[0:3]
	v_mfma_f32_16x16x32_bf16 v[56:59], v[194:197], v[210:213], v[56:59]
	v_mfma_f32_16x16x32_bf16 v[48:51], v[202:205], v[210:213], v[48:51]
	v_mfma_f32_16x16x32_bf16 v[40:43], v[194:197], v[218:221], v[40:43]
	v_mfma_f32_16x16x32_bf16 v[32:35], v[202:205], v[218:221], v[32:35]
	v_mfma_f32_16x16x32_bf16 v[24:27], v[194:197], v[226:229], v[24:27]
	v_mfma_f32_16x16x32_bf16 v[16:19], v[202:205], v[226:229], v[16:19]
	v_mfma_f32_16x16x32_bf16 v[8:11], v[194:197], v[234:237], v[8:11]
	v_mfma_f32_16x16x32_bf16 v[0:3], v[202:205], v[234:237], v[0:3]
	s_setprio 0
	s_barrier
	s_add_i32 s27, s27, 2
	v_lshl_add_u64 v[160:161], v[160:161], 0, s[18:19]
	s_cmp_gt_u32 s27, 13
	v_lshl_add_u64 v[162:163], v[162:163], 0, s[18:19]
	s_cbranch_scc1 .LBB0_74

.LBB0_76:
	v_lshl_add_u32 v156, s48, 12, v168
	ds_read_b128 v[158:161], v156
	v_pk_mul_f32 v[120:121], v[124:125], v[120:121]
	v_pk_mul_f32 v[122:123], v[126:127], v[122:123]
	v_pk_mul_f32 v[112:113], v[116:117], v[112:113]
	v_pk_mul_f32 v[114:115], v[118:119], v[114:115]
	s_waitcnt lgkmcnt(0)
	v_mov_b32_e32 v162, v159
	v_mov_b32_e32 v163, v160
	v_mov_b32_e32 v159, v161
	v_pk_add_f32 v[158:159], v[162:163], v[158:159]
	v_pk_mul_f32 v[104:105], v[108:109], v[104:105]
	v_add_f32_e32 v157, v158, v159
	v_fmamk_f32 v157, v157, 0x3a800000, v171
	v_mul_f32_e32 v158, 0x4b800000, v157
	v_cmp_gt_f32_e32 vcc, s45, v157
	v_pk_mul_f32 v[106:107], v[110:111], v[106:107]
	v_pk_mul_f32 v[96:97], v[100:101], v[96:97]
	v_cndmask_b32_e32 v157, v157, v158, vcc
	v_rsq_f32_e32 v157, v157
	v_pk_mul_f32 v[98:99], v[102:103], v[98:99]
	v_pk_mul_f32 v[88:89], v[92:93], v[88:89]
	v_pk_mul_f32 v[90:91], v[94:95], v[90:91]
	v_mul_f32_e32 v158, 0x45800000, v157
	v_cndmask_b32_e32 v157, v157, v158, vcc
	v_mul_f32_e32 v158, 0xbfb8aa3b, v157
	v_pk_mul_f32 v[124:125], v[124:125], v[158:159] op_sel_hi:[1,0]
	v_pk_mul_f32 v[126:127], v[126:127], v[158:159] op_sel_hi:[1,0]
	v_exp_f32_e32 v124, v124
	v_exp_f32_e32 v125, v125
	v_exp_f32_e32 v126, v126
	v_exp_f32_e32 v127, v127
	v_mul_f32_e32 v160, v157, v157
	v_pk_add_f32 v[124:125], v[124:125], 1.0 op_sel_hi:[1,0]
	v_pk_mul_f32 v[120:121], v[120:121], v[160:161] op_sel_hi:[1,0]
	v_rcp_f32_e32 v124, v124
	v_rcp_f32_e32 v125, v125
	v_pk_add_f32 v[126:127], v[126:127], 1.0 op_sel_hi:[1,0]
	v_pk_mul_f32 v[122:123], v[122:123], v[160:161] op_sel_hi:[1,0]
	v_pk_mul_f32 v[112:113], v[112:113], v[160:161] op_sel_hi:[1,0]
	v_pk_mul_f32 v[120:121], v[120:121], v[124:125]
	v_rcp_f32_e32 v124, v126
	v_rcp_f32_e32 v125, v127
	v_pk_mul_f32 v[126:127], v[116:117], v[158:159] op_sel_hi:[1,0]
	v_cvt_pk_bf16_f32 v120, v120, v121
	v_pk_mul_f32 v[80:81], v[84:85], v[80:81]
	v_exp_f32_e32 v126, v126
	v_exp_f32_e32 v127, v127
	v_pk_mul_f32 v[122:123], v[122:123], v[124:125]
	v_pk_mul_f32 v[124:125], v[118:119], v[158:159] op_sel_hi:[1,0]
	v_cvt_pk_bf16_f32 v121, v122, v123
	v_pk_add_f32 v[122:123], v[126:127], 1.0 op_sel_hi:[1,0]
	v_exp_f32_e32 v124, v124
	v_exp_f32_e32 v125, v125
	v_rcp_f32_e32 v122, v122
	v_rcp_f32_e32 v123, v123
	v_pk_mul_f32 v[82:83], v[86:87], v[82:83]
	v_pk_add_f32 v[116:117], v[124:125], 1.0 op_sel_hi:[1,0]
	v_pk_mul_f32 v[72:73], v[76:77], v[72:73]
	v_rcp_f32_e32 v116, v116
	v_rcp_f32_e32 v117, v117
	v_pk_mul_f32 v[112:113], v[112:113], v[122:123]
	v_pk_mul_f32 v[74:75], v[78:79], v[74:75]
	v_cvt_pk_bf16_f32 v122, v112, v113
	v_pk_mul_f32 v[112:113], v[114:115], v[160:161] op_sel_hi:[1,0]
	v_lshl_add_u32 v114, s28, 8, v166
	v_pk_mul_f32 v[112:113], v[112:113], v[116:117]
	v_pk_mul_f32 v[64:65], v[68:69], v[64:65]
	v_cvt_pk_bf16_f32 v123, v112, v113
	ds_read_b128 v[116:119], v156 offset:256
	v_lshl_or_b32 v112, s30, 7, v169
	v_ashrrev_i32_e32 v113, 31, v112
	v_lshlrev_b64 v[112:113], 1, v[112:113]
	v_pk_mul_f32 v[66:67], v[70:71], v[66:67]
	s_waitcnt lgkmcnt(0)
	v_mov_b32_e32 v124, v117
	v_mov_b32_e32 v125, v118
	v_mov_b32_e32 v117, v119
	v_pk_add_f32 v[116:117], v[124:125], v[116:117]
	v_pk_mul_f32 v[56:57], v[60:61], v[56:57]
	v_add_f32_e32 v115, v116, v117
	v_fmamk_f32 v115, v115, 0x3a800000, v171
	v_mul_f32_e32 v116, 0x4b800000, v115
	v_cmp_gt_f32_e32 vcc, s45, v115
	v_pk_mul_f32 v[58:59], v[62:63], v[58:59]
	v_pk_mul_f32 v[48:49], v[52:53], v[48:49]
	v_cndmask_b32_e32 v115, v115, v116, vcc
	v_rsq_f32_e32 v115, v115
	v_mad_i64_i32 v[116:117], s[6:7], v114, s44, v[142:143]
	v_lshl_add_u64 v[116:117], v[116:117], 0, v[112:113]
	v_mul_f32_e32 v118, 0x45800000, v115
	v_cndmask_b32_e32 v115, v115, v118, vcc
	v_mul_f32_e32 v118, 0xbfb8aa3b, v115
	v_pk_mul_f32 v[124:125], v[108:109], v[118:119] op_sel_hi:[1,0]
	v_pk_mul_f32 v[108:109], v[110:111], v[118:119] op_sel_hi:[1,0]
	v_exp_f32_e32 v124, v124
	v_exp_f32_e32 v108, v108
	v_exp_f32_e32 v109, v109
	v_exp_f32_e32 v125, v125
	global_store_dwordx4 v[116:117], v[120:123], off
	v_mul_f32_e32 v116, v115, v115
	v_pk_add_f32 v[108:109], v[108:109], 1.0 op_sel_hi:[1,0]
	v_pk_add_f32 v[120:121], v[124:125], 1.0 op_sel_hi:[1,0]
	v_rcp_f32_e32 v108, v108
	v_rcp_f32_e32 v109, v109
	v_rcp_f32_e32 v120, v120
	v_rcp_f32_e32 v121, v121
	v_pk_mul_f32 v[110:111], v[100:101], v[118:119] op_sel_hi:[1,0]
	v_pk_mul_f32 v[106:107], v[106:107], v[116:117] op_sel_hi:[1,0]
	v_exp_f32_e32 v110, v110
	v_exp_f32_e32 v111, v111
	v_pk_mul_f32 v[106:107], v[106:107], v[108:109]
	v_pk_mul_f32 v[108:109], v[102:103], v[118:119] op_sel_hi:[1,0]
	v_pk_mul_f32 v[104:105], v[104:105], v[116:117] op_sel_hi:[1,0]
	v_exp_f32_e32 v108, v108
	v_exp_f32_e32 v109, v109
	v_pk_mul_f32 v[104:105], v[104:105], v[120:121]
	v_pk_mul_f32 v[96:97], v[96:97], v[116:117] op_sel_hi:[1,0]
	v_cvt_pk_bf16_f32 v104, v104, v105
	v_cvt_pk_bf16_f32 v105, v106, v107
	v_pk_add_f32 v[106:107], v[110:111], 1.0 op_sel_hi:[1,0]
	v_pk_add_f32 v[100:101], v[108:109], 1.0 op_sel_hi:[1,0]
	v_rcp_f32_e32 v106, v106
	v_rcp_f32_e32 v107, v107
	v_rcp_f32_e32 v100, v100
	v_rcp_f32_e32 v101, v101
	v_pk_mul_f32 v[50:51], v[54:55], v[50:51]
	v_pk_mul_f32 v[96:97], v[96:97], v[106:107]
	v_pk_mul_f32 v[40:41], v[44:45], v[40:41]
	v_cvt_pk_bf16_f32 v106, v96, v97
	v_pk_mul_f32 v[96:97], v[98:99], v[116:117] op_sel_hi:[1,0]
	v_pk_mul_f32 v[42:43], v[46:47], v[42:43]
	v_pk_mul_f32 v[96:97], v[96:97], v[100:101]
	v_pk_mul_f32 v[32:33], v[36:37], v[32:33]
	v_cvt_pk_bf16_f32 v107, v96, v97
	ds_read_b128 v[96:99], v156 offset:512
	v_pk_mul_f32 v[34:35], v[38:39], v[34:35]
	v_pk_mul_f32 v[24:25], v[28:29], v[24:25]
	v_pk_mul_f32 v[26:27], v[30:31], v[26:27]
	v_pk_mul_f32 v[16:17], v[20:21], v[16:17]
	s_waitcnt lgkmcnt(0)
	v_mov_b32_e32 v100, v97
	v_mov_b32_e32 v101, v98
	v_mov_b32_e32 v97, v99
	v_pk_add_f32 v[96:97], v[100:101], v[96:97]
	v_pk_mul_f32 v[18:19], v[22:23], v[18:19]
	v_add_f32_e32 v96, v96, v97
	v_fmamk_f32 v96, v96, 0x3a800000, v171
	v_mul_f32_e32 v97, 0x4b800000, v96
	v_cmp_gt_f32_e32 vcc, s45, v96
	v_pk_mul_f32 v[8:9], v[12:13], v[8:9]
	v_pk_mul_f32 v[10:11], v[14:15], v[10:11]
	v_cndmask_b32_e32 v96, v96, v97, vcc
	v_rsq_f32_e32 v98, v96
	v_or_b32_e32 v96, 16, v114
	v_mad_i64_i32 v[96:97], s[6:7], v96, s44, v[142:143]
	v_mul_f32_e32 v99, 0x45800000, v98
	v_cndmask_b32_e32 v99, v98, v99, vcc
	v_mul_f32_e32 v98, 0xbfb8aa3b, v99
	v_pk_mul_f32 v[100:101], v[92:93], v[98:99] op_sel_hi:[1,0]
	v_pk_mul_f32 v[92:93], v[94:95], v[98:99] op_sel_hi:[1,0]
	v_exp_f32_e32 v100, v100
	v_exp_f32_e32 v92, v92
	v_exp_f32_e32 v93, v93
	v_exp_f32_e32 v101, v101
	v_lshl_add_u64 v[96:97], v[96:97], 0, v[112:113]
	global_store_dwordx4 v[96:97], v[104:107], off
	v_pk_add_f32 v[92:93], v[92:93], 1.0 op_sel_hi:[1,0]
	v_pk_add_f32 v[100:101], v[100:101], 1.0 op_sel_hi:[1,0]
	v_rcp_f32_e32 v92, v92
	v_rcp_f32_e32 v93, v93
	v_mul_f32_e32 v96, v99, v99
	v_rcp_f32_e32 v100, v100
	v_rcp_f32_e32 v101, v101
	v_pk_mul_f32 v[94:95], v[84:85], v[98:99] op_sel_hi:[1,0]
	v_pk_mul_f32 v[90:91], v[90:91], v[96:97] op_sel_hi:[1,0]
	v_exp_f32_e32 v94, v94
	v_exp_f32_e32 v95, v95
	v_pk_mul_f32 v[90:91], v[90:91], v[92:93]
	v_pk_mul_f32 v[92:93], v[86:87], v[98:99] op_sel_hi:[1,0]
	v_pk_mul_f32 v[88:89], v[88:89], v[96:97] op_sel_hi:[1,0]
	v_exp_f32_e32 v92, v92
	v_exp_f32_e32 v93, v93
	v_pk_mul_f32 v[88:89], v[88:89], v[100:101]
	v_pk_mul_f32 v[80:81], v[80:81], v[96:97] op_sel_hi:[1,0]
	v_cvt_pk_bf16_f32 v88, v88, v89
	v_cvt_pk_bf16_f32 v89, v90, v91
	v_pk_add_f32 v[90:91], v[94:95], 1.0 op_sel_hi:[1,0]
	v_pk_add_f32 v[84:85], v[92:93], 1.0 op_sel_hi:[1,0]
	v_rcp_f32_e32 v90, v90
	v_rcp_f32_e32 v91, v91
	v_rcp_f32_e32 v84, v84
	v_rcp_f32_e32 v85, v85
	v_pk_mul_f32 v[0:1], v[4:5], v[0:1]
	v_pk_mul_f32 v[80:81], v[80:81], v[90:91]
	v_pk_mul_f32 v[2:3], v[6:7], v[2:3]
	v_cvt_pk_bf16_f32 v90, v80, v81
	v_pk_mul_f32 v[80:81], v[82:83], v[96:97] op_sel_hi:[1,0]
	s_nop 0
	v_pk_mul_f32 v[80:81], v[80:81], v[84:85]
	s_nop 0
	v_cvt_pk_bf16_f32 v91, v80, v81
	ds_read_b128 v[80:83], v156 offset:768
	s_waitcnt lgkmcnt(0)
	v_mov_b32_e32 v84, v81
	v_mov_b32_e32 v85, v82
	v_mov_b32_e32 v81, v83
	v_pk_add_f32 v[80:81], v[84:85], v[80:81]
	s_nop 0
	v_add_f32_e32 v80, v80, v81
	v_fmamk_f32 v80, v80, 0x3a800000, v171
	v_mul_f32_e32 v81, 0x4b800000, v80
	v_cmp_gt_f32_e32 vcc, s45, v80
	s_nop 1
	v_cndmask_b32_e32 v80, v80, v81, vcc
	v_rsq_f32_e32 v82, v80
	v_or_b32_e32 v80, 32, v114
	v_mad_i64_i32 v[80:81], s[6:7], v80, s44, v[142:143]
	v_mul_f32_e32 v83, 0x45800000, v82
	v_cndmask_b32_e32 v83, v82, v83, vcc
	v_mul_f32_e32 v82, 0xbfb8aa3b, v83
	v_pk_mul_f32 v[84:85], v[76:77], v[82:83] op_sel_hi:[1,0]
	v_pk_mul_f32 v[76:77], v[78:79], v[82:83] op_sel_hi:[1,0]
	v_exp_f32_e32 v84, v84
	v_exp_f32_e32 v76, v76
	v_exp_f32_e32 v77, v77
	v_exp_f32_e32 v85, v85
	v_lshl_add_u64 v[80:81], v[80:81], 0, v[112:113]
	global_store_dwordx4 v[80:81], v[88:91], off
	v_pk_add_f32 v[76:77], v[76:77], 1.0 op_sel_hi:[1,0]
	v_pk_add_f32 v[84:85], v[84:85], 1.0 op_sel_hi:[1,0]
	v_rcp_f32_e32 v76, v76
	v_rcp_f32_e32 v77, v77
	v_mul_f32_e32 v80, v83, v83
	v_rcp_f32_e32 v84, v84
	v_rcp_f32_e32 v85, v85
	v_pk_mul_f32 v[78:79], v[68:69], v[82:83] op_sel_hi:[1,0]
	v_pk_mul_f32 v[74:75], v[74:75], v[80:81] op_sel_hi:[1,0]
	v_exp_f32_e32 v78, v78
	v_exp_f32_e32 v79, v79
	v_pk_mul_f32 v[74:75], v[74:75], v[76:77]
	v_pk_mul_f32 v[76:77], v[70:71], v[82:83] op_sel_hi:[1,0]
	v_pk_mul_f32 v[72:73], v[72:73], v[80:81] op_sel_hi:[1,0]
	v_exp_f32_e32 v76, v76
	v_exp_f32_e32 v77, v77
	v_pk_mul_f32 v[72:73], v[72:73], v[84:85]
	v_pk_mul_f32 v[64:65], v[64:65], v[80:81] op_sel_hi:[1,0]
	v_cvt_pk_bf16_f32 v72, v72, v73
	v_cvt_pk_bf16_f32 v73, v74, v75
	v_pk_add_f32 v[74:75], v[78:79], 1.0 op_sel_hi:[1,0]
	v_pk_add_f32 v[68:69], v[76:77], 1.0 op_sel_hi:[1,0]
	v_rcp_f32_e32 v74, v74
	v_rcp_f32_e32 v75, v75
	v_rcp_f32_e32 v68, v68
	v_rcp_f32_e32 v69, v69
	v_pk_mul_f32 v[64:65], v[64:65], v[74:75]
	s_nop 0
	v_cvt_pk_bf16_f32 v74, v64, v65
	v_pk_mul_f32 v[64:65], v[66:67], v[80:81] op_sel_hi:[1,0]
	s_nop 0
	v_pk_mul_f32 v[64:65], v[64:65], v[68:69]
	s_nop 0
	v_cvt_pk_bf16_f32 v75, v64, v65
	ds_read_b128 v[64:67], v156 offset:2048
	s_waitcnt lgkmcnt(0)
	v_mov_b32_e32 v68, v65
	v_mov_b32_e32 v69, v66
	v_mov_b32_e32 v65, v67
	v_pk_add_f32 v[64:65], v[68:69], v[64:65]
	s_nop 0
	v_add_f32_e32 v64, v64, v65
	v_fmamk_f32 v64, v64, 0x3a800000, v171
	v_mul_f32_e32 v65, 0x4b800000, v64
	v_cmp_gt_f32_e32 vcc, s45, v64
	s_nop 1
	v_cndmask_b32_e32 v64, v64, v65, vcc
	v_rsq_f32_e32 v66, v64
	v_or_b32_e32 v64, 48, v114
	v_mad_i64_i32 v[64:65], s[6:7], v64, s44, v[142:143]
	v_mul_f32_e32 v67, 0x45800000, v66
	v_cndmask_b32_e32 v67, v66, v67, vcc
	v_mul_f32_e32 v66, 0xbfb8aa3b, v67
	v_pk_mul_f32 v[68:69], v[60:61], v[66:67] op_sel_hi:[1,0]
	v_pk_mul_f32 v[60:61], v[62:63], v[66:67] op_sel_hi:[1,0]
	v_exp_f32_e32 v68, v68
	v_exp_f32_e32 v60, v60
	v_exp_f32_e32 v61, v61
	v_exp_f32_e32 v69, v69
	v_lshl_add_u64 v[64:65], v[64:65], 0, v[112:113]
	global_store_dwordx4 v[64:65], v[72:75], off
	v_pk_add_f32 v[60:61], v[60:61], 1.0 op_sel_hi:[1,0]
	v_pk_add_f32 v[68:69], v[68:69], 1.0 op_sel_hi:[1,0]
	v_rcp_f32_e32 v60, v60
	v_rcp_f32_e32 v61, v61
	v_mul_f32_e32 v64, v67, v67
	v_rcp_f32_e32 v68, v68
	v_rcp_f32_e32 v69, v69
	v_pk_mul_f32 v[62:63], v[52:53], v[66:67] op_sel_hi:[1,0]
	v_pk_mul_f32 v[58:59], v[58:59], v[64:65] op_sel_hi:[1,0]
	v_exp_f32_e32 v62, v62
	v_exp_f32_e32 v63, v63
	v_pk_mul_f32 v[58:59], v[58:59], v[60:61]
	v_pk_mul_f32 v[60:61], v[54:55], v[66:67] op_sel_hi:[1,0]
	v_pk_mul_f32 v[56:57], v[56:57], v[64:65] op_sel_hi:[1,0]
	v_exp_f32_e32 v60, v60
	v_exp_f32_e32 v61, v61
	v_pk_mul_f32 v[56:57], v[56:57], v[68:69]
	v_pk_mul_f32 v[48:49], v[48:49], v[64:65] op_sel_hi:[1,0]
	v_cvt_pk_bf16_f32 v56, v56, v57
	v_cvt_pk_bf16_f32 v57, v58, v59
	v_pk_add_f32 v[58:59], v[62:63], 1.0 op_sel_hi:[1,0]
	v_pk_add_f32 v[52:53], v[60:61], 1.0 op_sel_hi:[1,0]
	v_rcp_f32_e32 v58, v58
	v_rcp_f32_e32 v59, v59
	v_rcp_f32_e32 v52, v52
	v_rcp_f32_e32 v53, v53
	v_pk_mul_f32 v[48:49], v[48:49], v[58:59]
	s_nop 0
	v_cvt_pk_bf16_f32 v58, v48, v49
	v_pk_mul_f32 v[48:49], v[50:51], v[64:65] op_sel_hi:[1,0]
	s_nop 0
	v_pk_mul_f32 v[48:49], v[48:49], v[52:53]
	s_nop 0
	v_cvt_pk_bf16_f32 v59, v48, v49
	ds_read_b128 v[48:51], v156 offset:2304
	s_waitcnt lgkmcnt(0)
	v_mov_b32_e32 v52, v49
	v_mov_b32_e32 v53, v50
	v_mov_b32_e32 v49, v51
	v_pk_add_f32 v[48:49], v[52:53], v[48:49]
	s_nop 0
	v_add_f32_e32 v48, v48, v49
	v_fmamk_f32 v48, v48, 0x3a800000, v171
	v_mul_f32_e32 v49, 0x4b800000, v48
	v_cmp_gt_f32_e32 vcc, s45, v48
	s_nop 1
	v_cndmask_b32_e32 v48, v48, v49, vcc
	v_rsq_f32_e32 v50, v48
	v_add_u32_e32 v48, 0x80, v114
	v_mad_i64_i32 v[48:49], s[6:7], v48, s44, v[142:143]
	v_mul_f32_e32 v51, 0x45800000, v50
	v_cndmask_b32_e32 v51, v50, v51, vcc
	v_mul_f32_e32 v50, 0xbfb8aa3b, v51
	v_pk_mul_f32 v[52:53], v[44:45], v[50:51] op_sel_hi:[1,0]
	v_pk_mul_f32 v[44:45], v[46:47], v[50:51] op_sel_hi:[1,0]
	v_exp_f32_e32 v52, v52
	v_exp_f32_e32 v44, v44
	v_exp_f32_e32 v45, v45
	v_exp_f32_e32 v53, v53
	v_lshl_add_u64 v[48:49], v[48:49], 0, v[112:113]
	global_store_dwordx4 v[48:49], v[56:59], off
	v_pk_add_f32 v[44:45], v[44:45], 1.0 op_sel_hi:[1,0]
	v_pk_add_f32 v[52:53], v[52:53], 1.0 op_sel_hi:[1,0]
	v_rcp_f32_e32 v44, v44
	v_rcp_f32_e32 v45, v45
	v_mul_f32_e32 v48, v51, v51
	v_rcp_f32_e32 v52, v52
	v_rcp_f32_e32 v53, v53
	v_pk_mul_f32 v[46:47], v[36:37], v[50:51] op_sel_hi:[1,0]
	v_pk_mul_f32 v[42:43], v[42:43], v[48:49] op_sel_hi:[1,0]
	v_exp_f32_e32 v46, v46
	v_exp_f32_e32 v47, v47
	v_pk_mul_f32 v[42:43], v[42:43], v[44:45]
	v_pk_mul_f32 v[44:45], v[38:39], v[50:51] op_sel_hi:[1,0]
	v_pk_mul_f32 v[40:41], v[40:41], v[48:49] op_sel_hi:[1,0]
	v_exp_f32_e32 v44, v44
	v_exp_f32_e32 v45, v45
	v_pk_mul_f32 v[40:41], v[40:41], v[52:53]
	v_pk_mul_f32 v[32:33], v[32:33], v[48:49] op_sel_hi:[1,0]
	v_cvt_pk_bf16_f32 v40, v40, v41
	v_cvt_pk_bf16_f32 v41, v42, v43
	v_pk_add_f32 v[42:43], v[46:47], 1.0 op_sel_hi:[1,0]
	v_pk_add_f32 v[36:37], v[44:45], 1.0 op_sel_hi:[1,0]
	v_rcp_f32_e32 v42, v42
	v_rcp_f32_e32 v43, v43
	v_rcp_f32_e32 v36, v36
	v_rcp_f32_e32 v37, v37
	v_pk_mul_f32 v[32:33], v[32:33], v[42:43]
	s_nop 0
	v_cvt_pk_bf16_f32 v42, v32, v33
	v_pk_mul_f32 v[32:33], v[34:35], v[48:49] op_sel_hi:[1,0]
	s_nop 0
	v_pk_mul_f32 v[32:33], v[32:33], v[36:37]
	s_nop 0
	v_cvt_pk_bf16_f32 v43, v32, v33
	ds_read_b128 v[32:35], v156 offset:2560
	s_waitcnt lgkmcnt(0)
	v_mov_b32_e32 v36, v33
	v_mov_b32_e32 v37, v34
	v_mov_b32_e32 v33, v35
	v_pk_add_f32 v[32:33], v[36:37], v[32:33]
	s_nop 0
	v_add_f32_e32 v32, v32, v33
	v_fmamk_f32 v32, v32, 0x3a800000, v171
	v_mul_f32_e32 v33, 0x4b800000, v32
	v_cmp_gt_f32_e32 vcc, s45, v32
	s_nop 1
	v_cndmask_b32_e32 v32, v32, v33, vcc
	v_rsq_f32_e32 v34, v32
	v_add_u32_e32 v32, 0x90, v114
	v_mad_i64_i32 v[32:33], s[6:7], v32, s44, v[142:143]
	v_mul_f32_e32 v35, 0x45800000, v34
	v_cndmask_b32_e32 v35, v34, v35, vcc
	v_mul_f32_e32 v34, 0xbfb8aa3b, v35
	v_pk_mul_f32 v[36:37], v[28:29], v[34:35] op_sel_hi:[1,0]
	v_pk_mul_f32 v[28:29], v[30:31], v[34:35] op_sel_hi:[1,0]
	v_exp_f32_e32 v36, v36
	v_exp_f32_e32 v28, v28
	v_exp_f32_e32 v29, v29
	v_exp_f32_e32 v37, v37
	v_lshl_add_u64 v[32:33], v[32:33], 0, v[112:113]
	global_store_dwordx4 v[32:33], v[40:43], off
	v_pk_add_f32 v[28:29], v[28:29], 1.0 op_sel_hi:[1,0]
	v_pk_add_f32 v[36:37], v[36:37], 1.0 op_sel_hi:[1,0]
	v_rcp_f32_e32 v28, v28
	v_rcp_f32_e32 v29, v29
	v_mul_f32_e32 v32, v35, v35
	v_rcp_f32_e32 v36, v36
	v_rcp_f32_e32 v37, v37
	v_pk_mul_f32 v[30:31], v[20:21], v[34:35] op_sel_hi:[1,0]
	v_pk_mul_f32 v[26:27], v[26:27], v[32:33] op_sel_hi:[1,0]
	v_exp_f32_e32 v30, v30
	v_exp_f32_e32 v31, v31
	v_pk_mul_f32 v[26:27], v[26:27], v[28:29]
	v_pk_mul_f32 v[28:29], v[22:23], v[34:35] op_sel_hi:[1,0]
	v_pk_mul_f32 v[24:25], v[24:25], v[32:33] op_sel_hi:[1,0]
	v_exp_f32_e32 v28, v28
	v_exp_f32_e32 v29, v29
	v_pk_mul_f32 v[24:25], v[24:25], v[36:37]
	v_pk_mul_f32 v[16:17], v[16:17], v[32:33] op_sel_hi:[1,0]
	v_cvt_pk_bf16_f32 v24, v24, v25
	v_cvt_pk_bf16_f32 v25, v26, v27
	v_pk_add_f32 v[26:27], v[30:31], 1.0 op_sel_hi:[1,0]
	v_pk_add_f32 v[20:21], v[28:29], 1.0 op_sel_hi:[1,0]
	v_rcp_f32_e32 v26, v26
	v_rcp_f32_e32 v27, v27
	v_rcp_f32_e32 v20, v20
	v_rcp_f32_e32 v21, v21
	v_pk_mul_f32 v[16:17], v[16:17], v[26:27]
	s_nop 0
	v_cvt_pk_bf16_f32 v26, v16, v17
	v_pk_mul_f32 v[16:17], v[18:19], v[32:33] op_sel_hi:[1,0]
	s_nop 0
	v_pk_mul_f32 v[16:17], v[16:17], v[20:21]
	v_add_u32_e32 v20, 0xa0, v114
	v_cvt_pk_bf16_f32 v27, v16, v17
	ds_read_b128 v[16:19], v156 offset:2816
	v_mad_i64_i32 v[20:21], s[6:7], v20, s44, v[142:143]
	s_waitcnt lgkmcnt(0)
	v_mov_b32_e32 v22, v17
	v_mov_b32_e32 v23, v18
	v_mov_b32_e32 v17, v19
	v_pk_add_f32 v[16:17], v[22:23], v[16:17]
	s_nop 0
	v_add_f32_e32 v16, v16, v17
	v_fmamk_f32 v16, v16, 0x3a800000, v171
	v_mul_f32_e32 v17, 0x4b800000, v16
	v_cmp_gt_f32_e32 vcc, s45, v16
	s_nop 1
	v_cndmask_b32_e32 v16, v16, v17, vcc
	v_rsq_f32_e32 v18, v16
	v_lshl_add_u64 v[16:17], v[20:21], 0, v[112:113]
	global_store_dwordx4 v[16:17], v[24:27], off
	v_add_u32_e32 v17, 0xb0, v114
	v_mul_f32_e32 v16, 0x45800000, v18
	v_cndmask_b32_e32 v22, v18, v16, vcc
	v_mul_f32_e32 v16, 0xbfb8aa3b, v22
	v_pk_mul_f32 v[18:19], v[12:13], v[16:17] op_sel_hi:[1,0]
	v_pk_mul_f32 v[12:13], v[14:15], v[16:17] op_sel_hi:[1,0]
	v_exp_f32_e32 v18, v18
	v_exp_f32_e32 v12, v12
	v_exp_f32_e32 v13, v13
	v_exp_f32_e32 v19, v19
	v_mul_f32_e32 v22, v22, v22
	v_pk_mul_f32 v[14:15], v[4:5], v[16:17] op_sel_hi:[1,0]
	v_pk_add_f32 v[12:13], v[12:13], 1.0 op_sel_hi:[1,0]
	v_pk_add_f32 v[18:19], v[18:19], 1.0 op_sel_hi:[1,0]
	v_rcp_f32_e32 v12, v12
	v_rcp_f32_e32 v13, v13
	v_rcp_f32_e32 v18, v18
	v_rcp_f32_e32 v19, v19
	v_exp_f32_e32 v14, v14
	v_exp_f32_e32 v15, v15
	v_pk_mul_f32 v[10:11], v[10:11], v[22:23] op_sel_hi:[1,0]
	v_pk_mul_f32 v[8:9], v[8:9], v[22:23] op_sel_hi:[1,0]
	v_pk_mul_f32 v[10:11], v[10:11], v[12:13]
	v_pk_mul_f32 v[12:13], v[6:7], v[16:17] op_sel_hi:[1,0]
	v_pk_mul_f32 v[8:9], v[8:9], v[18:19]
	v_exp_f32_e32 v12, v12
	v_exp_f32_e32 v13, v13
	v_cvt_pk_bf16_f32 v8, v8, v9
	v_cvt_pk_bf16_f32 v9, v10, v11
	v_pk_add_f32 v[10:11], v[14:15], 1.0 op_sel_hi:[1,0]
	v_pk_add_f32 v[4:5], v[12:13], 1.0 op_sel_hi:[1,0]
	v_rcp_f32_e32 v10, v10
	v_rcp_f32_e32 v11, v11
	v_rcp_f32_e32 v4, v4
	v_rcp_f32_e32 v5, v5
	v_pk_mul_f32 v[0:1], v[0:1], v[22:23] op_sel_hi:[1,0]
	v_mad_i64_i32 v[20:21], s[6:7], v17, s44, v[142:143]
	v_pk_mul_f32 v[0:1], v[0:1], v[10:11]
	s_andn2_b64 vcc, exec, s[4:5]
	v_cvt_pk_bf16_f32 v10, v0, v1
	v_pk_mul_f32 v[0:1], v[2:3], v[22:23] op_sel_hi:[1,0]
	s_mov_b64 s[4:5], -1
	v_pk_mul_f32 v[0:1], v[0:1], v[4:5]
	s_nop 0
	v_cvt_pk_bf16_f32 v11, v0, v1
	v_lshl_add_u64 v[0:1], v[20:21], 0, v[112:113]
	global_store_dwordx4 v[0:1], v[8:11], off
	s_mov_b32 s100, 1
	s_cbranch_vccnz .LBB0_66
	s_andn2_b64 vcc, exec, s[10:11]
	s_cbranch_vccnz .LBB0_65
	s_barrier
	s_branch .LBB0_65

.LBB0_252:
	s_mov_b64 s[14:15], 0x80
	s_add_i32 m0, s31, 0x18000
	v_lshl_add_u64 v[6:7], v[6:7], 0, s[14:15]
	s_waitcnt vmcnt(2)
	s_barrier
	global_load_lds_dwordx4 v[6:7], off
	v_lshl_add_u64 v[6:7], v[8:9], 0, s[14:15]
	s_add_i32 m0, s31, 0x1a000
	s_add_i32 s37, s31, 0x8000
	global_load_lds_dwordx4 v[6:7], off
	v_lshl_add_u64 v[6:7], v[10:11], 0, s[14:15]
	s_mov_b32 m0, s37
	s_add_i32 s38, s31, 0xa000
	global_load_lds_dwordx4 v[6:7], off
	v_lshl_add_u64 v[6:7], v[12:13], 0, s[14:15]
	s_mov_b32 m0, s38
	s_mov_b64 s[16:17], 0x40080
	global_load_lds_dwordx4 v[6:7], off
	v_lshl_add_u64 v[6:7], v[2:3], 0, s[16:17]
	s_add_i32 m0, s31, 0x1c000
	v_lshl_add_u64 v[8:9], v[6:7], 0, v[134:135]
	global_load_lds_dwordx4 v[8:9], off
	v_lshl_add_u64 v[6:7], v[6:7], 0, v[140:141]
	s_add_i32 m0, s31, 0x1e000
	s_and_b32 s18, s2, 7
	s_lshl_b32 s18, s18, 23
	s_add_u32 s18, s18, 0xd000000
	s_mov_b32 s19, 0
	global_load_lds_dwordx4 v[6:7], off
	v_lshl_add_u64 v[142:143], v[4:5], 0, s[18:19]
	v_lshrrev_b32_e32 v5, 1, v14
	v_and_b32_e32 v5, 24, v5
	v_and_b32_e32 v4, 15, v14
	v_lshlrev_b32_e32 v6, 1, v5
	v_lshl_or_b32 v166, s9, 6, v4
	v_lshl_or_b32 v4, v4, 6, v6
	v_lshlrev_b32_e32 v6, 2, v14
	s_sext_i32_i8 s54, s7
	s_lshl_b32 s7, s9, 13
	v_and_b32_e32 v6, 32, v6
	v_bitop3_b32 v7, v4, s7, v6 bitop3:0xde
	s_lshl_b32 s7, s8, 5
	s_and_b32 s7, s7, 0x60
	s_lshl_b32 s8, s7, 7
	v_bitop3_b32 v167, v4, s8, v6 bitop3:0xde
	v_lshlrev_b32_e32 v4, 14, v18
	v_and_b32_e32 v4, 0xffff8000, v4
	v_or_b32_e32 v169, s7, v5
	v_lshl_add_u32 v4, v19, 11, v4
	v_and_b32_e32 v5, 1, v18
	v_lshl_or_b32 v4, v5, 6, v4
	v_lshl_add_u32 v144, v20, 1, v4
	v_lshlrev_b32_e32 v4, 14, v15
	v_and_b32_e32 v4, 0xffff8000, v4
	s_waitcnt vmcnt(6)
	s_cmpk_lt_u32 s6, 0x100
	v_lshl_add_u32 v4, v16, 11, v4
	v_and_b32_e32 v5, 1, v15
	s_cselect_b64 s[18:19], -1, 0
	s_add_i32 s6, 0, 0x21c00
	v_lshl_or_b32 v4, v5, 6, v4
	s_mov_b32 s22, 0xfffc0080
	s_mov_b32 s55, 0
	v_lshl_add_u32 v168, v166, 4, s6
	v_mov_b32_e32 v145, v135
	v_lshl_add_u32 v146, v17, 1, v4
	v_mov_b32_e32 v147, v135
	v_mov_b64_e32 v[148:149], 0x380
	v_mov_b64_e32 v[150:151], 0x37f
	s_movk_i32 s39, 0x71
	s_mov_b64 s[20:21], 0x100
	s_mov_b32 s23, -1
	s_add_i32 s42, 0, 0x10000
	s_add_i32 s43, 0, 0x14000
	v_add_u32_e32 v170, 0, v7
	s_add_i32 s44, s31, 0xc000
	s_add_i32 s45, s31, 0xe000
	s_movk_i32 s50, 0xe00
	v_mov_b32_e32 v171, 0x358637bd
	s_mov_b32 s51, 0x800000
	s_mov_b32 s52, 0
	s_barrier
	s_mov_b32 s100, 0
	s_branch .LBB0_255

.LBB0_258:
	v_add_u32_e32 v186, s42, v167
	v_add_u32_e32 v202, s43, v167
	ds_read_b128 v[172:175], v186
	ds_read_b128 v[178:181], v186 offset:1024
	ds_read_b128 v[182:185], v186 offset:2048
	ds_read_b128 v[186:189], v186 offset:3072
	ds_read_b128 v[190:193], v202
	ds_read_b128 v[194:197], v202 offset:1024
	ds_read_b128 v[198:201], v202 offset:2048
	ds_read_b128 v[202:205], v202 offset:3072
	v_lshl_add_u64 v[206:207], v[164:165], 0, s[22:23]
	v_cndmask_b32_e64 v239, v207, v157, s[8:9]
	v_cndmask_b32_e64 v238, v206, v156, s[8:9]
	v_cndmask_b32_e64 v241, v163, v159, s[8:9]
	v_cndmask_b32_e64 v240, v162, v158, s[8:9]
	s_mov_b32 m0, s44
	v_lshl_add_u64 v[242:243], v[164:165], 0, v[146:147]
	ds_read_b128 v[206:209], v170
	ds_read_b128 v[210:213], v170 offset:1024
	ds_read_b128 v[214:217], v170 offset:2048
	ds_read_b128 v[218:221], v170 offset:3072
	ds_read_b128 v[222:225], v170 offset:4096
	ds_read_b128 v[226:229], v170 offset:5120
	ds_read_b128 v[230:233], v170 offset:6144
	ds_read_b128 v[234:237], v170 offset:7168
	global_load_lds_dwordx4 v[242:243], off
	v_lshl_add_u64 v[242:243], v[164:165], 0, v[144:145]
	s_mov_b32 m0, s45
	s_nop 0
	global_load_lds_dwordx4 v[242:243], off
	s_cmp_eq_u32 s100, 0
	s_cbranch_scc1 .Lgw8_8345_0
	s_waitcnt vmcnt(24)
	s_branch .Lgwd_8345_0

.Lgwd_8345_0:
	s_waitcnt lgkmcnt(0)
	s_barrier
	s_setprio 1
	s_waitcnt lgkmcnt(0)
	v_mfma_f32_16x16x32_bf16 v[124:127], v[172:175], v[206:209], v[124:127]
	v_mfma_f32_16x16x32_bf16 v[120:123], v[182:185], v[206:209], v[120:123]
	v_mfma_f32_16x16x32_bf16 v[108:111], v[172:175], v[214:217], v[108:111]
	v_mfma_f32_16x16x32_bf16 v[104:107], v[182:185], v[214:217], v[104:107]
	v_mfma_f32_16x16x32_bf16 v[92:95], v[172:175], v[222:225], v[92:95]
	v_mfma_f32_16x16x32_bf16 v[88:91], v[182:185], v[222:225], v[88:91]
	v_mfma_f32_16x16x32_bf16 v[76:79], v[172:175], v[230:233], v[76:79]
	v_mfma_f32_16x16x32_bf16 v[72:75], v[182:185], v[230:233], v[72:75]
	v_mfma_f32_16x16x32_bf16 v[124:127], v[178:181], v[210:213], v[124:127]
	v_mfma_f32_16x16x32_bf16 v[120:123], v[186:189], v[210:213], v[120:123]
	v_mfma_f32_16x16x32_bf16 v[108:111], v[178:181], v[218:221], v[108:111]
	v_mfma_f32_16x16x32_bf16 v[104:107], v[186:189], v[218:221], v[104:107]
	v_mfma_f32_16x16x32_bf16 v[92:95], v[178:181], v[226:229], v[92:95]
	v_mfma_f32_16x16x32_bf16 v[88:91], v[186:189], v[226:229], v[88:91]
	v_mfma_f32_16x16x32_bf16 v[76:79], v[178:181], v[234:237], v[76:79]
	v_mfma_f32_16x16x32_bf16 v[72:75], v[186:189], v[234:237], v[72:75]
	s_setprio 0
	s_setprio 1
	v_mfma_f32_16x16x32_bf16 v[116:119], v[190:193], v[206:209], v[116:119]
	v_mfma_f32_16x16x32_bf16 v[112:115], v[198:201], v[206:209], v[112:115]
	v_mfma_f32_16x16x32_bf16 v[100:103], v[190:193], v[214:217], v[100:103]
	v_mfma_f32_16x16x32_bf16 v[96:99], v[198:201], v[214:217], v[96:99]
	v_mfma_f32_16x16x32_bf16 v[84:87], v[190:193], v[222:225], v[84:87]
	v_mfma_f32_16x16x32_bf16 v[80:83], v[198:201], v[222:225], v[80:83]
	v_mfma_f32_16x16x32_bf16 v[68:71], v[190:193], v[230:233], v[68:71]
	v_mfma_f32_16x16x32_bf16 v[64:67], v[198:201], v[230:233], v[64:67]
	v_mfma_f32_16x16x32_bf16 v[116:119], v[194:197], v[210:213], v[116:119]
	v_mfma_f32_16x16x32_bf16 v[112:115], v[202:205], v[210:213], v[112:115]
	v_mfma_f32_16x16x32_bf16 v[100:103], v[194:197], v[218:221], v[100:103]
	v_mfma_f32_16x16x32_bf16 v[96:99], v[202:205], v[218:221], v[96:99]
	v_mfma_f32_16x16x32_bf16 v[84:87], v[194:197], v[226:229], v[84:87]
	v_mfma_f32_16x16x32_bf16 v[80:83], v[202:205], v[226:229], v[80:83]
	v_mfma_f32_16x16x32_bf16 v[68:71], v[194:197], v[234:237], v[68:71]
	v_mfma_f32_16x16x32_bf16 v[64:67], v[202:205], v[234:237], v[64:67]
	s_setprio 0
	s_barrier
	s_add_i32 s8, s42, s3
	v_lshl_add_u64 v[242:243], v[240:241], 0, v[134:135]
	s_mov_b32 m0, s8
	ds_read_b128 v[206:209], v170 offset:16384
	ds_read_b128 v[210:213], v170 offset:17408
	ds_read_b128 v[214:217], v170 offset:18432
	ds_read_b128 v[218:221], v170 offset:19456
	ds_read_b128 v[222:225], v170 offset:20480
	ds_read_b128 v[226:229], v170 offset:21504
	ds_read_b128 v[230:233], v170 offset:22528
	ds_read_b128 v[234:237], v170 offset:23552
	global_load_lds_dwordx4 v[242:243], off
	v_lshl_add_u64 v[244:245], v[240:241], 0, v[140:141]
	s_add_i32 m0, s8, 0x2000
	v_lshl_add_u64 v[246:247], v[240:241], 0, s[10:11]
	s_add_i32 s8, s43, s3
	global_load_lds_dwordx4 v[244:245], off
	v_lshl_add_u64 v[248:249], v[246:247], 0, v[134:135]
	s_mov_b32 m0, s8
	v_lshl_add_u64 v[246:247], v[246:247], 0, v[140:141]
	global_load_lds_dwordx4 v[248:249], off
	s_add_i32 m0, s8, 0x2000
	v_lshl_add_u64 v[248:249], v[238:239], 0, v[138:139]
	global_load_lds_dwordx4 v[246:247], off
	v_lshl_add_u64 v[246:247], v[238:239], 0, v[136:137]
	s_mov_b32 m0, s31
	s_nop 0
	global_load_lds_dwordx4 v[246:247], off
	s_mov_b32 m0, s34
	s_nop 0
	global_load_lds_dwordx4 v[248:249], off
	s_cmp_eq_u32 s100, 0
	s_cbranch_scc1 .Lgw8_8345_1
	s_waitcnt vmcnt(24)
	s_mov_b32 s100, 0
	s_branch .Lgwd_8345_1

.Lgwd_8345_1:
	s_waitcnt lgkmcnt(0)
	s_barrier
	s_setprio 1
	s_waitcnt lgkmcnt(0)
	v_mfma_f32_16x16x32_bf16 v[60:63], v[172:175], v[206:209], v[60:63]
	v_mfma_f32_16x16x32_bf16 v[56:59], v[182:185], v[206:209], v[56:59]
	v_mfma_f32_16x16x32_bf16 v[44:47], v[172:175], v[214:217], v[44:47]
	v_mfma_f32_16x16x32_bf16 v[40:43], v[182:185], v[214:217], v[40:43]
	v_mfma_f32_16x16x32_bf16 v[28:31], v[172:175], v[222:225], v[28:31]
	v_mfma_f32_16x16x32_bf16 v[24:27], v[182:185], v[222:225], v[24:27]
	v_mfma_f32_16x16x32_bf16 v[12:15], v[172:175], v[230:233], v[12:15]
	v_mfma_f32_16x16x32_bf16 v[8:11], v[182:185], v[230:233], v[8:11]
	v_mfma_f32_16x16x32_bf16 v[60:63], v[178:181], v[210:213], v[60:63]
	v_mfma_f32_16x16x32_bf16 v[56:59], v[186:189], v[210:213], v[56:59]
	v_mfma_f32_16x16x32_bf16 v[44:47], v[178:181], v[218:221], v[44:47]
	v_mfma_f32_16x16x32_bf16 v[40:43], v[186:189], v[218:221], v[40:43]
	v_mfma_f32_16x16x32_bf16 v[28:31], v[178:181], v[226:229], v[28:31]
	v_mfma_f32_16x16x32_bf16 v[24:27], v[186:189], v[226:229], v[24:27]
	v_mfma_f32_16x16x32_bf16 v[12:15], v[178:181], v[234:237], v[12:15]
	v_mfma_f32_16x16x32_bf16 v[8:11], v[186:189], v[234:237], v[8:11]
	s_setprio 0
	s_setprio 1
	v_mfma_f32_16x16x32_bf16 v[52:55], v[190:193], v[206:209], v[52:55]
	v_mfma_f32_16x16x32_bf16 v[48:51], v[198:201], v[206:209], v[48:51]
	v_mfma_f32_16x16x32_bf16 v[36:39], v[190:193], v[214:217], v[36:39]
	v_mfma_f32_16x16x32_bf16 v[32:35], v[198:201], v[214:217], v[32:35]
	v_mfma_f32_16x16x32_bf16 v[20:23], v[190:193], v[222:225], v[20:23]
	v_mfma_f32_16x16x32_bf16 v[16:19], v[198:201], v[222:225], v[16:19]
	v_mfma_f32_16x16x32_bf16 v[4:7], v[190:193], v[230:233], v[4:7]
	v_mfma_f32_16x16x32_bf16 v[0:3], v[198:201], v[230:233], v[0:3]
	v_mfma_f32_16x16x32_bf16 v[52:55], v[194:197], v[210:213], v[52:55]
	v_mfma_f32_16x16x32_bf16 v[48:51], v[202:205], v[210:213], v[48:51]
	v_mfma_f32_16x16x32_bf16 v[36:39], v[194:197], v[218:221], v[36:39]
	v_mfma_f32_16x16x32_bf16 v[32:35], v[202:205], v[218:221], v[32:35]
	v_mfma_f32_16x16x32_bf16 v[20:23], v[194:197], v[226:229], v[20:23]
	v_mfma_f32_16x16x32_bf16 v[16:19], v[202:205], v[226:229], v[16:19]
	v_mfma_f32_16x16x32_bf16 v[4:7], v[194:197], v[234:237], v[4:7]
	v_mfma_f32_16x16x32_bf16 v[0:3], v[202:205], v[234:237], v[0:3]
	s_setprio 0
	s_barrier
	s_add_i32 s8, 0, 0x18000
	s_add_i32 s9, 0, 0x1c000
	v_add_u32_e32 v186, s8, v167
	v_add_u32_e32 v202, s9, v167
	ds_read_b128 v[172:175], v186
	ds_read_b128 v[178:181], v186 offset:1024
	ds_read_b128 v[182:185], v186 offset:2048
	ds_read_b128 v[186:189], v186 offset:3072
	ds_read_b128 v[190:193], v202
	ds_read_b128 v[194:197], v202 offset:1024
	ds_read_b128 v[198:201], v202 offset:2048
	ds_read_b128 v[202:205], v202 offset:3072
	v_lshl_add_u64 v[238:239], v[238:239], 0, s[10:11]
	s_mov_b32 m0, s35
	v_lshl_add_u64 v[250:251], v[238:239], 0, v[136:137]
	ds_read_b128 v[206:209], v170 offset:32768
	ds_read_b128 v[210:213], v170 offset:33792
	ds_read_b128 v[214:217], v170 offset:34816
	ds_read_b128 v[218:221], v170 offset:35840
	ds_read_b128 v[222:225], v170 offset:36864
	ds_read_b128 v[226:229], v170 offset:37888
	ds_read_b128 v[230:233], v170 offset:38912
	ds_read_b128 v[234:237], v170 offset:39936
	global_load_lds_dwordx4 v[250:251], off
	v_lshl_add_u64 v[238:239], v[238:239], 0, v[138:139]
	s_mov_b32 m0, s36
	s_nop 0
	global_load_lds_dwordx4 v[238:239], off
	s_waitcnt vmcnt(8)
	s_waitcnt lgkmcnt(0)
	s_barrier
	s_setprio 1
	s_waitcnt lgkmcnt(0)
	v_mfma_f32_16x16x32_bf16 v[124:127], v[172:175], v[206:209], v[124:127]
	v_mfma_f32_16x16x32_bf16 v[120:123], v[182:185], v[206:209], v[120:123]
	v_mfma_f32_16x16x32_bf16 v[108:111], v[172:175], v[214:217], v[108:111]
	v_mfma_f32_16x16x32_bf16 v[104:107], v[182:185], v[214:217], v[104:107]
	v_mfma_f32_16x16x32_bf16 v[92:95], v[172:175], v[222:225], v[92:95]
	v_mfma_f32_16x16x32_bf16 v[88:91], v[182:185], v[222:225], v[88:91]
	v_mfma_f32_16x16x32_bf16 v[76:79], v[172:175], v[230:233], v[76:79]
	v_mfma_f32_16x16x32_bf16 v[72:75], v[182:185], v[230:233], v[72:75]
	v_mfma_f32_16x16x32_bf16 v[124:127], v[178:181], v[210:213], v[124:127]
	v_mfma_f32_16x16x32_bf16 v[120:123], v[186:189], v[210:213], v[120:123]
	v_mfma_f32_16x16x32_bf16 v[108:111], v[178:181], v[218:221], v[108:111]
	v_mfma_f32_16x16x32_bf16 v[104:107], v[186:189], v[218:221], v[104:107]
	v_mfma_f32_16x16x32_bf16 v[92:95], v[178:181], v[226:229], v[92:95]
	v_mfma_f32_16x16x32_bf16 v[88:91], v[186:189], v[226:229], v[88:91]
	v_mfma_f32_16x16x32_bf16 v[76:79], v[178:181], v[234:237], v[76:79]
	v_mfma_f32_16x16x32_bf16 v[72:75], v[186:189], v[234:237], v[72:75]
	s_setprio 0
	s_setprio 1
	v_mfma_f32_16x16x32_bf16 v[116:119], v[190:193], v[206:209], v[116:119]
	v_mfma_f32_16x16x32_bf16 v[112:115], v[198:201], v[206:209], v[112:115]
	v_mfma_f32_16x16x32_bf16 v[100:103], v[190:193], v[214:217], v[100:103]
	v_mfma_f32_16x16x32_bf16 v[96:99], v[198:201], v[214:217], v[96:99]
	v_mfma_f32_16x16x32_bf16 v[84:87], v[190:193], v[222:225], v[84:87]
	v_mfma_f32_16x16x32_bf16 v[80:83], v[198:201], v[222:225], v[80:83]
	v_mfma_f32_16x16x32_bf16 v[68:71], v[190:193], v[230:233], v[68:71]
	v_mfma_f32_16x16x32_bf16 v[64:67], v[198:201], v[230:233], v[64:67]
	v_mfma_f32_16x16x32_bf16 v[116:119], v[194:197], v[210:213], v[116:119]
	v_mfma_f32_16x16x32_bf16 v[112:115], v[202:205], v[210:213], v[112:115]
	v_mfma_f32_16x16x32_bf16 v[100:103], v[194:197], v[218:221], v[100:103]
	v_mfma_f32_16x16x32_bf16 v[96:99], v[202:205], v[218:221], v[96:99]
	v_mfma_f32_16x16x32_bf16 v[84:87], v[194:197], v[226:229], v[84:87]
	v_mfma_f32_16x16x32_bf16 v[80:83], v[202:205], v[226:229], v[80:83]
	v_mfma_f32_16x16x32_bf16 v[68:71], v[194:197], v[234:237], v[68:71]
	v_mfma_f32_16x16x32_bf16 v[64:67], v[202:205], v[234:237], v[64:67]
	s_setprio 0
	s_barrier
	s_add_i32 s8, s8, s3
	v_lshl_add_u64 v[238:239], v[242:243], 0, s[14:15]
	s_mov_b32 m0, s8
	ds_read_b128 v[206:209], v170 offset:49152
	ds_read_b128 v[210:213], v170 offset:50176
	ds_read_b128 v[214:217], v170 offset:51200
	ds_read_b128 v[218:221], v170 offset:52224
	ds_read_b128 v[222:225], v170 offset:53248
	ds_read_b128 v[226:229], v170 offset:54272
	ds_read_b128 v[230:233], v170 offset:55296
	ds_read_b128 v[234:237], v170 offset:56320
	global_load_lds_dwordx4 v[238:239], off
	v_lshl_add_u64 v[238:239], v[244:245], 0, s[14:15]
	s_add_i32 m0, s8, 0x2000
	s_add_i32 s8, s9, s3
	global_load_lds_dwordx4 v[238:239], off
	v_lshl_add_u64 v[238:239], v[240:241], 0, s[16:17]
	v_lshl_add_u64 v[240:241], v[238:239], 0, v[134:135]
	s_mov_b32 m0, s8
	v_lshl_add_u64 v[238:239], v[238:239], 0, v[140:141]
	global_load_lds_dwordx4 v[240:241], off
	s_add_i32 m0, s8, 0x2000
	s_nop 0
	global_load_lds_dwordx4 v[238:239], off
	v_lshl_add_u64 v[238:239], v[246:247], 0, s[14:15]
	s_mov_b32 m0, s37
	s_nop 0
	global_load_lds_dwordx4 v[238:239], off
	v_lshl_add_u64 v[238:239], v[248:249], 0, s[14:15]
	s_mov_b32 m0, s38
	s_nop 0
	global_load_lds_dwordx4 v[238:239], off
	s_waitcnt vmcnt(8)
	s_waitcnt lgkmcnt(0)
	s_barrier
	s_setprio 1
	s_waitcnt lgkmcnt(0)
	v_mfma_f32_16x16x32_bf16 v[60:63], v[172:175], v[206:209], v[60:63]
	v_mfma_f32_16x16x32_bf16 v[56:59], v[182:185], v[206:209], v[56:59]
	v_mfma_f32_16x16x32_bf16 v[44:47], v[172:175], v[214:217], v[44:47]
	v_mfma_f32_16x16x32_bf16 v[40:43], v[182:185], v[214:217], v[40:43]
	v_mfma_f32_16x16x32_bf16 v[28:31], v[172:175], v[222:225], v[28:31]
	v_mfma_f32_16x16x32_bf16 v[24:27], v[182:185], v[222:225], v[24:27]
	v_mfma_f32_16x16x32_bf16 v[12:15], v[172:175], v[230:233], v[12:15]
	v_mfma_f32_16x16x32_bf16 v[8:11], v[182:185], v[230:233], v[8:11]
	v_mfma_f32_16x16x32_bf16 v[60:63], v[178:181], v[210:213], v[60:63]
	v_mfma_f32_16x16x32_bf16 v[56:59], v[186:189], v[210:213], v[56:59]
	v_mfma_f32_16x16x32_bf16 v[44:47], v[178:181], v[218:221], v[44:47]
	v_mfma_f32_16x16x32_bf16 v[40:43], v[186:189], v[218:221], v[40:43]
	v_mfma_f32_16x16x32_bf16 v[28:31], v[178:181], v[226:229], v[28:31]
	v_mfma_f32_16x16x32_bf16 v[24:27], v[186:189], v[226:229], v[24:27]
	v_mfma_f32_16x16x32_bf16 v[12:15], v[178:181], v[234:237], v[12:15]
	v_mfma_f32_16x16x32_bf16 v[8:11], v[186:189], v[234:237], v[8:11]
	s_setprio 0
	s_setprio 1
	v_mfma_f32_16x16x32_bf16 v[52:55], v[190:193], v[206:209], v[52:55]
	v_mfma_f32_16x16x32_bf16 v[48:51], v[198:201], v[206:209], v[48:51]
	v_mfma_f32_16x16x32_bf16 v[36:39], v[190:193], v[214:217], v[36:39]
	v_mfma_f32_16x16x32_bf16 v[32:35], v[198:201], v[214:217], v[32:35]
	v_mfma_f32_16x16x32_bf16 v[20:23], v[190:193], v[222:225], v[20:23]
	v_mfma_f32_16x16x32_bf16 v[16:19], v[198:201], v[222:225], v[16:19]
	v_mfma_f32_16x16x32_bf16 v[4:7], v[190:193], v[230:233], v[4:7]
	v_mfma_f32_16x16x32_bf16 v[0:3], v[198:201], v[230:233], v[0:3]
	v_mfma_f32_16x16x32_bf16 v[52:55], v[194:197], v[210:213], v[52:55]
	v_mfma_f32_16x16x32_bf16 v[48:51], v[202:205], v[210:213], v[48:51]
	v_mfma_f32_16x16x32_bf16 v[36:39], v[194:197], v[218:221], v[36:39]
	v_mfma_f32_16x16x32_bf16 v[32:35], v[202:205], v[218:221], v[32:35]
	v_mfma_f32_16x16x32_bf16 v[20:23], v[194:197], v[226:229], v[20:23]
	v_mfma_f32_16x16x32_bf16 v[16:19], v[202:205], v[226:229], v[16:19]
	v_mfma_f32_16x16x32_bf16 v[4:7], v[194:197], v[234:237], v[4:7]
	v_mfma_f32_16x16x32_bf16 v[0:3], v[202:205], v[234:237], v[0:3]
	s_setprio 0
	s_barrier
	s_add_i32 s29, s29, 2
	v_lshl_add_u64 v[162:163], v[162:163], 0, s[20:21]
	s_cmp_gt_u32 s29, 13
	v_lshl_add_u64 v[164:165], v[164:165], 0, s[20:21]
	s_cbranch_scc1 .LBB0_262

.LBB0_264:
	v_lshl_add_u32 v158, s55, 12, v168
	ds_read_b128 v[160:163], v158
	v_lshl_or_b32 v156, s54, 8, v169
	v_lshl_add_u32 v159, s30, 8, v166
	v_ashrrev_i32_e32 v157, 31, v156
	v_lshlrev_b64 v[156:157], 1, v[156:157]
	s_waitcnt lgkmcnt(0)
	v_mov_b32_e32 v164, v161
	v_mov_b32_e32 v165, v162
	v_mov_b32_e32 v161, v163
	v_pk_add_f32 v[160:161], v[164:165], v[160:161]
	s_nop 0
	v_add_f32_e32 v160, v160, v161
	v_fmamk_f32 v160, v160, 0x3a800000, v171
	v_mul_f32_e32 v161, 0x4b800000, v160
	v_cmp_gt_f32_e32 vcc, s51, v160
	s_nop 1
	v_cndmask_b32_e32 v160, v160, v161, vcc
	v_rsq_f32_e32 v162, v160
	v_mad_i64_i32 v[160:161], s[8:9], v159, s50, v[142:143]
	v_lshl_add_u64 v[160:161], v[160:161], 0, v[156:157]
	v_mul_f32_e32 v163, 0x45800000, v162
	v_cndmask_b32_e32 v162, v162, v163, vcc
	v_pk_mul_f32 v[126:127], v[126:127], v[162:163] op_sel_hi:[1,0]
	v_pk_mul_f32 v[124:125], v[124:125], v[162:163] op_sel_hi:[1,0]
	v_pk_mul_f32 v[164:165], v[122:123], v[162:163] op_sel_hi:[1,0]
	v_pk_mul_f32 v[122:123], v[120:121], v[162:163] op_sel_hi:[1,0]
	v_cvt_pk_bf16_f32 v120, v124, v125
	v_cvt_pk_bf16_f32 v121, v126, v127
	v_pk_mul_f32 v[118:119], v[118:119], v[162:163] op_sel_hi:[1,0]
	v_cvt_pk_bf16_f32 v122, v122, v123
	v_cvt_pk_bf16_f32 v123, v164, v165
	global_store_dwordx4 v[160:161], v[120:123], off
	v_pk_mul_f32 v[116:117], v[116:117], v[162:163] op_sel_hi:[1,0]
	s_nop 0
	v_pk_mul_f32 v[120:121], v[114:115], v[162:163] op_sel_hi:[1,0]
	v_pk_mul_f32 v[114:115], v[112:113], v[162:163] op_sel_hi:[1,0]
	v_cvt_pk_bf16_f32 v112, v116, v117
	v_cvt_pk_bf16_f32 v113, v118, v119
	s_nop 0
	v_cvt_pk_bf16_f32 v114, v114, v115
	v_cvt_pk_bf16_f32 v115, v120, v121
	ds_read_b128 v[116:119], v158 offset:256
	global_store_dwordx4 v[160:161], v[112:115], off offset:256
	s_nop 1
	v_or_b32_e32 v114, 16, v159
	s_waitcnt lgkmcnt(0)
	v_mov_b32_e32 v112, v117
	v_mov_b32_e32 v113, v118
	v_mov_b32_e32 v117, v119
	v_pk_add_f32 v[112:113], v[112:113], v[116:117]
	s_nop 0
	v_add_f32_e32 v112, v112, v113
	v_fmamk_f32 v112, v112, 0x3a800000, v171
	v_mul_f32_e32 v113, 0x4b800000, v112
	v_cmp_gt_f32_e32 vcc, s51, v112
	s_nop 1
	v_cndmask_b32_e32 v112, v112, v113, vcc
	v_rsq_f32_e32 v115, v112
	v_mad_i64_i32 v[112:113], s[8:9], v114, s50, v[142:143]
	v_lshl_add_u64 v[112:113], v[112:113], 0, v[156:157]
	v_mul_f32_e32 v114, 0x45800000, v115
	v_cndmask_b32_e32 v114, v115, v114, vcc
	v_pk_mul_f32 v[110:111], v[110:111], v[114:115] op_sel_hi:[1,0]
	v_pk_mul_f32 v[108:109], v[108:109], v[114:115] op_sel_hi:[1,0]
	v_pk_mul_f32 v[116:117], v[106:107], v[114:115] op_sel_hi:[1,0]
	v_pk_mul_f32 v[106:107], v[104:105], v[114:115] op_sel_hi:[1,0]
	v_cvt_pk_bf16_f32 v104, v108, v109
	v_cvt_pk_bf16_f32 v105, v110, v111
	v_pk_mul_f32 v[102:103], v[102:103], v[114:115] op_sel_hi:[1,0]
	v_cvt_pk_bf16_f32 v106, v106, v107
	v_cvt_pk_bf16_f32 v107, v116, v117
	global_store_dwordx4 v[112:113], v[104:107], off
	v_pk_mul_f32 v[100:101], v[100:101], v[114:115] op_sel_hi:[1,0]
	s_nop 0
	v_pk_mul_f32 v[104:105], v[98:99], v[114:115] op_sel_hi:[1,0]
	v_pk_mul_f32 v[98:99], v[96:97], v[114:115] op_sel_hi:[1,0]
	v_cvt_pk_bf16_f32 v96, v100, v101
	v_cvt_pk_bf16_f32 v97, v102, v103
	s_nop 0
	v_cvt_pk_bf16_f32 v98, v98, v99
	v_cvt_pk_bf16_f32 v99, v104, v105
	ds_read_b128 v[100:103], v158 offset:512
	global_store_dwordx4 v[112:113], v[96:99], off offset:256
	s_nop 1
	v_or_b32_e32 v98, 32, v159
	s_waitcnt lgkmcnt(0)
	v_mov_b32_e32 v96, v101
	v_mov_b32_e32 v97, v102
	v_mov_b32_e32 v101, v103
	v_pk_add_f32 v[96:97], v[96:97], v[100:101]
	s_nop 0
	v_add_f32_e32 v96, v96, v97
	v_fmamk_f32 v96, v96, 0x3a800000, v171
	v_mul_f32_e32 v97, 0x4b800000, v96
	v_cmp_gt_f32_e32 vcc, s51, v96
	s_nop 1
	v_cndmask_b32_e32 v96, v96, v97, vcc
	v_rsq_f32_e32 v99, v96
	v_mad_i64_i32 v[96:97], s[8:9], v98, s50, v[142:143]
	v_lshl_add_u64 v[96:97], v[96:97], 0, v[156:157]
	v_mul_f32_e32 v98, 0x45800000, v99
	v_cndmask_b32_e32 v98, v99, v98, vcc
	v_pk_mul_f32 v[94:95], v[94:95], v[98:99] op_sel_hi:[1,0]
	v_pk_mul_f32 v[92:93], v[92:93], v[98:99] op_sel_hi:[1,0]
	v_pk_mul_f32 v[100:101], v[90:91], v[98:99] op_sel_hi:[1,0]
	v_pk_mul_f32 v[90:91], v[88:89], v[98:99] op_sel_hi:[1,0]
	v_cvt_pk_bf16_f32 v88, v92, v93
	v_cvt_pk_bf16_f32 v89, v94, v95
	v_pk_mul_f32 v[86:87], v[86:87], v[98:99] op_sel_hi:[1,0]
	v_cvt_pk_bf16_f32 v90, v90, v91
	v_cvt_pk_bf16_f32 v91, v100, v101
	global_store_dwordx4 v[96:97], v[88:91], off
	v_pk_mul_f32 v[84:85], v[84:85], v[98:99] op_sel_hi:[1,0]
	s_nop 0
	v_pk_mul_f32 v[88:89], v[82:83], v[98:99] op_sel_hi:[1,0]
	v_pk_mul_f32 v[82:83], v[80:81], v[98:99] op_sel_hi:[1,0]
	v_cvt_pk_bf16_f32 v80, v84, v85
	v_cvt_pk_bf16_f32 v81, v86, v87
	s_nop 0
	v_cvt_pk_bf16_f32 v82, v82, v83
	v_cvt_pk_bf16_f32 v83, v88, v89
	ds_read_b128 v[84:87], v158 offset:768
	global_store_dwordx4 v[96:97], v[80:83], off offset:256
	s_nop 1
	v_or_b32_e32 v82, 48, v159
	s_waitcnt lgkmcnt(0)
	v_mov_b32_e32 v80, v85
	v_mov_b32_e32 v81, v86
	v_mov_b32_e32 v85, v87
	v_pk_add_f32 v[80:81], v[80:81], v[84:85]
	s_nop 0
	v_add_f32_e32 v80, v80, v81
	v_fmamk_f32 v80, v80, 0x3a800000, v171
	v_mul_f32_e32 v81, 0x4b800000, v80
	v_cmp_gt_f32_e32 vcc, s51, v80
	s_nop 1
	v_cndmask_b32_e32 v80, v80, v81, vcc
	v_rsq_f32_e32 v83, v80
	v_mad_i64_i32 v[80:81], s[8:9], v82, s50, v[142:143]
	v_lshl_add_u64 v[80:81], v[80:81], 0, v[156:157]
	v_mul_f32_e32 v82, 0x45800000, v83
	v_cndmask_b32_e32 v82, v83, v82, vcc
	v_pk_mul_f32 v[78:79], v[78:79], v[82:83] op_sel_hi:[1,0]
	v_pk_mul_f32 v[76:77], v[76:77], v[82:83] op_sel_hi:[1,0]
	v_pk_mul_f32 v[84:85], v[74:75], v[82:83] op_sel_hi:[1,0]
	v_pk_mul_f32 v[74:75], v[72:73], v[82:83] op_sel_hi:[1,0]
	v_cvt_pk_bf16_f32 v72, v76, v77
	v_cvt_pk_bf16_f32 v73, v78, v79
	v_pk_mul_f32 v[70:71], v[70:71], v[82:83] op_sel_hi:[1,0]
	v_cvt_pk_bf16_f32 v74, v74, v75
	v_cvt_pk_bf16_f32 v75, v84, v85
	global_store_dwordx4 v[80:81], v[72:75], off
	v_pk_mul_f32 v[68:69], v[68:69], v[82:83] op_sel_hi:[1,0]
	s_nop 0
	v_pk_mul_f32 v[72:73], v[66:67], v[82:83] op_sel_hi:[1,0]
	v_pk_mul_f32 v[66:67], v[64:65], v[82:83] op_sel_hi:[1,0]
	v_cvt_pk_bf16_f32 v64, v68, v69
	v_cvt_pk_bf16_f32 v65, v70, v71
	s_nop 0
	v_cvt_pk_bf16_f32 v66, v66, v67
	v_cvt_pk_bf16_f32 v67, v72, v73
	ds_read_b128 v[68:71], v158 offset:2048
	global_store_dwordx4 v[80:81], v[64:67], off offset:256
	s_nop 1
	v_add_u32_e32 v66, 0x80, v159
	s_waitcnt lgkmcnt(0)
	v_mov_b32_e32 v64, v69
	v_mov_b32_e32 v65, v70
	v_mov_b32_e32 v69, v71
	v_pk_add_f32 v[64:65], v[64:65], v[68:69]
	s_nop 0
	v_add_f32_e32 v64, v64, v65
	v_fmamk_f32 v64, v64, 0x3a800000, v171
	v_mul_f32_e32 v65, 0x4b800000, v64
	v_cmp_gt_f32_e32 vcc, s51, v64
	s_nop 1
	v_cndmask_b32_e32 v64, v64, v65, vcc
	v_rsq_f32_e32 v67, v64
	v_mad_i64_i32 v[64:65], s[8:9], v66, s50, v[142:143]
	v_lshl_add_u64 v[64:65], v[64:65], 0, v[156:157]
	v_mul_f32_e32 v66, 0x45800000, v67
	v_cndmask_b32_e32 v66, v67, v66, vcc
	v_pk_mul_f32 v[62:63], v[62:63], v[66:67] op_sel_hi:[1,0]
	v_pk_mul_f32 v[60:61], v[60:61], v[66:67] op_sel_hi:[1,0]
	v_pk_mul_f32 v[68:69], v[58:59], v[66:67] op_sel_hi:[1,0]
	v_pk_mul_f32 v[58:59], v[56:57], v[66:67] op_sel_hi:[1,0]
	v_cvt_pk_bf16_f32 v56, v60, v61
	v_cvt_pk_bf16_f32 v57, v62, v63
	v_pk_mul_f32 v[54:55], v[54:55], v[66:67] op_sel_hi:[1,0]
	v_cvt_pk_bf16_f32 v58, v58, v59
	v_cvt_pk_bf16_f32 v59, v68, v69
	global_store_dwordx4 v[64:65], v[56:59], off
	v_pk_mul_f32 v[52:53], v[52:53], v[66:67] op_sel_hi:[1,0]
	s_nop 0
	v_pk_mul_f32 v[56:57], v[50:51], v[66:67] op_sel_hi:[1,0]
	v_pk_mul_f32 v[50:51], v[48:49], v[66:67] op_sel_hi:[1,0]
	v_cvt_pk_bf16_f32 v48, v52, v53
	v_cvt_pk_bf16_f32 v49, v54, v55
	s_nop 0
	v_cvt_pk_bf16_f32 v50, v50, v51
	v_cvt_pk_bf16_f32 v51, v56, v57
	ds_read_b128 v[52:55], v158 offset:2304
	global_store_dwordx4 v[64:65], v[48:51], off offset:256
	s_nop 1
	v_add_u32_e32 v50, 0x90, v159
	s_waitcnt lgkmcnt(0)
	v_mov_b32_e32 v48, v53
	v_mov_b32_e32 v49, v54
	v_mov_b32_e32 v53, v55
	v_pk_add_f32 v[48:49], v[48:49], v[52:53]
	s_nop 0
	v_add_f32_e32 v48, v48, v49
	v_fmamk_f32 v48, v48, 0x3a800000, v171
	v_mul_f32_e32 v49, 0x4b800000, v48
	v_cmp_gt_f32_e32 vcc, s51, v48
	s_nop 1
	v_cndmask_b32_e32 v48, v48, v49, vcc
	v_rsq_f32_e32 v51, v48
	v_mad_i64_i32 v[48:49], s[8:9], v50, s50, v[142:143]
	v_lshl_add_u64 v[48:49], v[48:49], 0, v[156:157]
	v_mul_f32_e32 v50, 0x45800000, v51
	v_cndmask_b32_e32 v50, v51, v50, vcc
	v_pk_mul_f32 v[46:47], v[46:47], v[50:51] op_sel_hi:[1,0]
	v_pk_mul_f32 v[44:45], v[44:45], v[50:51] op_sel_hi:[1,0]
	v_pk_mul_f32 v[52:53], v[42:43], v[50:51] op_sel_hi:[1,0]
	v_pk_mul_f32 v[42:43], v[40:41], v[50:51] op_sel_hi:[1,0]
	v_cvt_pk_bf16_f32 v40, v44, v45
	v_cvt_pk_bf16_f32 v41, v46, v47
	v_pk_mul_f32 v[38:39], v[38:39], v[50:51] op_sel_hi:[1,0]
	v_cvt_pk_bf16_f32 v42, v42, v43
	v_cvt_pk_bf16_f32 v43, v52, v53
	global_store_dwordx4 v[48:49], v[40:43], off
	v_pk_mul_f32 v[36:37], v[36:37], v[50:51] op_sel_hi:[1,0]
	s_nop 0
	v_pk_mul_f32 v[40:41], v[34:35], v[50:51] op_sel_hi:[1,0]
	v_pk_mul_f32 v[34:35], v[32:33], v[50:51] op_sel_hi:[1,0]
	v_cvt_pk_bf16_f32 v32, v36, v37
	v_cvt_pk_bf16_f32 v33, v38, v39
	s_nop 0
	v_cvt_pk_bf16_f32 v34, v34, v35
	v_cvt_pk_bf16_f32 v35, v40, v41
	ds_read_b128 v[36:39], v158 offset:2560
	global_store_dwordx4 v[48:49], v[32:35], off offset:256
	s_nop 1
	v_add_u32_e32 v34, 0xa0, v159
	s_waitcnt lgkmcnt(0)
	v_mov_b32_e32 v32, v37
	v_mov_b32_e32 v33, v38
	v_mov_b32_e32 v37, v39
	v_pk_add_f32 v[32:33], v[32:33], v[36:37]
	s_nop 0
	v_add_f32_e32 v32, v32, v33
	v_fmamk_f32 v32, v32, 0x3a800000, v171
	v_mul_f32_e32 v33, 0x4b800000, v32
	v_cmp_gt_f32_e32 vcc, s51, v32
	s_nop 1
	v_cndmask_b32_e32 v32, v32, v33, vcc
	v_rsq_f32_e32 v35, v32
	v_mad_i64_i32 v[32:33], s[8:9], v34, s50, v[142:143]
	v_lshl_add_u64 v[32:33], v[32:33], 0, v[156:157]
	v_mul_f32_e32 v34, 0x45800000, v35
	v_cndmask_b32_e32 v34, v35, v34, vcc
	v_pk_mul_f32 v[30:31], v[30:31], v[34:35] op_sel_hi:[1,0]
	v_pk_mul_f32 v[28:29], v[28:29], v[34:35] op_sel_hi:[1,0]
	v_pk_mul_f32 v[36:37], v[26:27], v[34:35] op_sel_hi:[1,0]
	v_pk_mul_f32 v[26:27], v[24:25], v[34:35] op_sel_hi:[1,0]
	v_cvt_pk_bf16_f32 v24, v28, v29
	v_cvt_pk_bf16_f32 v25, v30, v31
	v_pk_mul_f32 v[22:23], v[22:23], v[34:35] op_sel_hi:[1,0]
	v_cvt_pk_bf16_f32 v26, v26, v27
	v_cvt_pk_bf16_f32 v27, v36, v37
	global_store_dwordx4 v[32:33], v[24:27], off
	v_pk_mul_f32 v[20:21], v[20:21], v[34:35] op_sel_hi:[1,0]
	s_nop 0
	v_pk_mul_f32 v[24:25], v[18:19], v[34:35] op_sel_hi:[1,0]
	v_pk_mul_f32 v[18:19], v[16:17], v[34:35] op_sel_hi:[1,0]
	v_cvt_pk_bf16_f32 v16, v20, v21
	v_cvt_pk_bf16_f32 v17, v22, v23
	s_nop 0
	v_cvt_pk_bf16_f32 v18, v18, v19
	v_cvt_pk_bf16_f32 v19, v24, v25
	ds_read_b128 v[20:23], v158 offset:2816
	global_store_dwordx4 v[32:33], v[16:19], off offset:256
	s_nop 1
	v_add_u32_e32 v18, 0xb0, v159
	s_waitcnt lgkmcnt(0)
	v_mov_b32_e32 v16, v21
	v_mov_b32_e32 v17, v22
	v_mov_b32_e32 v21, v23
	v_pk_add_f32 v[16:17], v[16:17], v[20:21]
	s_nop 0
	v_add_f32_e32 v16, v16, v17
	v_fmamk_f32 v16, v16, 0x3a800000, v171
	v_mul_f32_e32 v17, 0x4b800000, v16
	v_cmp_gt_f32_e32 vcc, s51, v16
	s_nop 1
	v_cndmask_b32_e32 v16, v16, v17, vcc
	v_rsq_f32_e32 v19, v16
	v_mad_i64_i32 v[16:17], s[8:9], v18, s50, v[142:143]
	v_lshl_add_u64 v[16:17], v[16:17], 0, v[156:157]
	v_mul_f32_e32 v18, 0x45800000, v19
	v_cndmask_b32_e32 v18, v19, v18, vcc
	v_pk_mul_f32 v[14:15], v[14:15], v[18:19] op_sel_hi:[1,0]
	v_pk_mul_f32 v[12:13], v[12:13], v[18:19] op_sel_hi:[1,0]
	v_pk_mul_f32 v[20:21], v[10:11], v[18:19] op_sel_hi:[1,0]
	v_pk_mul_f32 v[10:11], v[8:9], v[18:19] op_sel_hi:[1,0]
	v_cvt_pk_bf16_f32 v8, v12, v13
	v_cvt_pk_bf16_f32 v9, v14, v15
	s_andn2_b64 vcc, exec, s[6:7]
	v_cvt_pk_bf16_f32 v10, v10, v11
	v_cvt_pk_bf16_f32 v11, v20, v21
	global_store_dwordx4 v[16:17], v[8:11], off
	s_mov_b64 s[6:7], -1
	v_pk_mul_f32 v[6:7], v[6:7], v[18:19] op_sel_hi:[1,0]
	v_pk_mul_f32 v[8:9], v[2:3], v[18:19] op_sel_hi:[1,0]
	v_pk_mul_f32 v[2:3], v[0:1], v[18:19] op_sel_hi:[1,0]
	v_pk_mul_f32 v[4:5], v[4:5], v[18:19] op_sel_hi:[1,0]
	s_nop 0
	v_cvt_pk_bf16_f32 v0, v4, v5
	v_cvt_pk_bf16_f32 v1, v6, v7
	v_cvt_pk_bf16_f32 v2, v2, v3
	v_cvt_pk_bf16_f32 v3, v8, v9
	global_store_dwordx4 v[16:17], v[0:3], off offset:256
	s_mov_b32 s100, 1
	s_cbranch_vccnz .LBB0_254
	s_andn2_b64 vcc, exec, s[12:13]
	s_cbranch_vccnz .LBB0_253
	s_barrier
	s_branch .LBB0_253

.LBB0_613:
	s_mov_b64 s[16:17], 0x80
	s_add_i32 m0, s35, 0x18000
	v_lshl_add_u64 v[6:7], v[6:7], 0, s[16:17]
	s_waitcnt vmcnt(2)
	s_barrier
	global_load_lds_dwordx4 v[6:7], off
	v_lshl_add_u64 v[6:7], v[8:9], 0, s[16:17]
	s_add_i32 m0, s35, 0x1a000
	s_add_i32 s40, s35, 0x8000
	global_load_lds_dwordx4 v[6:7], off
	v_lshl_add_u64 v[6:7], v[10:11], 0, s[16:17]
	s_mov_b32 m0, s40
	s_add_i32 s41, s35, 0xa000
	global_load_lds_dwordx4 v[6:7], off
	v_lshl_add_u64 v[6:7], v[12:13], 0, s[16:17]
	s_mov_b32 m0, s41
	s_mov_b64 s[18:19], 0x40080
	global_load_lds_dwordx4 v[6:7], off
	v_lshl_add_u64 v[6:7], v[2:3], 0, s[18:19]
	s_add_i32 m0, s35, 0x1c000
	v_lshl_add_u64 v[8:9], v[6:7], 0, v[136:137]
	global_load_lds_dwordx4 v[8:9], off
	v_lshl_add_u64 v[6:7], v[6:7], 0, v[140:141]
	s_add_i32 m0, s35, 0x1e000
	s_mov_b64 s[20:21], 0xd000000
	global_load_lds_dwordx4 v[6:7], off
	v_lshl_add_u64 v[142:143], v[4:5], 0, s[20:21]
	v_lshrrev_b32_e32 v5, 1, v14
	v_and_b32_e32 v5, 24, v5
	v_and_b32_e32 v4, 15, v14
	v_lshlrev_b32_e32 v6, 1, v5
	v_lshl_or_b32 v166, s10, 6, v4
	v_lshl_or_b32 v4, v4, 6, v6
	v_lshlrev_b32_e32 v6, 2, v14
	s_lshl_b32 s9, s9, 5
	s_lshl_b32 s10, s10, 13
	v_and_b32_e32 v6, 32, v6
	s_and_b32 s9, s9, 0x60
	v_bitop3_b32 v7, v4, s10, v6 bitop3:0xde
	s_lshl_b32 s10, s9, 7
	v_bitop3_b32 v167, v4, s10, v6 bitop3:0xde
	v_lshlrev_b32_e32 v4, 14, v18
	v_and_b32_e32 v4, 0xffff8000, v4
	v_or_b32_e32 v169, s9, v5
	v_lshl_add_u32 v4, v19, 11, v4
	v_and_b32_e32 v5, 1, v18
	v_lshl_or_b32 v4, v5, 6, v4
	v_lshl_add_u32 v144, v20, 1, v4
	v_lshlrev_b32_e32 v4, 14, v15
	v_and_b32_e32 v4, 0xffff8000, v4
	s_waitcnt vmcnt(6)
	s_cmpk_lt_u32 s8, 0x100
	v_lshl_add_u32 v4, v16, 11, v4
	v_and_b32_e32 v5, 1, v15
	s_cselect_b64 s[20:21], -1, 0
	s_add_i32 s8, 0, 0x21c00
	v_lshl_or_b32 v4, v5, 6, v4
	s_mov_b32 s26, 0xfffc0080
	s_mov_b32 s55, 0
	v_lshl_add_u32 v168, v166, 4, s8
	v_mov_b32_e32 v145, v137
	v_lshl_add_u32 v146, v17, 1, v4
	v_mov_b32_e32 v147, v137
	v_mov_b64_e32 v[148:149], 0xb00
	v_mov_b64_e32 v[150:151], 0xaff
	s_movk_i32 s42, 0x161
	s_mov_b64 s[22:23], 0x100
	s_mov_b32 s27, -1
	s_add_i32 s43, 0, 0x10000
	s_add_i32 s44, 0, 0x14000
	v_add_u32_e32 v170, 0, v7
	s_add_i32 s45, s35, 0xc000
	s_add_i32 s50, s35, 0xe000
	s_movk_i32 s51, 0x1600
	v_mov_b32_e32 v171, 0x358637bd
	s_mov_b32 s52, 0x800000
	s_mov_b32 s53, 0
	s_barrier
	s_mov_b32 s100, 0
	s_branch .LBB0_616

.LBB0_619:
	v_add_u32_e32 v186, s43, v167
	v_add_u32_e32 v202, s44, v167
	ds_read_b128 v[172:175], v186
	ds_read_b128 v[178:181], v186 offset:1024
	ds_read_b128 v[182:185], v186 offset:2048
	ds_read_b128 v[186:189], v186 offset:3072
	ds_read_b128 v[190:193], v202
	ds_read_b128 v[194:197], v202 offset:1024
	ds_read_b128 v[198:201], v202 offset:2048
	ds_read_b128 v[202:205], v202 offset:3072
	v_lshl_add_u64 v[206:207], v[164:165], 0, s[26:27]
	v_cndmask_b32_e64 v215, v207, v157, s[10:11]
	v_cndmask_b32_e64 v214, v206, v156, s[10:11]
	v_cndmask_b32_e64 v243, v163, v159, s[10:11]
	v_cndmask_b32_e64 v242, v162, v158, s[10:11]
	s_mov_b32 m0, s45
	v_lshl_add_u64 v[244:245], v[164:165], 0, v[146:147]
	ds_read_b128 v[206:209], v170
	ds_read_b128 v[210:213], v170 offset:1024
	ds_read_b128 v[218:221], v170 offset:2048
	ds_read_b128 v[222:225], v170 offset:3072
	ds_read_b128 v[226:229], v170 offset:4096
	ds_read_b128 v[230:233], v170 offset:5120
	ds_read_b128 v[234:237], v170 offset:6144
	ds_read_b128 v[238:241], v170 offset:7168
	global_load_lds_dwordx4 v[244:245], off
	v_lshl_add_u64 v[244:245], v[164:165], 0, v[144:145]
	s_mov_b32 m0, s50
	s_nop 0
	global_load_lds_dwordx4 v[244:245], off
	s_cmp_eq_u32 s100, 0
	s_cbranch_scc1 .Lgw8_20706_0
	s_waitcnt vmcnt(16)
	s_branch .Lgwd_20706_0

.Lgwd_20706_0:
	s_waitcnt lgkmcnt(0)
	s_barrier
	s_setprio 1
	s_waitcnt lgkmcnt(0)
	v_mfma_f32_16x16x32_bf16 v[124:127], v[172:175], v[206:209], v[124:127]
	v_mfma_f32_16x16x32_bf16 v[116:119], v[182:185], v[206:209], v[116:119]
	v_mfma_f32_16x16x32_bf16 v[108:111], v[172:175], v[218:221], v[108:111]
	v_mfma_f32_16x16x32_bf16 v[100:103], v[182:185], v[218:221], v[100:103]
	v_mfma_f32_16x16x32_bf16 v[92:95], v[172:175], v[226:229], v[92:95]
	v_mfma_f32_16x16x32_bf16 v[84:87], v[182:185], v[226:229], v[84:87]
	v_mfma_f32_16x16x32_bf16 v[76:79], v[172:175], v[234:237], v[76:79]
	v_mfma_f32_16x16x32_bf16 v[68:71], v[182:185], v[234:237], v[68:71]
	v_mfma_f32_16x16x32_bf16 v[124:127], v[178:181], v[210:213], v[124:127]
	v_mfma_f32_16x16x32_bf16 v[116:119], v[186:189], v[210:213], v[116:119]
	v_mfma_f32_16x16x32_bf16 v[108:111], v[178:181], v[222:225], v[108:111]
	v_mfma_f32_16x16x32_bf16 v[100:103], v[186:189], v[222:225], v[100:103]
	v_mfma_f32_16x16x32_bf16 v[92:95], v[178:181], v[230:233], v[92:95]
	v_mfma_f32_16x16x32_bf16 v[84:87], v[186:189], v[230:233], v[84:87]
	v_mfma_f32_16x16x32_bf16 v[76:79], v[178:181], v[238:241], v[76:79]
	v_mfma_f32_16x16x32_bf16 v[68:71], v[186:189], v[238:241], v[68:71]
	s_setprio 0
	s_setprio 1
	v_mfma_f32_16x16x32_bf16 v[120:123], v[190:193], v[206:209], v[120:123]
	v_mfma_f32_16x16x32_bf16 v[112:115], v[198:201], v[206:209], v[112:115]
	v_mfma_f32_16x16x32_bf16 v[104:107], v[190:193], v[218:221], v[104:107]
	v_mfma_f32_16x16x32_bf16 v[96:99], v[198:201], v[218:221], v[96:99]
	v_mfma_f32_16x16x32_bf16 v[88:91], v[190:193], v[226:229], v[88:91]
	v_mfma_f32_16x16x32_bf16 v[80:83], v[198:201], v[226:229], v[80:83]
	v_mfma_f32_16x16x32_bf16 v[72:75], v[190:193], v[234:237], v[72:75]
	v_mfma_f32_16x16x32_bf16 v[64:67], v[198:201], v[234:237], v[64:67]
	v_mfma_f32_16x16x32_bf16 v[120:123], v[194:197], v[210:213], v[120:123]
	v_mfma_f32_16x16x32_bf16 v[112:115], v[202:205], v[210:213], v[112:115]
	v_mfma_f32_16x16x32_bf16 v[104:107], v[194:197], v[222:225], v[104:107]
	v_mfma_f32_16x16x32_bf16 v[96:99], v[202:205], v[222:225], v[96:99]
	v_mfma_f32_16x16x32_bf16 v[88:91], v[194:197], v[230:233], v[88:91]
	v_mfma_f32_16x16x32_bf16 v[80:83], v[202:205], v[230:233], v[80:83]
	v_mfma_f32_16x16x32_bf16 v[72:75], v[194:197], v[238:241], v[72:75]
	v_mfma_f32_16x16x32_bf16 v[64:67], v[202:205], v[238:241], v[64:67]
	s_setprio 0
	s_barrier
	s_add_i32 s10, s43, s3
	v_lshl_add_u64 v[244:245], v[242:243], 0, v[136:137]
	s_mov_b32 m0, s10
	ds_read_b128 v[206:209], v170 offset:16384
	ds_read_b128 v[210:213], v170 offset:17408
	ds_read_b128 v[218:221], v170 offset:18432
	ds_read_b128 v[222:225], v170 offset:19456
	ds_read_b128 v[226:229], v170 offset:20480
	ds_read_b128 v[230:233], v170 offset:21504
	ds_read_b128 v[234:237], v170 offset:22528
	ds_read_b128 v[238:241], v170 offset:23552
	global_load_lds_dwordx4 v[244:245], off
	v_lshl_add_u64 v[246:247], v[242:243], 0, v[140:141]
	s_add_i32 m0, s10, 0x2000
	v_lshl_add_u64 v[248:249], v[242:243], 0, s[12:13]
	s_add_i32 s10, s44, s3
	global_load_lds_dwordx4 v[246:247], off
	v_lshl_add_u64 v[250:251], v[248:249], 0, v[136:137]
	s_mov_b32 m0, s10
	v_lshl_add_u64 v[248:249], v[248:249], 0, v[140:141]
	global_load_lds_dwordx4 v[250:251], off
	s_add_i32 m0, s10, 0x2000
	v_lshl_add_u64 v[250:251], v[214:215], 0, v[138:139]
	global_load_lds_dwordx4 v[248:249], off
	v_lshl_add_u64 v[248:249], v[214:215], 0, v[134:135]
	s_mov_b32 m0, s35
	s_nop 0
	global_load_lds_dwordx4 v[248:249], off
	s_mov_b32 m0, s37
	s_nop 0
	global_load_lds_dwordx4 v[250:251], off
	s_cmp_eq_u32 s100, 0
	s_cbranch_scc1 .Lgw8_20706_1
	s_waitcnt vmcnt(16)
	s_mov_b32 s100, 0
	s_branch .Lgwd_20706_1

.Lgwd_20706_1:
	s_waitcnt lgkmcnt(0)
	s_barrier
	s_setprio 1
	s_waitcnt lgkmcnt(0)
	v_mfma_f32_16x16x32_bf16 v[60:63], v[172:175], v[206:209], v[60:63]
	v_mfma_f32_16x16x32_bf16 v[52:55], v[182:185], v[206:209], v[52:55]
	v_mfma_f32_16x16x32_bf16 v[44:47], v[172:175], v[218:221], v[44:47]
	v_mfma_f32_16x16x32_bf16 v[36:39], v[182:185], v[218:221], v[36:39]
	v_mfma_f32_16x16x32_bf16 v[28:31], v[172:175], v[226:229], v[28:31]
	v_mfma_f32_16x16x32_bf16 v[20:23], v[182:185], v[226:229], v[20:23]
	v_mfma_f32_16x16x32_bf16 v[12:15], v[172:175], v[234:237], v[12:15]
	v_mfma_f32_16x16x32_bf16 v[4:7], v[182:185], v[234:237], v[4:7]
	v_mfma_f32_16x16x32_bf16 v[60:63], v[178:181], v[210:213], v[60:63]
	v_mfma_f32_16x16x32_bf16 v[52:55], v[186:189], v[210:213], v[52:55]
	v_mfma_f32_16x16x32_bf16 v[44:47], v[178:181], v[222:225], v[44:47]
	v_mfma_f32_16x16x32_bf16 v[36:39], v[186:189], v[222:225], v[36:39]
	v_mfma_f32_16x16x32_bf16 v[28:31], v[178:181], v[230:233], v[28:31]
	v_mfma_f32_16x16x32_bf16 v[20:23], v[186:189], v[230:233], v[20:23]
	v_mfma_f32_16x16x32_bf16 v[12:15], v[178:181], v[238:241], v[12:15]
	v_mfma_f32_16x16x32_bf16 v[4:7], v[186:189], v[238:241], v[4:7]
	s_setprio 0
	s_setprio 1
	v_mfma_f32_16x16x32_bf16 v[56:59], v[190:193], v[206:209], v[56:59]
	v_mfma_f32_16x16x32_bf16 v[48:51], v[198:201], v[206:209], v[48:51]
	v_mfma_f32_16x16x32_bf16 v[40:43], v[190:193], v[218:221], v[40:43]
	v_mfma_f32_16x16x32_bf16 v[32:35], v[198:201], v[218:221], v[32:35]
	v_mfma_f32_16x16x32_bf16 v[24:27], v[190:193], v[226:229], v[24:27]
	v_mfma_f32_16x16x32_bf16 v[16:19], v[198:201], v[226:229], v[16:19]
	v_mfma_f32_16x16x32_bf16 v[8:11], v[190:193], v[234:237], v[8:11]
	v_mfma_f32_16x16x32_bf16 v[0:3], v[198:201], v[234:237], v[0:3]
	v_mfma_f32_16x16x32_bf16 v[56:59], v[194:197], v[210:213], v[56:59]
	v_mfma_f32_16x16x32_bf16 v[48:51], v[202:205], v[210:213], v[48:51]
	v_mfma_f32_16x16x32_bf16 v[40:43], v[194:197], v[222:225], v[40:43]
	v_mfma_f32_16x16x32_bf16 v[32:35], v[202:205], v[222:225], v[32:35]
	v_mfma_f32_16x16x32_bf16 v[24:27], v[194:197], v[230:233], v[24:27]
	v_mfma_f32_16x16x32_bf16 v[16:19], v[202:205], v[230:233], v[16:19]
	v_mfma_f32_16x16x32_bf16 v[8:11], v[194:197], v[238:241], v[8:11]
	v_mfma_f32_16x16x32_bf16 v[0:3], v[202:205], v[238:241], v[0:3]
	s_setprio 0
	s_barrier
	s_add_i32 s10, 0, 0x18000
	s_add_i32 s11, 0, 0x1c000
	v_add_u32_e32 v186, s10, v167
	v_add_u32_e32 v202, s11, v167
	ds_read_b128 v[172:175], v186
	ds_read_b128 v[178:181], v186 offset:1024
	ds_read_b128 v[182:185], v186 offset:2048
	ds_read_b128 v[186:189], v186 offset:3072
	ds_read_b128 v[190:193], v202
	ds_read_b128 v[194:197], v202 offset:1024
	ds_read_b128 v[198:201], v202 offset:2048
	ds_read_b128 v[202:205], v202 offset:3072
	v_lshl_add_u64 v[214:215], v[214:215], 0, s[12:13]
	s_mov_b32 m0, s38
	v_lshl_add_u64 v[252:253], v[214:215], 0, v[134:135]
	ds_read_b128 v[206:209], v170 offset:32768
	ds_read_b128 v[210:213], v170 offset:33792
	ds_read_b128 v[218:221], v170 offset:34816
	ds_read_b128 v[222:225], v170 offset:35840
	ds_read_b128 v[226:229], v170 offset:36864
	ds_read_b128 v[230:233], v170 offset:37888
	ds_read_b128 v[234:237], v170 offset:38912
	ds_read_b128 v[238:241], v170 offset:39936
	global_load_lds_dwordx4 v[252:253], off
	v_lshl_add_u64 v[214:215], v[214:215], 0, v[138:139]
	s_mov_b32 m0, s39
	s_nop 0
	global_load_lds_dwordx4 v[214:215], off
	s_waitcnt vmcnt(8)
	s_waitcnt lgkmcnt(0)
	s_barrier
	s_setprio 1
	s_waitcnt lgkmcnt(0)
	v_mfma_f32_16x16x32_bf16 v[124:127], v[172:175], v[206:209], v[124:127]
	v_mfma_f32_16x16x32_bf16 v[116:119], v[182:185], v[206:209], v[116:119]
	v_mfma_f32_16x16x32_bf16 v[108:111], v[172:175], v[218:221], v[108:111]
	v_mfma_f32_16x16x32_bf16 v[100:103], v[182:185], v[218:221], v[100:103]
	v_mfma_f32_16x16x32_bf16 v[92:95], v[172:175], v[226:229], v[92:95]
	v_mfma_f32_16x16x32_bf16 v[84:87], v[182:185], v[226:229], v[84:87]
	v_mfma_f32_16x16x32_bf16 v[76:79], v[172:175], v[234:237], v[76:79]
	v_mfma_f32_16x16x32_bf16 v[68:71], v[182:185], v[234:237], v[68:71]
	v_mfma_f32_16x16x32_bf16 v[124:127], v[178:181], v[210:213], v[124:127]
	v_mfma_f32_16x16x32_bf16 v[116:119], v[186:189], v[210:213], v[116:119]
	v_mfma_f32_16x16x32_bf16 v[108:111], v[178:181], v[222:225], v[108:111]
	v_mfma_f32_16x16x32_bf16 v[100:103], v[186:189], v[222:225], v[100:103]
	v_mfma_f32_16x16x32_bf16 v[92:95], v[178:181], v[230:233], v[92:95]
	v_mfma_f32_16x16x32_bf16 v[84:87], v[186:189], v[230:233], v[84:87]
	v_mfma_f32_16x16x32_bf16 v[76:79], v[178:181], v[238:241], v[76:79]
	v_mfma_f32_16x16x32_bf16 v[68:71], v[186:189], v[238:241], v[68:71]
	s_setprio 0
	s_setprio 1
	v_mfma_f32_16x16x32_bf16 v[120:123], v[190:193], v[206:209], v[120:123]
	v_mfma_f32_16x16x32_bf16 v[112:115], v[198:201], v[206:209], v[112:115]
	v_mfma_f32_16x16x32_bf16 v[104:107], v[190:193], v[218:221], v[104:107]
	v_mfma_f32_16x16x32_bf16 v[96:99], v[198:201], v[218:221], v[96:99]
	v_mfma_f32_16x16x32_bf16 v[88:91], v[190:193], v[226:229], v[88:91]
	v_mfma_f32_16x16x32_bf16 v[80:83], v[198:201], v[226:229], v[80:83]
	v_mfma_f32_16x16x32_bf16 v[72:75], v[190:193], v[234:237], v[72:75]
	v_mfma_f32_16x16x32_bf16 v[64:67], v[198:201], v[234:237], v[64:67]
	v_mfma_f32_16x16x32_bf16 v[120:123], v[194:197], v[210:213], v[120:123]
	v_mfma_f32_16x16x32_bf16 v[112:115], v[202:205], v[210:213], v[112:115]
	v_mfma_f32_16x16x32_bf16 v[104:107], v[194:197], v[222:225], v[104:107]
	v_mfma_f32_16x16x32_bf16 v[96:99], v[202:205], v[222:225], v[96:99]
	v_mfma_f32_16x16x32_bf16 v[88:91], v[194:197], v[230:233], v[88:91]
	v_mfma_f32_16x16x32_bf16 v[80:83], v[202:205], v[230:233], v[80:83]
	v_mfma_f32_16x16x32_bf16 v[72:75], v[194:197], v[238:241], v[72:75]
	v_mfma_f32_16x16x32_bf16 v[64:67], v[202:205], v[238:241], v[64:67]
	s_setprio 0
	s_barrier
	s_add_i32 s10, s10, s3
	v_lshl_add_u64 v[214:215], v[244:245], 0, s[16:17]
	s_mov_b32 m0, s10
	ds_read_b128 v[206:209], v170 offset:49152
	ds_read_b128 v[210:213], v170 offset:50176
	ds_read_b128 v[218:221], v170 offset:51200
	ds_read_b128 v[222:225], v170 offset:52224
	ds_read_b128 v[226:229], v170 offset:53248
	ds_read_b128 v[230:233], v170 offset:54272
	ds_read_b128 v[234:237], v170 offset:55296
	ds_read_b128 v[238:241], v170 offset:56320
	global_load_lds_dwordx4 v[214:215], off
	v_lshl_add_u64 v[214:215], v[246:247], 0, s[16:17]
	s_add_i32 m0, s10, 0x2000
	s_add_i32 s10, s11, s3
	global_load_lds_dwordx4 v[214:215], off
	v_lshl_add_u64 v[214:215], v[242:243], 0, s[18:19]
	v_lshl_add_u64 v[242:243], v[214:215], 0, v[136:137]
	s_mov_b32 m0, s10
	v_lshl_add_u64 v[214:215], v[214:215], 0, v[140:141]
	global_load_lds_dwordx4 v[242:243], off
	s_add_i32 m0, s10, 0x2000
	s_nop 0
	global_load_lds_dwordx4 v[214:215], off
	v_lshl_add_u64 v[214:215], v[248:249], 0, s[16:17]
	s_mov_b32 m0, s40
	s_nop 0
	global_load_lds_dwordx4 v[214:215], off
	v_lshl_add_u64 v[214:215], v[250:251], 0, s[16:17]
	s_mov_b32 m0, s41
	s_nop 0
	global_load_lds_dwordx4 v[214:215], off
	s_waitcnt vmcnt(8)
	s_waitcnt lgkmcnt(0)
	s_barrier
	s_setprio 1
	s_waitcnt lgkmcnt(0)
	v_mfma_f32_16x16x32_bf16 v[60:63], v[172:175], v[206:209], v[60:63]
	v_mfma_f32_16x16x32_bf16 v[52:55], v[182:185], v[206:209], v[52:55]
	v_mfma_f32_16x16x32_bf16 v[44:47], v[172:175], v[218:221], v[44:47]
	v_mfma_f32_16x16x32_bf16 v[36:39], v[182:185], v[218:221], v[36:39]
	v_mfma_f32_16x16x32_bf16 v[28:31], v[172:175], v[226:229], v[28:31]
	v_mfma_f32_16x16x32_bf16 v[20:23], v[182:185], v[226:229], v[20:23]
	v_mfma_f32_16x16x32_bf16 v[12:15], v[172:175], v[234:237], v[12:15]
	v_mfma_f32_16x16x32_bf16 v[4:7], v[182:185], v[234:237], v[4:7]
	v_mfma_f32_16x16x32_bf16 v[60:63], v[178:181], v[210:213], v[60:63]
	v_mfma_f32_16x16x32_bf16 v[52:55], v[186:189], v[210:213], v[52:55]
	v_mfma_f32_16x16x32_bf16 v[44:47], v[178:181], v[222:225], v[44:47]
	v_mfma_f32_16x16x32_bf16 v[36:39], v[186:189], v[222:225], v[36:39]
	v_mfma_f32_16x16x32_bf16 v[28:31], v[178:181], v[230:233], v[28:31]
	v_mfma_f32_16x16x32_bf16 v[20:23], v[186:189], v[230:233], v[20:23]
	v_mfma_f32_16x16x32_bf16 v[12:15], v[178:181], v[238:241], v[12:15]
	v_mfma_f32_16x16x32_bf16 v[4:7], v[186:189], v[238:241], v[4:7]
	s_setprio 0
	s_setprio 1
	v_mfma_f32_16x16x32_bf16 v[56:59], v[190:193], v[206:209], v[56:59]
	v_mfma_f32_16x16x32_bf16 v[48:51], v[198:201], v[206:209], v[48:51]
	v_mfma_f32_16x16x32_bf16 v[40:43], v[190:193], v[218:221], v[40:43]
	v_mfma_f32_16x16x32_bf16 v[32:35], v[198:201], v[218:221], v[32:35]
	v_mfma_f32_16x16x32_bf16 v[24:27], v[190:193], v[226:229], v[24:27]
	v_mfma_f32_16x16x32_bf16 v[16:19], v[198:201], v[226:229], v[16:19]
	v_mfma_f32_16x16x32_bf16 v[8:11], v[190:193], v[234:237], v[8:11]
	v_mfma_f32_16x16x32_bf16 v[0:3], v[198:201], v[234:237], v[0:3]
	v_mfma_f32_16x16x32_bf16 v[56:59], v[194:197], v[210:213], v[56:59]
	v_mfma_f32_16x16x32_bf16 v[48:51], v[202:205], v[210:213], v[48:51]
	v_mfma_f32_16x16x32_bf16 v[40:43], v[194:197], v[222:225], v[40:43]
	v_mfma_f32_16x16x32_bf16 v[32:35], v[202:205], v[222:225], v[32:35]
	v_mfma_f32_16x16x32_bf16 v[24:27], v[194:197], v[230:233], v[24:27]
	v_mfma_f32_16x16x32_bf16 v[16:19], v[202:205], v[230:233], v[16:19]
	v_mfma_f32_16x16x32_bf16 v[8:11], v[194:197], v[238:241], v[8:11]
	v_mfma_f32_16x16x32_bf16 v[0:3], v[202:205], v[238:241], v[0:3]
	s_setprio 0
	s_barrier
	s_add_i32 s31, s31, 2
	v_lshl_add_u64 v[162:163], v[162:163], 0, s[22:23]
	s_cmp_gt_u32 s31, 13
	v_lshl_add_u64 v[164:165], v[164:165], 0, s[22:23]
	s_cbranch_scc1 .LBB0_623

.LBB0_625:
	v_lshl_add_u32 v156, s55, 12, v168
	ds_read_b128 v[158:161], v156
	v_pk_mul_f32 v[120:121], v[124:125], v[120:121]
	v_pk_mul_f32 v[122:123], v[126:127], v[122:123]
	v_pk_mul_f32 v[112:113], v[116:117], v[112:113]
	v_pk_mul_f32 v[114:115], v[118:119], v[114:115]
	s_waitcnt lgkmcnt(0)
	v_mov_b32_e32 v162, v159
	v_mov_b32_e32 v163, v160
	v_mov_b32_e32 v159, v161
	v_pk_add_f32 v[158:159], v[162:163], v[158:159]
	v_pk_mul_f32 v[104:105], v[108:109], v[104:105]
	v_add_f32_e32 v157, v158, v159
	v_fmamk_f32 v157, v157, 0x3a800000, v171
	v_mul_f32_e32 v158, 0x4b800000, v157
	v_cmp_gt_f32_e32 vcc, s52, v157
	v_pk_mul_f32 v[106:107], v[110:111], v[106:107]
	v_pk_mul_f32 v[96:97], v[100:101], v[96:97]
	v_cndmask_b32_e32 v157, v157, v158, vcc
	v_rsq_f32_e32 v157, v157
	v_pk_mul_f32 v[98:99], v[102:103], v[98:99]
	v_pk_mul_f32 v[88:89], v[92:93], v[88:89]
	v_pk_mul_f32 v[90:91], v[94:95], v[90:91]
	v_mul_f32_e32 v158, 0x45800000, v157
	v_cndmask_b32_e32 v157, v157, v158, vcc
	v_mul_f32_e32 v158, 0xbfb8aa3b, v157
	v_pk_mul_f32 v[124:125], v[124:125], v[158:159] op_sel_hi:[1,0]
	v_pk_mul_f32 v[126:127], v[126:127], v[158:159] op_sel_hi:[1,0]
	v_exp_f32_e32 v124, v124
	v_exp_f32_e32 v125, v125
	v_exp_f32_e32 v126, v126
	v_exp_f32_e32 v127, v127
	v_mul_f32_e32 v160, v157, v157
	v_pk_add_f32 v[124:125], v[124:125], 1.0 op_sel_hi:[1,0]
	v_pk_mul_f32 v[120:121], v[120:121], v[160:161] op_sel_hi:[1,0]
	v_rcp_f32_e32 v124, v124
	v_rcp_f32_e32 v125, v125
	v_pk_add_f32 v[126:127], v[126:127], 1.0 op_sel_hi:[1,0]
	v_pk_mul_f32 v[122:123], v[122:123], v[160:161] op_sel_hi:[1,0]
	v_pk_mul_f32 v[112:113], v[112:113], v[160:161] op_sel_hi:[1,0]
	v_pk_mul_f32 v[120:121], v[120:121], v[124:125]
	v_rcp_f32_e32 v124, v126
	v_rcp_f32_e32 v125, v127
	v_pk_mul_f32 v[126:127], v[116:117], v[158:159] op_sel_hi:[1,0]
	v_cvt_pk_bf16_f32 v120, v120, v121
	v_pk_mul_f32 v[80:81], v[84:85], v[80:81]
	v_exp_f32_e32 v126, v126
	v_exp_f32_e32 v127, v127
	v_pk_mul_f32 v[122:123], v[122:123], v[124:125]
	v_pk_mul_f32 v[124:125], v[118:119], v[158:159] op_sel_hi:[1,0]
	v_cvt_pk_bf16_f32 v121, v122, v123
	v_pk_add_f32 v[122:123], v[126:127], 1.0 op_sel_hi:[1,0]
	v_exp_f32_e32 v124, v124
	v_exp_f32_e32 v125, v125
	v_rcp_f32_e32 v122, v122
	v_rcp_f32_e32 v123, v123
	v_pk_mul_f32 v[82:83], v[86:87], v[82:83]
	v_pk_add_f32 v[116:117], v[124:125], 1.0 op_sel_hi:[1,0]
	v_pk_mul_f32 v[72:73], v[76:77], v[72:73]
	v_rcp_f32_e32 v116, v116
	v_rcp_f32_e32 v117, v117
	v_pk_mul_f32 v[112:113], v[112:113], v[122:123]
	v_pk_mul_f32 v[74:75], v[78:79], v[74:75]
	v_cvt_pk_bf16_f32 v122, v112, v113
	v_pk_mul_f32 v[112:113], v[114:115], v[160:161] op_sel_hi:[1,0]
	v_lshl_add_u32 v114, s34, 8, v166
	v_pk_mul_f32 v[112:113], v[112:113], v[116:117]
	v_pk_mul_f32 v[64:65], v[68:69], v[64:65]
	v_cvt_pk_bf16_f32 v123, v112, v113
	ds_read_b128 v[116:119], v156 offset:256
	v_lshl_or_b32 v112, s36, 7, v169
	v_ashrrev_i32_e32 v113, 31, v112
	v_lshlrev_b64 v[112:113], 1, v[112:113]
	v_pk_mul_f32 v[66:67], v[70:71], v[66:67]
	s_waitcnt lgkmcnt(0)
	v_mov_b32_e32 v124, v117
	v_mov_b32_e32 v125, v118
	v_mov_b32_e32 v117, v119
	v_pk_add_f32 v[116:117], v[124:125], v[116:117]
	v_pk_mul_f32 v[56:57], v[60:61], v[56:57]
	v_add_f32_e32 v115, v116, v117
	v_fmamk_f32 v115, v115, 0x3a800000, v171
	v_mul_f32_e32 v116, 0x4b800000, v115
	v_cmp_gt_f32_e32 vcc, s52, v115
	v_pk_mul_f32 v[58:59], v[62:63], v[58:59]
	v_pk_mul_f32 v[48:49], v[52:53], v[48:49]
	v_cndmask_b32_e32 v115, v115, v116, vcc
	v_rsq_f32_e32 v115, v115
	v_mad_i64_i32 v[116:117], s[10:11], v114, s51, v[142:143]
	v_lshl_add_u64 v[116:117], v[116:117], 0, v[112:113]
	v_mul_f32_e32 v118, 0x45800000, v115
	v_cndmask_b32_e32 v115, v115, v118, vcc
	v_mul_f32_e32 v118, 0xbfb8aa3b, v115
	v_pk_mul_f32 v[124:125], v[108:109], v[118:119] op_sel_hi:[1,0]
	v_pk_mul_f32 v[108:109], v[110:111], v[118:119] op_sel_hi:[1,0]
	v_exp_f32_e32 v124, v124
	v_exp_f32_e32 v108, v108
	v_exp_f32_e32 v109, v109
	v_exp_f32_e32 v125, v125
	global_store_dwordx4 v[116:117], v[120:123], off
	v_mul_f32_e32 v116, v115, v115
	v_pk_add_f32 v[108:109], v[108:109], 1.0 op_sel_hi:[1,0]
	v_pk_add_f32 v[120:121], v[124:125], 1.0 op_sel_hi:[1,0]
	v_rcp_f32_e32 v108, v108
	v_rcp_f32_e32 v109, v109
	v_rcp_f32_e32 v120, v120
	v_rcp_f32_e32 v121, v121
	v_pk_mul_f32 v[110:111], v[100:101], v[118:119] op_sel_hi:[1,0]
	v_pk_mul_f32 v[106:107], v[106:107], v[116:117] op_sel_hi:[1,0]
	v_exp_f32_e32 v110, v110
	v_exp_f32_e32 v111, v111
	v_pk_mul_f32 v[106:107], v[106:107], v[108:109]
	v_pk_mul_f32 v[108:109], v[102:103], v[118:119] op_sel_hi:[1,0]
	v_pk_mul_f32 v[104:105], v[104:105], v[116:117] op_sel_hi:[1,0]
	v_exp_f32_e32 v108, v108
	v_exp_f32_e32 v109, v109
	v_pk_mul_f32 v[104:105], v[104:105], v[120:121]
	v_pk_mul_f32 v[96:97], v[96:97], v[116:117] op_sel_hi:[1,0]
	v_cvt_pk_bf16_f32 v104, v104, v105
	v_cvt_pk_bf16_f32 v105, v106, v107
	v_pk_add_f32 v[106:107], v[110:111], 1.0 op_sel_hi:[1,0]
	v_pk_add_f32 v[100:101], v[108:109], 1.0 op_sel_hi:[1,0]
	v_rcp_f32_e32 v106, v106
	v_rcp_f32_e32 v107, v107
	v_rcp_f32_e32 v100, v100
	v_rcp_f32_e32 v101, v101
	v_pk_mul_f32 v[50:51], v[54:55], v[50:51]
	v_pk_mul_f32 v[96:97], v[96:97], v[106:107]
	v_pk_mul_f32 v[40:41], v[44:45], v[40:41]
	v_cvt_pk_bf16_f32 v106, v96, v97
	v_pk_mul_f32 v[96:97], v[98:99], v[116:117] op_sel_hi:[1,0]
	v_pk_mul_f32 v[42:43], v[46:47], v[42:43]
	v_pk_mul_f32 v[96:97], v[96:97], v[100:101]
	v_pk_mul_f32 v[32:33], v[36:37], v[32:33]
	v_cvt_pk_bf16_f32 v107, v96, v97
	ds_read_b128 v[96:99], v156 offset:512
	v_pk_mul_f32 v[34:35], v[38:39], v[34:35]
	v_pk_mul_f32 v[24:25], v[28:29], v[24:25]
	v_pk_mul_f32 v[26:27], v[30:31], v[26:27]
	v_pk_mul_f32 v[16:17], v[20:21], v[16:17]
	s_waitcnt lgkmcnt(0)
	v_mov_b32_e32 v100, v97
	v_mov_b32_e32 v101, v98
	v_mov_b32_e32 v97, v99
	v_pk_add_f32 v[96:97], v[100:101], v[96:97]
	v_pk_mul_f32 v[18:19], v[22:23], v[18:19]
	v_add_f32_e32 v96, v96, v97
	v_fmamk_f32 v96, v96, 0x3a800000, v171
	v_mul_f32_e32 v97, 0x4b800000, v96
	v_cmp_gt_f32_e32 vcc, s52, v96
	v_pk_mul_f32 v[8:9], v[12:13], v[8:9]
	v_pk_mul_f32 v[10:11], v[14:15], v[10:11]
	v_cndmask_b32_e32 v96, v96, v97, vcc
	v_rsq_f32_e32 v98, v96
	v_or_b32_e32 v96, 16, v114
	v_mad_i64_i32 v[96:97], s[10:11], v96, s51, v[142:143]
	v_mul_f32_e32 v99, 0x45800000, v98
	v_cndmask_b32_e32 v99, v98, v99, vcc
	v_mul_f32_e32 v98, 0xbfb8aa3b, v99
	v_pk_mul_f32 v[100:101], v[92:93], v[98:99] op_sel_hi:[1,0]
	v_pk_mul_f32 v[92:93], v[94:95], v[98:99] op_sel_hi:[1,0]
	v_exp_f32_e32 v100, v100
	v_exp_f32_e32 v92, v92
	v_exp_f32_e32 v93, v93
	v_exp_f32_e32 v101, v101
	v_lshl_add_u64 v[96:97], v[96:97], 0, v[112:113]
	global_store_dwordx4 v[96:97], v[104:107], off
	v_pk_add_f32 v[92:93], v[92:93], 1.0 op_sel_hi:[1,0]
	v_pk_add_f32 v[100:101], v[100:101], 1.0 op_sel_hi:[1,0]
	v_rcp_f32_e32 v92, v92
	v_rcp_f32_e32 v93, v93
	v_mul_f32_e32 v96, v99, v99
	v_rcp_f32_e32 v100, v100
	v_rcp_f32_e32 v101, v101
	v_pk_mul_f32 v[94:95], v[84:85], v[98:99] op_sel_hi:[1,0]
	v_pk_mul_f32 v[90:91], v[90:91], v[96:97] op_sel_hi:[1,0]
	v_exp_f32_e32 v94, v94
	v_exp_f32_e32 v95, v95
	v_pk_mul_f32 v[90:91], v[90:91], v[92:93]
	v_pk_mul_f32 v[92:93], v[86:87], v[98:99] op_sel_hi:[1,0]
	v_pk_mul_f32 v[88:89], v[88:89], v[96:97] op_sel_hi:[1,0]
	v_exp_f32_e32 v92, v92
	v_exp_f32_e32 v93, v93
	v_pk_mul_f32 v[88:89], v[88:89], v[100:101]
	v_pk_mul_f32 v[80:81], v[80:81], v[96:97] op_sel_hi:[1,0]
	v_cvt_pk_bf16_f32 v88, v88, v89
	v_cvt_pk_bf16_f32 v89, v90, v91
	v_pk_add_f32 v[90:91], v[94:95], 1.0 op_sel_hi:[1,0]
	v_pk_add_f32 v[84:85], v[92:93], 1.0 op_sel_hi:[1,0]
	v_rcp_f32_e32 v90, v90
	v_rcp_f32_e32 v91, v91
	v_rcp_f32_e32 v84, v84
	v_rcp_f32_e32 v85, v85
	v_pk_mul_f32 v[0:1], v[4:5], v[0:1]
	v_pk_mul_f32 v[80:81], v[80:81], v[90:91]
	v_pk_mul_f32 v[2:3], v[6:7], v[2:3]
	v_cvt_pk_bf16_f32 v90, v80, v81
	v_pk_mul_f32 v[80:81], v[82:83], v[96:97] op_sel_hi:[1,0]
	s_nop 0
	v_pk_mul_f32 v[80:81], v[80:81], v[84:85]
	s_nop 0
	v_cvt_pk_bf16_f32 v91, v80, v81
	ds_read_b128 v[80:83], v156 offset:768
	s_waitcnt lgkmcnt(0)
	v_mov_b32_e32 v84, v81
	v_mov_b32_e32 v85, v82
	v_mov_b32_e32 v81, v83
	v_pk_add_f32 v[80:81], v[84:85], v[80:81]
	s_nop 0
	v_add_f32_e32 v80, v80, v81
	v_fmamk_f32 v80, v80, 0x3a800000, v171
	v_mul_f32_e32 v81, 0x4b800000, v80
	v_cmp_gt_f32_e32 vcc, s52, v80
	s_nop 1
	v_cndmask_b32_e32 v80, v80, v81, vcc
	v_rsq_f32_e32 v82, v80
	v_or_b32_e32 v80, 32, v114
	v_mad_i64_i32 v[80:81], s[10:11], v80, s51, v[142:143]
	v_mul_f32_e32 v83, 0x45800000, v82
	v_cndmask_b32_e32 v83, v82, v83, vcc
	v_mul_f32_e32 v82, 0xbfb8aa3b, v83
	v_pk_mul_f32 v[84:85], v[76:77], v[82:83] op_sel_hi:[1,0]
	v_pk_mul_f32 v[76:77], v[78:79], v[82:83] op_sel_hi:[1,0]
	v_exp_f32_e32 v84, v84
	v_exp_f32_e32 v76, v76
	v_exp_f32_e32 v77, v77
	v_exp_f32_e32 v85, v85
	v_lshl_add_u64 v[80:81], v[80:81], 0, v[112:113]
	global_store_dwordx4 v[80:81], v[88:91], off
	v_pk_add_f32 v[76:77], v[76:77], 1.0 op_sel_hi:[1,0]
	v_pk_add_f32 v[84:85], v[84:85], 1.0 op_sel_hi:[1,0]
	v_rcp_f32_e32 v76, v76
	v_rcp_f32_e32 v77, v77
	v_mul_f32_e32 v80, v83, v83
	v_rcp_f32_e32 v84, v84
	v_rcp_f32_e32 v85, v85
	v_pk_mul_f32 v[78:79], v[68:69], v[82:83] op_sel_hi:[1,0]
	v_pk_mul_f32 v[74:75], v[74:75], v[80:81] op_sel_hi:[1,0]
	v_exp_f32_e32 v78, v78
	v_exp_f32_e32 v79, v79
	v_pk_mul_f32 v[74:75], v[74:75], v[76:77]
	v_pk_mul_f32 v[76:77], v[70:71], v[82:83] op_sel_hi:[1,0]
	v_pk_mul_f32 v[72:73], v[72:73], v[80:81] op_sel_hi:[1,0]
	v_exp_f32_e32 v76, v76
	v_exp_f32_e32 v77, v77
	v_pk_mul_f32 v[72:73], v[72:73], v[84:85]
	v_pk_mul_f32 v[64:65], v[64:65], v[80:81] op_sel_hi:[1,0]
	v_cvt_pk_bf16_f32 v72, v72, v73
	v_cvt_pk_bf16_f32 v73, v74, v75
	v_pk_add_f32 v[74:75], v[78:79], 1.0 op_sel_hi:[1,0]
	v_pk_add_f32 v[68:69], v[76:77], 1.0 op_sel_hi:[1,0]
	v_rcp_f32_e32 v74, v74
	v_rcp_f32_e32 v75, v75
	v_rcp_f32_e32 v68, v68
	v_rcp_f32_e32 v69, v69
	v_pk_mul_f32 v[64:65], v[64:65], v[74:75]
	s_nop 0
	v_cvt_pk_bf16_f32 v74, v64, v65
	v_pk_mul_f32 v[64:65], v[66:67], v[80:81] op_sel_hi:[1,0]
	s_nop 0
	v_pk_mul_f32 v[64:65], v[64:65], v[68:69]
	s_nop 0
	v_cvt_pk_bf16_f32 v75, v64, v65
	ds_read_b128 v[64:67], v156 offset:2048
	s_waitcnt lgkmcnt(0)
	v_mov_b32_e32 v68, v65
	v_mov_b32_e32 v69, v66
	v_mov_b32_e32 v65, v67
	v_pk_add_f32 v[64:65], v[68:69], v[64:65]
	s_nop 0
	v_add_f32_e32 v64, v64, v65
	v_fmamk_f32 v64, v64, 0x3a800000, v171
	v_mul_f32_e32 v65, 0x4b800000, v64
	v_cmp_gt_f32_e32 vcc, s52, v64
	s_nop 1
	v_cndmask_b32_e32 v64, v64, v65, vcc
	v_rsq_f32_e32 v66, v64
	v_or_b32_e32 v64, 48, v114
	v_mad_i64_i32 v[64:65], s[10:11], v64, s51, v[142:143]
	v_mul_f32_e32 v67, 0x45800000, v66
	v_cndmask_b32_e32 v67, v66, v67, vcc
	v_mul_f32_e32 v66, 0xbfb8aa3b, v67
	v_pk_mul_f32 v[68:69], v[60:61], v[66:67] op_sel_hi:[1,0]
	v_pk_mul_f32 v[60:61], v[62:63], v[66:67] op_sel_hi:[1,0]
	v_exp_f32_e32 v68, v68
	v_exp_f32_e32 v60, v60
	v_exp_f32_e32 v61, v61
	v_exp_f32_e32 v69, v69
	v_lshl_add_u64 v[64:65], v[64:65], 0, v[112:113]
	global_store_dwordx4 v[64:65], v[72:75], off
	v_pk_add_f32 v[60:61], v[60:61], 1.0 op_sel_hi:[1,0]
	v_pk_add_f32 v[68:69], v[68:69], 1.0 op_sel_hi:[1,0]
	v_rcp_f32_e32 v60, v60
	v_rcp_f32_e32 v61, v61
	v_mul_f32_e32 v64, v67, v67
	v_rcp_f32_e32 v68, v68
	v_rcp_f32_e32 v69, v69
	v_pk_mul_f32 v[62:63], v[52:53], v[66:67] op_sel_hi:[1,0]
	v_pk_mul_f32 v[58:59], v[58:59], v[64:65] op_sel_hi:[1,0]
	v_exp_f32_e32 v62, v62
	v_exp_f32_e32 v63, v63
	v_pk_mul_f32 v[58:59], v[58:59], v[60:61]
	v_pk_mul_f32 v[60:61], v[54:55], v[66:67] op_sel_hi:[1,0]
	v_pk_mul_f32 v[56:57], v[56:57], v[64:65] op_sel_hi:[1,0]
	v_exp_f32_e32 v60, v60
	v_exp_f32_e32 v61, v61
	v_pk_mul_f32 v[56:57], v[56:57], v[68:69]
	v_pk_mul_f32 v[48:49], v[48:49], v[64:65] op_sel_hi:[1,0]
	v_cvt_pk_bf16_f32 v56, v56, v57
	v_cvt_pk_bf16_f32 v57, v58, v59
	v_pk_add_f32 v[58:59], v[62:63], 1.0 op_sel_hi:[1,0]
	v_pk_add_f32 v[52:53], v[60:61], 1.0 op_sel_hi:[1,0]
	v_rcp_f32_e32 v58, v58
	v_rcp_f32_e32 v59, v59
	v_rcp_f32_e32 v52, v52
	v_rcp_f32_e32 v53, v53
	v_pk_mul_f32 v[48:49], v[48:49], v[58:59]
	s_nop 0
	v_cvt_pk_bf16_f32 v58, v48, v49
	v_pk_mul_f32 v[48:49], v[50:51], v[64:65] op_sel_hi:[1,0]
	s_nop 0
	v_pk_mul_f32 v[48:49], v[48:49], v[52:53]
	s_nop 0
	v_cvt_pk_bf16_f32 v59, v48, v49
	ds_read_b128 v[48:51], v156 offset:2304
	s_waitcnt lgkmcnt(0)
	v_mov_b32_e32 v52, v49
	v_mov_b32_e32 v53, v50
	v_mov_b32_e32 v49, v51
	v_pk_add_f32 v[48:49], v[52:53], v[48:49]
	s_nop 0
	v_add_f32_e32 v48, v48, v49
	v_fmamk_f32 v48, v48, 0x3a800000, v171
	v_mul_f32_e32 v49, 0x4b800000, v48
	v_cmp_gt_f32_e32 vcc, s52, v48
	s_nop 1
	v_cndmask_b32_e32 v48, v48, v49, vcc
	v_rsq_f32_e32 v50, v48
	v_add_u32_e32 v48, 0x80, v114
	v_mad_i64_i32 v[48:49], s[10:11], v48, s51, v[142:143]
	v_mul_f32_e32 v51, 0x45800000, v50
	v_cndmask_b32_e32 v51, v50, v51, vcc
	v_mul_f32_e32 v50, 0xbfb8aa3b, v51
	v_pk_mul_f32 v[52:53], v[44:45], v[50:51] op_sel_hi:[1,0]
	v_pk_mul_f32 v[44:45], v[46:47], v[50:51] op_sel_hi:[1,0]
	v_exp_f32_e32 v52, v52
	v_exp_f32_e32 v44, v44
	v_exp_f32_e32 v45, v45
	v_exp_f32_e32 v53, v53
	v_lshl_add_u64 v[48:49], v[48:49], 0, v[112:113]
	global_store_dwordx4 v[48:49], v[56:59], off
	v_pk_add_f32 v[44:45], v[44:45], 1.0 op_sel_hi:[1,0]
	v_pk_add_f32 v[52:53], v[52:53], 1.0 op_sel_hi:[1,0]
	v_rcp_f32_e32 v44, v44
	v_rcp_f32_e32 v45, v45
	v_mul_f32_e32 v48, v51, v51
	v_rcp_f32_e32 v52, v52
	v_rcp_f32_e32 v53, v53
	v_pk_mul_f32 v[46:47], v[36:37], v[50:51] op_sel_hi:[1,0]
	v_pk_mul_f32 v[42:43], v[42:43], v[48:49] op_sel_hi:[1,0]
	v_exp_f32_e32 v46, v46
	v_exp_f32_e32 v47, v47
	v_pk_mul_f32 v[42:43], v[42:43], v[44:45]
	v_pk_mul_f32 v[44:45], v[38:39], v[50:51] op_sel_hi:[1,0]
	v_pk_mul_f32 v[40:41], v[40:41], v[48:49] op_sel_hi:[1,0]
	v_exp_f32_e32 v44, v44
	v_exp_f32_e32 v45, v45
	v_pk_mul_f32 v[40:41], v[40:41], v[52:53]
	v_pk_mul_f32 v[32:33], v[32:33], v[48:49] op_sel_hi:[1,0]
	v_cvt_pk_bf16_f32 v40, v40, v41
	v_cvt_pk_bf16_f32 v41, v42, v43
	v_pk_add_f32 v[42:43], v[46:47], 1.0 op_sel_hi:[1,0]
	v_pk_add_f32 v[36:37], v[44:45], 1.0 op_sel_hi:[1,0]
	v_rcp_f32_e32 v42, v42
	v_rcp_f32_e32 v43, v43
	v_rcp_f32_e32 v36, v36
	v_rcp_f32_e32 v37, v37
	v_pk_mul_f32 v[32:33], v[32:33], v[42:43]
	s_nop 0
	v_cvt_pk_bf16_f32 v42, v32, v33
	v_pk_mul_f32 v[32:33], v[34:35], v[48:49] op_sel_hi:[1,0]
	s_nop 0
	v_pk_mul_f32 v[32:33], v[32:33], v[36:37]
	s_nop 0
	v_cvt_pk_bf16_f32 v43, v32, v33
	ds_read_b128 v[32:35], v156 offset:2560
	s_waitcnt lgkmcnt(0)
	v_mov_b32_e32 v36, v33
	v_mov_b32_e32 v37, v34
	v_mov_b32_e32 v33, v35
	v_pk_add_f32 v[32:33], v[36:37], v[32:33]
	s_nop 0
	v_add_f32_e32 v32, v32, v33
	v_fmamk_f32 v32, v32, 0x3a800000, v171
	v_mul_f32_e32 v33, 0x4b800000, v32
	v_cmp_gt_f32_e32 vcc, s52, v32
	s_nop 1
	v_cndmask_b32_e32 v32, v32, v33, vcc
	v_rsq_f32_e32 v34, v32
	v_add_u32_e32 v32, 0x90, v114
	v_mad_i64_i32 v[32:33], s[10:11], v32, s51, v[142:143]
	v_mul_f32_e32 v35, 0x45800000, v34
	v_cndmask_b32_e32 v35, v34, v35, vcc
	v_mul_f32_e32 v34, 0xbfb8aa3b, v35
	v_pk_mul_f32 v[36:37], v[28:29], v[34:35] op_sel_hi:[1,0]
	v_pk_mul_f32 v[28:29], v[30:31], v[34:35] op_sel_hi:[1,0]
	v_exp_f32_e32 v36, v36
	v_exp_f32_e32 v28, v28
	v_exp_f32_e32 v29, v29
	v_exp_f32_e32 v37, v37
	v_lshl_add_u64 v[32:33], v[32:33], 0, v[112:113]
	global_store_dwordx4 v[32:33], v[40:43], off
	v_pk_add_f32 v[28:29], v[28:29], 1.0 op_sel_hi:[1,0]
	v_pk_add_f32 v[36:37], v[36:37], 1.0 op_sel_hi:[1,0]
	v_rcp_f32_e32 v28, v28
	v_rcp_f32_e32 v29, v29
	v_mul_f32_e32 v32, v35, v35
	v_rcp_f32_e32 v36, v36
	v_rcp_f32_e32 v37, v37
	v_pk_mul_f32 v[30:31], v[20:21], v[34:35] op_sel_hi:[1,0]
	v_pk_mul_f32 v[26:27], v[26:27], v[32:33] op_sel_hi:[1,0]
	v_exp_f32_e32 v30, v30
	v_exp_f32_e32 v31, v31
	v_pk_mul_f32 v[26:27], v[26:27], v[28:29]
	v_pk_mul_f32 v[28:29], v[22:23], v[34:35] op_sel_hi:[1,0]
	v_pk_mul_f32 v[24:25], v[24:25], v[32:33] op_sel_hi:[1,0]
	v_exp_f32_e32 v28, v28
	v_exp_f32_e32 v29, v29
	v_pk_mul_f32 v[24:25], v[24:25], v[36:37]
	v_pk_mul_f32 v[16:17], v[16:17], v[32:33] op_sel_hi:[1,0]
	v_cvt_pk_bf16_f32 v24, v24, v25
	v_cvt_pk_bf16_f32 v25, v26, v27
	v_pk_add_f32 v[26:27], v[30:31], 1.0 op_sel_hi:[1,0]
	v_pk_add_f32 v[20:21], v[28:29], 1.0 op_sel_hi:[1,0]
	v_rcp_f32_e32 v26, v26
	v_rcp_f32_e32 v27, v27
	v_rcp_f32_e32 v20, v20
	v_rcp_f32_e32 v21, v21
	v_pk_mul_f32 v[16:17], v[16:17], v[26:27]
	s_nop 0
	v_cvt_pk_bf16_f32 v26, v16, v17
	v_pk_mul_f32 v[16:17], v[18:19], v[32:33] op_sel_hi:[1,0]
	s_nop 0
	v_pk_mul_f32 v[16:17], v[16:17], v[20:21]
	v_add_u32_e32 v20, 0xa0, v114
	v_cvt_pk_bf16_f32 v27, v16, v17
	ds_read_b128 v[16:19], v156 offset:2816
	v_mad_i64_i32 v[20:21], s[10:11], v20, s51, v[142:143]
	s_waitcnt lgkmcnt(0)
	v_mov_b32_e32 v22, v17
	v_mov_b32_e32 v23, v18
	v_mov_b32_e32 v17, v19
	v_pk_add_f32 v[16:17], v[22:23], v[16:17]
	s_nop 0
	v_add_f32_e32 v16, v16, v17
	v_fmamk_f32 v16, v16, 0x3a800000, v171
	v_mul_f32_e32 v17, 0x4b800000, v16
	v_cmp_gt_f32_e32 vcc, s52, v16
	s_nop 1
	v_cndmask_b32_e32 v16, v16, v17, vcc
	v_rsq_f32_e32 v18, v16
	v_lshl_add_u64 v[16:17], v[20:21], 0, v[112:113]
	global_store_dwordx4 v[16:17], v[24:27], off
	v_add_u32_e32 v17, 0xb0, v114
	v_mul_f32_e32 v16, 0x45800000, v18
	v_cndmask_b32_e32 v22, v18, v16, vcc
	v_mul_f32_e32 v16, 0xbfb8aa3b, v22
	v_pk_mul_f32 v[18:19], v[12:13], v[16:17] op_sel_hi:[1,0]
	v_pk_mul_f32 v[12:13], v[14:15], v[16:17] op_sel_hi:[1,0]
	v_exp_f32_e32 v18, v18
	v_exp_f32_e32 v12, v12
	v_exp_f32_e32 v13, v13
	v_exp_f32_e32 v19, v19
	v_mul_f32_e32 v22, v22, v22
	v_pk_mul_f32 v[14:15], v[4:5], v[16:17] op_sel_hi:[1,0]
	v_pk_add_f32 v[12:13], v[12:13], 1.0 op_sel_hi:[1,0]
	v_pk_add_f32 v[18:19], v[18:19], 1.0 op_sel_hi:[1,0]
	v_rcp_f32_e32 v12, v12
	v_rcp_f32_e32 v13, v13
	v_rcp_f32_e32 v18, v18
	v_rcp_f32_e32 v19, v19
	v_exp_f32_e32 v14, v14
	v_exp_f32_e32 v15, v15
	v_pk_mul_f32 v[10:11], v[10:11], v[22:23] op_sel_hi:[1,0]
	v_pk_mul_f32 v[8:9], v[8:9], v[22:23] op_sel_hi:[1,0]
	v_pk_mul_f32 v[10:11], v[10:11], v[12:13]
	v_pk_mul_f32 v[12:13], v[6:7], v[16:17] op_sel_hi:[1,0]
	v_pk_mul_f32 v[8:9], v[8:9], v[18:19]
	v_exp_f32_e32 v12, v12
	v_exp_f32_e32 v13, v13
	v_cvt_pk_bf16_f32 v8, v8, v9
	v_cvt_pk_bf16_f32 v9, v10, v11
	v_pk_add_f32 v[10:11], v[14:15], 1.0 op_sel_hi:[1,0]
	v_pk_add_f32 v[4:5], v[12:13], 1.0 op_sel_hi:[1,0]
	v_rcp_f32_e32 v10, v10
	v_rcp_f32_e32 v11, v11
	v_rcp_f32_e32 v4, v4
	v_rcp_f32_e32 v5, v5
	v_pk_mul_f32 v[0:1], v[0:1], v[22:23] op_sel_hi:[1,0]
	v_mad_i64_i32 v[20:21], s[10:11], v17, s51, v[142:143]
	v_pk_mul_f32 v[0:1], v[0:1], v[10:11]
	s_andn2_b64 vcc, exec, s[8:9]
	v_cvt_pk_bf16_f32 v10, v0, v1
	v_pk_mul_f32 v[0:1], v[2:3], v[22:23] op_sel_hi:[1,0]
	s_mov_b64 s[8:9], -1
	v_pk_mul_f32 v[0:1], v[0:1], v[4:5]
	s_nop 0
	v_cvt_pk_bf16_f32 v11, v0, v1
	v_lshl_add_u64 v[0:1], v[20:21], 0, v[112:113]
	global_store_dwordx4 v[0:1], v[8:11], off
	s_mov_b32 s100, 1
	s_cbranch_vccnz .LBB0_615
	s_andn2_b64 vcc, exec, s[14:15]
	s_cbranch_vccnz .LBB0_614
	s_barrier
	s_branch .LBB0_614

.LBB0_989:
	s_mov_b64 s[16:17], 0x80
	s_add_i32 m0, s35, 0x18000
	v_lshl_add_u64 v[6:7], v[6:7], 0, s[16:17]
	s_waitcnt vmcnt(2)
	s_barrier
	global_load_lds_dwordx4 v[6:7], off
	v_lshl_add_u64 v[6:7], v[8:9], 0, s[16:17]
	s_add_i32 m0, s35, 0x1a000
	s_add_i32 s39, s35, 0x8000
	global_load_lds_dwordx4 v[6:7], off
	v_lshl_add_u64 v[6:7], v[10:11], 0, s[16:17]
	s_mov_b32 m0, s39
	s_add_i32 s40, s35, 0xa000
	global_load_lds_dwordx4 v[6:7], off
	v_lshl_add_u64 v[6:7], v[12:13], 0, s[16:17]
	s_mov_b32 m0, s40
	s_mov_b64 s[18:19], 0x40080
	global_load_lds_dwordx4 v[6:7], off
	v_lshl_add_u64 v[6:7], v[2:3], 0, s[18:19]
	s_add_i32 m0, s35, 0x1c000
	v_lshl_add_u64 v[8:9], v[6:7], 0, v[134:135]
	global_load_lds_dwordx4 v[8:9], off
	v_lshl_add_u64 v[6:7], v[6:7], 0, v[140:141]
	s_add_i32 m0, s35, 0x1e000
	s_and_b32 s20, s2, 7
	s_lshl_b32 s20, s20, 23
	s_add_u32 s20, s20, 0xd000000
	s_mov_b32 s21, 0
	global_load_lds_dwordx4 v[6:7], off
	v_lshl_add_u64 v[142:143], v[4:5], 0, s[20:21]
	v_lshrrev_b32_e32 v5, 1, v14
	v_and_b32_e32 v5, 24, v5
	v_and_b32_e32 v4, 15, v14
	v_lshlrev_b32_e32 v6, 1, v5
	v_lshl_or_b32 v166, s11, 6, v4
	v_lshl_or_b32 v4, v4, 6, v6
	v_lshlrev_b32_e32 v6, 2, v14
	s_sext_i32_i8 s52, s9
	s_lshl_b32 s9, s11, 13
	v_and_b32_e32 v6, 32, v6
	v_bitop3_b32 v7, v4, s9, v6 bitop3:0xde
	s_lshl_b32 s9, s10, 5
	s_and_b32 s9, s9, 0x60
	s_lshl_b32 s10, s9, 7
	v_bitop3_b32 v167, v4, s10, v6 bitop3:0xde
	v_lshlrev_b32_e32 v4, 14, v18
	v_and_b32_e32 v4, 0xffff8000, v4
	v_or_b32_e32 v169, s9, v5
	v_lshl_add_u32 v4, v19, 11, v4
	v_and_b32_e32 v5, 1, v18
	v_lshl_or_b32 v4, v5, 6, v4
	v_lshl_add_u32 v144, v20, 1, v4
	v_lshlrev_b32_e32 v4, 14, v15
	v_and_b32_e32 v4, 0xffff8000, v4
	s_waitcnt vmcnt(6)
	s_cmpk_lt_u32 s8, 0x100
	v_lshl_add_u32 v4, v16, 11, v4
	v_and_b32_e32 v5, 1, v15
	s_cselect_b64 s[20:21], -1, 0
	s_add_i32 s8, 0, 0x21c00
	v_lshl_or_b32 v4, v5, 6, v4
	s_mov_b32 s26, 0xfffc0080
	s_mov_b32 s53, 0
	v_lshl_add_u32 v168, v166, 4, s8
	v_mov_b32_e32 v145, v135
	v_lshl_add_u32 v146, v17, 1, v4
	v_mov_b32_e32 v147, v135
	v_mov_b64_e32 v[148:149], 0x380
	v_mov_b64_e32 v[150:151], 0x37f
	s_movk_i32 s41, 0x71
	s_mov_b64 s[22:23], 0x100
	s_mov_b32 s27, -1
	s_add_i32 s42, 0, 0x10000
	s_add_i32 s43, 0, 0x14000
	v_add_u32_e32 v170, 0, v7
	s_add_i32 s44, s35, 0xc000
	s_add_i32 s45, s35, 0xe000
	s_movk_i32 s48, 0xe00
	v_mov_b32_e32 v171, 0x358637bd
	s_mov_b32 s49, 0x800000
	s_mov_b32 s50, 0
	s_barrier
	s_mov_b32 s100, 0
	s_branch .LBB0_992

.LBB0_995:
	v_add_u32_e32 v186, s42, v167
	v_add_u32_e32 v202, s43, v167
	ds_read_b128 v[172:175], v186
	ds_read_b128 v[178:181], v186 offset:1024
	ds_read_b128 v[182:185], v186 offset:2048
	ds_read_b128 v[186:189], v186 offset:3072
	ds_read_b128 v[190:193], v202
	ds_read_b128 v[194:197], v202 offset:1024
	ds_read_b128 v[198:201], v202 offset:2048
	ds_read_b128 v[202:205], v202 offset:3072
	v_lshl_add_u64 v[206:207], v[164:165], 0, s[26:27]
	v_cndmask_b32_e64 v215, v207, v157, s[10:11]
	v_cndmask_b32_e64 v214, v206, v156, s[10:11]
	v_cndmask_b32_e64 v243, v163, v159, s[10:11]
	v_cndmask_b32_e64 v242, v162, v158, s[10:11]
	s_mov_b32 m0, s44
	v_lshl_add_u64 v[244:245], v[164:165], 0, v[146:147]
	ds_read_b128 v[206:209], v170
	ds_read_b128 v[210:213], v170 offset:1024
	ds_read_b128 v[218:221], v170 offset:2048
	ds_read_b128 v[222:225], v170 offset:3072
	ds_read_b128 v[226:229], v170 offset:4096
	ds_read_b128 v[230:233], v170 offset:5120
	ds_read_b128 v[234:237], v170 offset:6144
	ds_read_b128 v[238:241], v170 offset:7168
	global_load_lds_dwordx4 v[244:245], off
	v_lshl_add_u64 v[244:245], v[164:165], 0, v[144:145]
	s_mov_b32 m0, s45
	s_nop 0
	global_load_lds_dwordx4 v[244:245], off
	s_cmp_eq_u32 s100, 0
	s_cbranch_scc1 .Lgw8_30123_0
	s_waitcnt vmcnt(24)
	s_branch .Lgwd_30123_0

.Lgwd_30123_0:
	s_waitcnt lgkmcnt(0)
	s_barrier
	s_setprio 1
	s_waitcnt lgkmcnt(0)
	v_mfma_f32_16x16x32_bf16 v[124:127], v[172:175], v[206:209], v[124:127]
	v_mfma_f32_16x16x32_bf16 v[120:123], v[182:185], v[206:209], v[120:123]
	v_mfma_f32_16x16x32_bf16 v[108:111], v[172:175], v[218:221], v[108:111]
	v_mfma_f32_16x16x32_bf16 v[104:107], v[182:185], v[218:221], v[104:107]
	v_mfma_f32_16x16x32_bf16 v[92:95], v[172:175], v[226:229], v[92:95]
	v_mfma_f32_16x16x32_bf16 v[88:91], v[182:185], v[226:229], v[88:91]
	v_mfma_f32_16x16x32_bf16 v[76:79], v[172:175], v[234:237], v[76:79]
	v_mfma_f32_16x16x32_bf16 v[72:75], v[182:185], v[234:237], v[72:75]
	v_mfma_f32_16x16x32_bf16 v[124:127], v[178:181], v[210:213], v[124:127]
	v_mfma_f32_16x16x32_bf16 v[120:123], v[186:189], v[210:213], v[120:123]
	v_mfma_f32_16x16x32_bf16 v[108:111], v[178:181], v[222:225], v[108:111]
	v_mfma_f32_16x16x32_bf16 v[104:107], v[186:189], v[222:225], v[104:107]
	v_mfma_f32_16x16x32_bf16 v[92:95], v[178:181], v[230:233], v[92:95]
	v_mfma_f32_16x16x32_bf16 v[88:91], v[186:189], v[230:233], v[88:91]
	v_mfma_f32_16x16x32_bf16 v[76:79], v[178:181], v[238:241], v[76:79]
	v_mfma_f32_16x16x32_bf16 v[72:75], v[186:189], v[238:241], v[72:75]
	s_setprio 0
	s_setprio 1
	v_mfma_f32_16x16x32_bf16 v[116:119], v[190:193], v[206:209], v[116:119]
	v_mfma_f32_16x16x32_bf16 v[112:115], v[198:201], v[206:209], v[112:115]
	v_mfma_f32_16x16x32_bf16 v[100:103], v[190:193], v[218:221], v[100:103]
	v_mfma_f32_16x16x32_bf16 v[96:99], v[198:201], v[218:221], v[96:99]
	v_mfma_f32_16x16x32_bf16 v[84:87], v[190:193], v[226:229], v[84:87]
	v_mfma_f32_16x16x32_bf16 v[80:83], v[198:201], v[226:229], v[80:83]
	v_mfma_f32_16x16x32_bf16 v[68:71], v[190:193], v[234:237], v[68:71]
	v_mfma_f32_16x16x32_bf16 v[64:67], v[198:201], v[234:237], v[64:67]
	v_mfma_f32_16x16x32_bf16 v[116:119], v[194:197], v[210:213], v[116:119]
	v_mfma_f32_16x16x32_bf16 v[112:115], v[202:205], v[210:213], v[112:115]
	v_mfma_f32_16x16x32_bf16 v[100:103], v[194:197], v[222:225], v[100:103]
	v_mfma_f32_16x16x32_bf16 v[96:99], v[202:205], v[222:225], v[96:99]
	v_mfma_f32_16x16x32_bf16 v[84:87], v[194:197], v[230:233], v[84:87]
	v_mfma_f32_16x16x32_bf16 v[80:83], v[202:205], v[230:233], v[80:83]
	v_mfma_f32_16x16x32_bf16 v[68:71], v[194:197], v[238:241], v[68:71]
	v_mfma_f32_16x16x32_bf16 v[64:67], v[202:205], v[238:241], v[64:67]
	s_setprio 0
	s_barrier
	s_add_i32 s10, s42, s3
	v_lshl_add_u64 v[244:245], v[242:243], 0, v[134:135]
	s_mov_b32 m0, s10
	ds_read_b128 v[206:209], v170 offset:16384
	ds_read_b128 v[210:213], v170 offset:17408
	ds_read_b128 v[218:221], v170 offset:18432
	ds_read_b128 v[222:225], v170 offset:19456
	ds_read_b128 v[226:229], v170 offset:20480
	ds_read_b128 v[230:233], v170 offset:21504
	ds_read_b128 v[234:237], v170 offset:22528
	ds_read_b128 v[238:241], v170 offset:23552
	global_load_lds_dwordx4 v[244:245], off
	v_lshl_add_u64 v[246:247], v[242:243], 0, v[140:141]
	s_add_i32 m0, s10, 0x2000
	v_lshl_add_u64 v[248:249], v[242:243], 0, s[12:13]
	s_add_i32 s10, s43, s3
	global_load_lds_dwordx4 v[246:247], off
	v_lshl_add_u64 v[250:251], v[248:249], 0, v[134:135]
	s_mov_b32 m0, s10
	v_lshl_add_u64 v[248:249], v[248:249], 0, v[140:141]
	global_load_lds_dwordx4 v[250:251], off
	s_add_i32 m0, s10, 0x2000
	v_lshl_add_u64 v[250:251], v[214:215], 0, v[138:139]
	global_load_lds_dwordx4 v[248:249], off
	v_lshl_add_u64 v[248:249], v[214:215], 0, v[136:137]
	s_mov_b32 m0, s35
	s_nop 0
	global_load_lds_dwordx4 v[248:249], off
	s_mov_b32 m0, s36
	s_nop 0
	global_load_lds_dwordx4 v[250:251], off
	s_cmp_eq_u32 s100, 0
	s_cbranch_scc1 .Lgw8_30123_1
	s_waitcnt vmcnt(24)
	s_mov_b32 s100, 0
	s_branch .Lgwd_30123_1

.Lgwd_30123_1:
	s_waitcnt lgkmcnt(0)
	s_barrier
	s_setprio 1
	s_waitcnt lgkmcnt(0)
	v_mfma_f32_16x16x32_bf16 v[60:63], v[172:175], v[206:209], v[60:63]
	v_mfma_f32_16x16x32_bf16 v[56:59], v[182:185], v[206:209], v[56:59]
	v_mfma_f32_16x16x32_bf16 v[44:47], v[172:175], v[218:221], v[44:47]
	v_mfma_f32_16x16x32_bf16 v[40:43], v[182:185], v[218:221], v[40:43]
	v_mfma_f32_16x16x32_bf16 v[28:31], v[172:175], v[226:229], v[28:31]
	v_mfma_f32_16x16x32_bf16 v[24:27], v[182:185], v[226:229], v[24:27]
	v_mfma_f32_16x16x32_bf16 v[12:15], v[172:175], v[234:237], v[12:15]
	v_mfma_f32_16x16x32_bf16 v[8:11], v[182:185], v[234:237], v[8:11]
	v_mfma_f32_16x16x32_bf16 v[60:63], v[178:181], v[210:213], v[60:63]
	v_mfma_f32_16x16x32_bf16 v[56:59], v[186:189], v[210:213], v[56:59]
	v_mfma_f32_16x16x32_bf16 v[44:47], v[178:181], v[222:225], v[44:47]
	v_mfma_f32_16x16x32_bf16 v[40:43], v[186:189], v[222:225], v[40:43]
	v_mfma_f32_16x16x32_bf16 v[28:31], v[178:181], v[230:233], v[28:31]
	v_mfma_f32_16x16x32_bf16 v[24:27], v[186:189], v[230:233], v[24:27]
	v_mfma_f32_16x16x32_bf16 v[12:15], v[178:181], v[238:241], v[12:15]
	v_mfma_f32_16x16x32_bf16 v[8:11], v[186:189], v[238:241], v[8:11]
	s_setprio 0
	s_setprio 1
	v_mfma_f32_16x16x32_bf16 v[52:55], v[190:193], v[206:209], v[52:55]
	v_mfma_f32_16x16x32_bf16 v[48:51], v[198:201], v[206:209], v[48:51]
	v_mfma_f32_16x16x32_bf16 v[36:39], v[190:193], v[218:221], v[36:39]
	v_mfma_f32_16x16x32_bf16 v[32:35], v[198:201], v[218:221], v[32:35]
	v_mfma_f32_16x16x32_bf16 v[20:23], v[190:193], v[226:229], v[20:23]
	v_mfma_f32_16x16x32_bf16 v[16:19], v[198:201], v[226:229], v[16:19]
	v_mfma_f32_16x16x32_bf16 v[4:7], v[190:193], v[234:237], v[4:7]
	v_mfma_f32_16x16x32_bf16 v[0:3], v[198:201], v[234:237], v[0:3]
	v_mfma_f32_16x16x32_bf16 v[52:55], v[194:197], v[210:213], v[52:55]
	v_mfma_f32_16x16x32_bf16 v[48:51], v[202:205], v[210:213], v[48:51]
	v_mfma_f32_16x16x32_bf16 v[36:39], v[194:197], v[222:225], v[36:39]
	v_mfma_f32_16x16x32_bf16 v[32:35], v[202:205], v[222:225], v[32:35]
	v_mfma_f32_16x16x32_bf16 v[20:23], v[194:197], v[230:233], v[20:23]
	v_mfma_f32_16x16x32_bf16 v[16:19], v[202:205], v[230:233], v[16:19]
	v_mfma_f32_16x16x32_bf16 v[4:7], v[194:197], v[238:241], v[4:7]
	v_mfma_f32_16x16x32_bf16 v[0:3], v[202:205], v[238:241], v[0:3]
	s_setprio 0
	s_barrier
	s_add_i32 s10, 0, 0x18000
	s_add_i32 s11, 0, 0x1c000
	v_add_u32_e32 v186, s10, v167
	v_add_u32_e32 v202, s11, v167
	ds_read_b128 v[172:175], v186
	ds_read_b128 v[178:181], v186 offset:1024
	ds_read_b128 v[182:185], v186 offset:2048
	ds_read_b128 v[186:189], v186 offset:3072
	ds_read_b128 v[190:193], v202
	ds_read_b128 v[194:197], v202 offset:1024
	ds_read_b128 v[198:201], v202 offset:2048
	ds_read_b128 v[202:205], v202 offset:3072
	v_lshl_add_u64 v[214:215], v[214:215], 0, s[12:13]
	s_mov_b32 m0, s37
	v_lshl_add_u64 v[252:253], v[214:215], 0, v[136:137]
	ds_read_b128 v[206:209], v170 offset:32768
	ds_read_b128 v[210:213], v170 offset:33792
	ds_read_b128 v[218:221], v170 offset:34816
	ds_read_b128 v[222:225], v170 offset:35840
	ds_read_b128 v[226:229], v170 offset:36864
	ds_read_b128 v[230:233], v170 offset:37888
	ds_read_b128 v[234:237], v170 offset:38912
	ds_read_b128 v[238:241], v170 offset:39936
	global_load_lds_dwordx4 v[252:253], off
	v_lshl_add_u64 v[214:215], v[214:215], 0, v[138:139]
	s_mov_b32 m0, s38
	s_nop 0
	global_load_lds_dwordx4 v[214:215], off
	s_waitcnt vmcnt(8)
	s_waitcnt lgkmcnt(0)
	s_barrier
	s_setprio 1
	s_waitcnt lgkmcnt(0)
	v_mfma_f32_16x16x32_bf16 v[124:127], v[172:175], v[206:209], v[124:127]
	v_mfma_f32_16x16x32_bf16 v[120:123], v[182:185], v[206:209], v[120:123]
	v_mfma_f32_16x16x32_bf16 v[108:111], v[172:175], v[218:221], v[108:111]
	v_mfma_f32_16x16x32_bf16 v[104:107], v[182:185], v[218:221], v[104:107]
	v_mfma_f32_16x16x32_bf16 v[92:95], v[172:175], v[226:229], v[92:95]
	v_mfma_f32_16x16x32_bf16 v[88:91], v[182:185], v[226:229], v[88:91]
	v_mfma_f32_16x16x32_bf16 v[76:79], v[172:175], v[234:237], v[76:79]
	v_mfma_f32_16x16x32_bf16 v[72:75], v[182:185], v[234:237], v[72:75]
	v_mfma_f32_16x16x32_bf16 v[124:127], v[178:181], v[210:213], v[124:127]
	v_mfma_f32_16x16x32_bf16 v[120:123], v[186:189], v[210:213], v[120:123]
	v_mfma_f32_16x16x32_bf16 v[108:111], v[178:181], v[222:225], v[108:111]
	v_mfma_f32_16x16x32_bf16 v[104:107], v[186:189], v[222:225], v[104:107]
	v_mfma_f32_16x16x32_bf16 v[92:95], v[178:181], v[230:233], v[92:95]
	v_mfma_f32_16x16x32_bf16 v[88:91], v[186:189], v[230:233], v[88:91]
	v_mfma_f32_16x16x32_bf16 v[76:79], v[178:181], v[238:241], v[76:79]
	v_mfma_f32_16x16x32_bf16 v[72:75], v[186:189], v[238:241], v[72:75]
	s_setprio 0
	s_setprio 1
	v_mfma_f32_16x16x32_bf16 v[116:119], v[190:193], v[206:209], v[116:119]
	v_mfma_f32_16x16x32_bf16 v[112:115], v[198:201], v[206:209], v[112:115]
	v_mfma_f32_16x16x32_bf16 v[100:103], v[190:193], v[218:221], v[100:103]
	v_mfma_f32_16x16x32_bf16 v[96:99], v[198:201], v[218:221], v[96:99]
	v_mfma_f32_16x16x32_bf16 v[84:87], v[190:193], v[226:229], v[84:87]
	v_mfma_f32_16x16x32_bf16 v[80:83], v[198:201], v[226:229], v[80:83]
	v_mfma_f32_16x16x32_bf16 v[68:71], v[190:193], v[234:237], v[68:71]
	v_mfma_f32_16x16x32_bf16 v[64:67], v[198:201], v[234:237], v[64:67]
	v_mfma_f32_16x16x32_bf16 v[116:119], v[194:197], v[210:213], v[116:119]
	v_mfma_f32_16x16x32_bf16 v[112:115], v[202:205], v[210:213], v[112:115]
	v_mfma_f32_16x16x32_bf16 v[100:103], v[194:197], v[222:225], v[100:103]
	v_mfma_f32_16x16x32_bf16 v[96:99], v[202:205], v[222:225], v[96:99]
	v_mfma_f32_16x16x32_bf16 v[84:87], v[194:197], v[230:233], v[84:87]
	v_mfma_f32_16x16x32_bf16 v[80:83], v[202:205], v[230:233], v[80:83]
	v_mfma_f32_16x16x32_bf16 v[68:71], v[194:197], v[238:241], v[68:71]
	v_mfma_f32_16x16x32_bf16 v[64:67], v[202:205], v[238:241], v[64:67]
	s_setprio 0
	s_barrier
	s_add_i32 s10, s10, s3
	v_lshl_add_u64 v[214:215], v[244:245], 0, s[16:17]
	s_mov_b32 m0, s10
	ds_read_b128 v[206:209], v170 offset:49152
	ds_read_b128 v[210:213], v170 offset:50176
	ds_read_b128 v[218:221], v170 offset:51200
	ds_read_b128 v[222:225], v170 offset:52224
	ds_read_b128 v[226:229], v170 offset:53248
	ds_read_b128 v[230:233], v170 offset:54272
	ds_read_b128 v[234:237], v170 offset:55296
	ds_read_b128 v[238:241], v170 offset:56320
	global_load_lds_dwordx4 v[214:215], off
	v_lshl_add_u64 v[214:215], v[246:247], 0, s[16:17]
	s_add_i32 m0, s10, 0x2000
	s_add_i32 s10, s11, s3
	global_load_lds_dwordx4 v[214:215], off
	v_lshl_add_u64 v[214:215], v[242:243], 0, s[18:19]
	v_lshl_add_u64 v[242:243], v[214:215], 0, v[134:135]
	s_mov_b32 m0, s10
	v_lshl_add_u64 v[214:215], v[214:215], 0, v[140:141]
	global_load_lds_dwordx4 v[242:243], off
	s_add_i32 m0, s10, 0x2000
	s_nop 0
	global_load_lds_dwordx4 v[214:215], off
	v_lshl_add_u64 v[214:215], v[248:249], 0, s[16:17]
	s_mov_b32 m0, s39
	s_nop 0
	global_load_lds_dwordx4 v[214:215], off
	v_lshl_add_u64 v[214:215], v[250:251], 0, s[16:17]
	s_mov_b32 m0, s40
	s_nop 0
	global_load_lds_dwordx4 v[214:215], off
	s_waitcnt vmcnt(8)
	s_waitcnt lgkmcnt(0)
	s_barrier
	s_setprio 1
	s_waitcnt lgkmcnt(0)
	v_mfma_f32_16x16x32_bf16 v[60:63], v[172:175], v[206:209], v[60:63]
	v_mfma_f32_16x16x32_bf16 v[56:59], v[182:185], v[206:209], v[56:59]
	v_mfma_f32_16x16x32_bf16 v[44:47], v[172:175], v[218:221], v[44:47]
	v_mfma_f32_16x16x32_bf16 v[40:43], v[182:185], v[218:221], v[40:43]
	v_mfma_f32_16x16x32_bf16 v[28:31], v[172:175], v[226:229], v[28:31]
	v_mfma_f32_16x16x32_bf16 v[24:27], v[182:185], v[226:229], v[24:27]
	v_mfma_f32_16x16x32_bf16 v[12:15], v[172:175], v[234:237], v[12:15]
	v_mfma_f32_16x16x32_bf16 v[8:11], v[182:185], v[234:237], v[8:11]
	v_mfma_f32_16x16x32_bf16 v[60:63], v[178:181], v[210:213], v[60:63]
	v_mfma_f32_16x16x32_bf16 v[56:59], v[186:189], v[210:213], v[56:59]
	v_mfma_f32_16x16x32_bf16 v[44:47], v[178:181], v[222:225], v[44:47]
	v_mfma_f32_16x16x32_bf16 v[40:43], v[186:189], v[222:225], v[40:43]
	v_mfma_f32_16x16x32_bf16 v[28:31], v[178:181], v[230:233], v[28:31]
	v_mfma_f32_16x16x32_bf16 v[24:27], v[186:189], v[230:233], v[24:27]
	v_mfma_f32_16x16x32_bf16 v[12:15], v[178:181], v[238:241], v[12:15]
	v_mfma_f32_16x16x32_bf16 v[8:11], v[186:189], v[238:241], v[8:11]
	s_setprio 0
	s_setprio 1
	v_mfma_f32_16x16x32_bf16 v[52:55], v[190:193], v[206:209], v[52:55]
	v_mfma_f32_16x16x32_bf16 v[48:51], v[198:201], v[206:209], v[48:51]
	v_mfma_f32_16x16x32_bf16 v[36:39], v[190:193], v[218:221], v[36:39]
	v_mfma_f32_16x16x32_bf16 v[32:35], v[198:201], v[218:221], v[32:35]
	v_mfma_f32_16x16x32_bf16 v[20:23], v[190:193], v[226:229], v[20:23]
	v_mfma_f32_16x16x32_bf16 v[16:19], v[198:201], v[226:229], v[16:19]
	v_mfma_f32_16x16x32_bf16 v[4:7], v[190:193], v[234:237], v[4:7]
	v_mfma_f32_16x16x32_bf16 v[0:3], v[198:201], v[234:237], v[0:3]
	v_mfma_f32_16x16x32_bf16 v[52:55], v[194:197], v[210:213], v[52:55]
	v_mfma_f32_16x16x32_bf16 v[48:51], v[202:205], v[210:213], v[48:51]
	v_mfma_f32_16x16x32_bf16 v[36:39], v[194:197], v[222:225], v[36:39]
	v_mfma_f32_16x16x32_bf16 v[32:35], v[202:205], v[222:225], v[32:35]
	v_mfma_f32_16x16x32_bf16 v[20:23], v[194:197], v[230:233], v[20:23]
	v_mfma_f32_16x16x32_bf16 v[16:19], v[202:205], v[230:233], v[16:19]
	v_mfma_f32_16x16x32_bf16 v[4:7], v[194:197], v[238:241], v[4:7]
	v_mfma_f32_16x16x32_bf16 v[0:3], v[202:205], v[238:241], v[0:3]
	s_setprio 0
	s_barrier
	s_add_i32 s31, s31, 2
	v_lshl_add_u64 v[162:163], v[162:163], 0, s[22:23]
	s_cmp_gt_u32 s31, 13
	v_lshl_add_u64 v[164:165], v[164:165], 0, s[22:23]
	s_cbranch_scc1 .LBB0_999

.LBB0_1001:
	v_lshl_add_u32 v158, s53, 12, v168
	ds_read_b128 v[160:163], v158
	v_lshl_or_b32 v156, s52, 8, v169
	v_lshl_add_u32 v159, s34, 8, v166
	v_ashrrev_i32_e32 v157, 31, v156
	v_lshlrev_b64 v[156:157], 1, v[156:157]
	s_waitcnt lgkmcnt(0)
	v_mov_b32_e32 v164, v161
	v_mov_b32_e32 v165, v162
	v_mov_b32_e32 v161, v163
	v_pk_add_f32 v[160:161], v[164:165], v[160:161]
	s_nop 0
	v_add_f32_e32 v160, v160, v161
	v_fmamk_f32 v160, v160, 0x3a800000, v171
	v_mul_f32_e32 v161, 0x4b800000, v160
	v_cmp_gt_f32_e32 vcc, s49, v160
	s_nop 1
	v_cndmask_b32_e32 v160, v160, v161, vcc
	v_rsq_f32_e32 v162, v160
	v_mad_i64_i32 v[160:161], s[10:11], v159, s48, v[142:143]
	v_lshl_add_u64 v[160:161], v[160:161], 0, v[156:157]
	v_mul_f32_e32 v163, 0x45800000, v162
	v_cndmask_b32_e32 v162, v162, v163, vcc
	v_pk_mul_f32 v[126:127], v[126:127], v[162:163] op_sel_hi:[1,0]
	v_pk_mul_f32 v[124:125], v[124:125], v[162:163] op_sel_hi:[1,0]
	v_pk_mul_f32 v[164:165], v[122:123], v[162:163] op_sel_hi:[1,0]
	v_pk_mul_f32 v[122:123], v[120:121], v[162:163] op_sel_hi:[1,0]
	v_cvt_pk_bf16_f32 v120, v124, v125
	v_cvt_pk_bf16_f32 v121, v126, v127
	v_pk_mul_f32 v[118:119], v[118:119], v[162:163] op_sel_hi:[1,0]
	v_cvt_pk_bf16_f32 v122, v122, v123
	v_cvt_pk_bf16_f32 v123, v164, v165
	global_store_dwordx4 v[160:161], v[120:123], off
	v_pk_mul_f32 v[116:117], v[116:117], v[162:163] op_sel_hi:[1,0]
	s_nop 0
	v_pk_mul_f32 v[120:121], v[114:115], v[162:163] op_sel_hi:[1,0]
	v_pk_mul_f32 v[114:115], v[112:113], v[162:163] op_sel_hi:[1,0]
	v_cvt_pk_bf16_f32 v112, v116, v117
	v_cvt_pk_bf16_f32 v113, v118, v119
	s_nop 0
	v_cvt_pk_bf16_f32 v114, v114, v115
	v_cvt_pk_bf16_f32 v115, v120, v121
	ds_read_b128 v[116:119], v158 offset:256
	global_store_dwordx4 v[160:161], v[112:115], off offset:256
	s_nop 1
	v_or_b32_e32 v114, 16, v159
	s_waitcnt lgkmcnt(0)
	v_mov_b32_e32 v112, v117
	v_mov_b32_e32 v113, v118
	v_mov_b32_e32 v117, v119
	v_pk_add_f32 v[112:113], v[112:113], v[116:117]
	s_nop 0
	v_add_f32_e32 v112, v112, v113
	v_fmamk_f32 v112, v112, 0x3a800000, v171
	v_mul_f32_e32 v113, 0x4b800000, v112
	v_cmp_gt_f32_e32 vcc, s49, v112
	s_nop 1
	v_cndmask_b32_e32 v112, v112, v113, vcc
	v_rsq_f32_e32 v115, v112
	v_mad_i64_i32 v[112:113], s[10:11], v114, s48, v[142:143]
	v_lshl_add_u64 v[112:113], v[112:113], 0, v[156:157]
	v_mul_f32_e32 v114, 0x45800000, v115
	v_cndmask_b32_e32 v114, v115, v114, vcc
	v_pk_mul_f32 v[110:111], v[110:111], v[114:115] op_sel_hi:[1,0]
	v_pk_mul_f32 v[108:109], v[108:109], v[114:115] op_sel_hi:[1,0]
	v_pk_mul_f32 v[116:117], v[106:107], v[114:115] op_sel_hi:[1,0]
	v_pk_mul_f32 v[106:107], v[104:105], v[114:115] op_sel_hi:[1,0]
	v_cvt_pk_bf16_f32 v104, v108, v109
	v_cvt_pk_bf16_f32 v105, v110, v111
	v_pk_mul_f32 v[102:103], v[102:103], v[114:115] op_sel_hi:[1,0]
	v_cvt_pk_bf16_f32 v106, v106, v107
	v_cvt_pk_bf16_f32 v107, v116, v117
	global_store_dwordx4 v[112:113], v[104:107], off
	v_pk_mul_f32 v[100:101], v[100:101], v[114:115] op_sel_hi:[1,0]
	s_nop 0
	v_pk_mul_f32 v[104:105], v[98:99], v[114:115] op_sel_hi:[1,0]
	v_pk_mul_f32 v[98:99], v[96:97], v[114:115] op_sel_hi:[1,0]
	v_cvt_pk_bf16_f32 v96, v100, v101
	v_cvt_pk_bf16_f32 v97, v102, v103
	s_nop 0
	v_cvt_pk_bf16_f32 v98, v98, v99
	v_cvt_pk_bf16_f32 v99, v104, v105
	ds_read_b128 v[100:103], v158 offset:512
	global_store_dwordx4 v[112:113], v[96:99], off offset:256
	s_nop 1
	v_or_b32_e32 v98, 32, v159
	s_waitcnt lgkmcnt(0)
	v_mov_b32_e32 v96, v101
	v_mov_b32_e32 v97, v102
	v_mov_b32_e32 v101, v103
	v_pk_add_f32 v[96:97], v[96:97], v[100:101]
	s_nop 0
	v_add_f32_e32 v96, v96, v97
	v_fmamk_f32 v96, v96, 0x3a800000, v171
	v_mul_f32_e32 v97, 0x4b800000, v96
	v_cmp_gt_f32_e32 vcc, s49, v96
	s_nop 1
	v_cndmask_b32_e32 v96, v96, v97, vcc
	v_rsq_f32_e32 v99, v96
	v_mad_i64_i32 v[96:97], s[10:11], v98, s48, v[142:143]
	v_lshl_add_u64 v[96:97], v[96:97], 0, v[156:157]
	v_mul_f32_e32 v98, 0x45800000, v99
	v_cndmask_b32_e32 v98, v99, v98, vcc
	v_pk_mul_f32 v[94:95], v[94:95], v[98:99] op_sel_hi:[1,0]
	v_pk_mul_f32 v[92:93], v[92:93], v[98:99] op_sel_hi:[1,0]
	v_pk_mul_f32 v[100:101], v[90:91], v[98:99] op_sel_hi:[1,0]
	v_pk_mul_f32 v[90:91], v[88:89], v[98:99] op_sel_hi:[1,0]
	v_cvt_pk_bf16_f32 v88, v92, v93
	v_cvt_pk_bf16_f32 v89, v94, v95
	v_pk_mul_f32 v[86:87], v[86:87], v[98:99] op_sel_hi:[1,0]
	v_cvt_pk_bf16_f32 v90, v90, v91
	v_cvt_pk_bf16_f32 v91, v100, v101
	global_store_dwordx4 v[96:97], v[88:91], off
	v_pk_mul_f32 v[84:85], v[84:85], v[98:99] op_sel_hi:[1,0]
	s_nop 0
	v_pk_mul_f32 v[88:89], v[82:83], v[98:99] op_sel_hi:[1,0]
	v_pk_mul_f32 v[82:83], v[80:81], v[98:99] op_sel_hi:[1,0]
	v_cvt_pk_bf16_f32 v80, v84, v85
	v_cvt_pk_bf16_f32 v81, v86, v87
	s_nop 0
	v_cvt_pk_bf16_f32 v82, v82, v83
	v_cvt_pk_bf16_f32 v83, v88, v89
	ds_read_b128 v[84:87], v158 offset:768
	global_store_dwordx4 v[96:97], v[80:83], off offset:256
	s_nop 1
	v_or_b32_e32 v82, 48, v159
	s_waitcnt lgkmcnt(0)
	v_mov_b32_e32 v80, v85
	v_mov_b32_e32 v81, v86
	v_mov_b32_e32 v85, v87
	v_pk_add_f32 v[80:81], v[80:81], v[84:85]
	s_nop 0
	v_add_f32_e32 v80, v80, v81
	v_fmamk_f32 v80, v80, 0x3a800000, v171
	v_mul_f32_e32 v81, 0x4b800000, v80
	v_cmp_gt_f32_e32 vcc, s49, v80
	s_nop 1
	v_cndmask_b32_e32 v80, v80, v81, vcc
	v_rsq_f32_e32 v83, v80
	v_mad_i64_i32 v[80:81], s[10:11], v82, s48, v[142:143]
	v_lshl_add_u64 v[80:81], v[80:81], 0, v[156:157]
	v_mul_f32_e32 v82, 0x45800000, v83
	v_cndmask_b32_e32 v82, v83, v82, vcc
	v_pk_mul_f32 v[78:79], v[78:79], v[82:83] op_sel_hi:[1,0]
	v_pk_mul_f32 v[76:77], v[76:77], v[82:83] op_sel_hi:[1,0]
	v_pk_mul_f32 v[84:85], v[74:75], v[82:83] op_sel_hi:[1,0]
	v_pk_mul_f32 v[74:75], v[72:73], v[82:83] op_sel_hi:[1,0]
	v_cvt_pk_bf16_f32 v72, v76, v77
	v_cvt_pk_bf16_f32 v73, v78, v79
	v_pk_mul_f32 v[70:71], v[70:71], v[82:83] op_sel_hi:[1,0]
	v_cvt_pk_bf16_f32 v74, v74, v75
	v_cvt_pk_bf16_f32 v75, v84, v85
	global_store_dwordx4 v[80:81], v[72:75], off
	v_pk_mul_f32 v[68:69], v[68:69], v[82:83] op_sel_hi:[1,0]
	s_nop 0
	v_pk_mul_f32 v[72:73], v[66:67], v[82:83] op_sel_hi:[1,0]
	v_pk_mul_f32 v[66:67], v[64:65], v[82:83] op_sel_hi:[1,0]
	v_cvt_pk_bf16_f32 v64, v68, v69
	v_cvt_pk_bf16_f32 v65, v70, v71
	s_nop 0
	v_cvt_pk_bf16_f32 v66, v66, v67
	v_cvt_pk_bf16_f32 v67, v72, v73
	ds_read_b128 v[68:71], v158 offset:2048
	global_store_dwordx4 v[80:81], v[64:67], off offset:256
	s_nop 1
	v_add_u32_e32 v66, 0x80, v159
	s_waitcnt lgkmcnt(0)
	v_mov_b32_e32 v64, v69
	v_mov_b32_e32 v65, v70
	v_mov_b32_e32 v69, v71
	v_pk_add_f32 v[64:65], v[64:65], v[68:69]
	s_nop 0
	v_add_f32_e32 v64, v64, v65
	v_fmamk_f32 v64, v64, 0x3a800000, v171
	v_mul_f32_e32 v65, 0x4b800000, v64
	v_cmp_gt_f32_e32 vcc, s49, v64
	s_nop 1
	v_cndmask_b32_e32 v64, v64, v65, vcc
	v_rsq_f32_e32 v67, v64
	v_mad_i64_i32 v[64:65], s[10:11], v66, s48, v[142:143]
	v_lshl_add_u64 v[64:65], v[64:65], 0, v[156:157]
	v_mul_f32_e32 v66, 0x45800000, v67
	v_cndmask_b32_e32 v66, v67, v66, vcc
	v_pk_mul_f32 v[62:63], v[62:63], v[66:67] op_sel_hi:[1,0]
	v_pk_mul_f32 v[60:61], v[60:61], v[66:67] op_sel_hi:[1,0]
	v_pk_mul_f32 v[68:69], v[58:59], v[66:67] op_sel_hi:[1,0]
	v_pk_mul_f32 v[58:59], v[56:57], v[66:67] op_sel_hi:[1,0]
	v_cvt_pk_bf16_f32 v56, v60, v61
	v_cvt_pk_bf16_f32 v57, v62, v63
	v_pk_mul_f32 v[54:55], v[54:55], v[66:67] op_sel_hi:[1,0]
	v_cvt_pk_bf16_f32 v58, v58, v59
	v_cvt_pk_bf16_f32 v59, v68, v69
	global_store_dwordx4 v[64:65], v[56:59], off
	v_pk_mul_f32 v[52:53], v[52:53], v[66:67] op_sel_hi:[1,0]
	s_nop 0
	v_pk_mul_f32 v[56:57], v[50:51], v[66:67] op_sel_hi:[1,0]
	v_pk_mul_f32 v[50:51], v[48:49], v[66:67] op_sel_hi:[1,0]
	v_cvt_pk_bf16_f32 v48, v52, v53
	v_cvt_pk_bf16_f32 v49, v54, v55
	s_nop 0
	v_cvt_pk_bf16_f32 v50, v50, v51
	v_cvt_pk_bf16_f32 v51, v56, v57
	ds_read_b128 v[52:55], v158 offset:2304
	global_store_dwordx4 v[64:65], v[48:51], off offset:256
	s_nop 1
	v_add_u32_e32 v50, 0x90, v159
	s_waitcnt lgkmcnt(0)
	v_mov_b32_e32 v48, v53
	v_mov_b32_e32 v49, v54
	v_mov_b32_e32 v53, v55
	v_pk_add_f32 v[48:49], v[48:49], v[52:53]
	s_nop 0
	v_add_f32_e32 v48, v48, v49
	v_fmamk_f32 v48, v48, 0x3a800000, v171
	v_mul_f32_e32 v49, 0x4b800000, v48
	v_cmp_gt_f32_e32 vcc, s49, v48
	s_nop 1
	v_cndmask_b32_e32 v48, v48, v49, vcc
	v_rsq_f32_e32 v51, v48
	v_mad_i64_i32 v[48:49], s[10:11], v50, s48, v[142:143]
	v_lshl_add_u64 v[48:49], v[48:49], 0, v[156:157]
	v_mul_f32_e32 v50, 0x45800000, v51
	v_cndmask_b32_e32 v50, v51, v50, vcc
	v_pk_mul_f32 v[46:47], v[46:47], v[50:51] op_sel_hi:[1,0]
	v_pk_mul_f32 v[44:45], v[44:45], v[50:51] op_sel_hi:[1,0]
	v_pk_mul_f32 v[52:53], v[42:43], v[50:51] op_sel_hi:[1,0]
	v_pk_mul_f32 v[42:43], v[40:41], v[50:51] op_sel_hi:[1,0]
	v_cvt_pk_bf16_f32 v40, v44, v45
	v_cvt_pk_bf16_f32 v41, v46, v47
	v_pk_mul_f32 v[38:39], v[38:39], v[50:51] op_sel_hi:[1,0]
	v_cvt_pk_bf16_f32 v42, v42, v43
	v_cvt_pk_bf16_f32 v43, v52, v53
	global_store_dwordx4 v[48:49], v[40:43], off
	v_pk_mul_f32 v[36:37], v[36:37], v[50:51] op_sel_hi:[1,0]
	s_nop 0
	v_pk_mul_f32 v[40:41], v[34:35], v[50:51] op_sel_hi:[1,0]
	v_pk_mul_f32 v[34:35], v[32:33], v[50:51] op_sel_hi:[1,0]
	v_cvt_pk_bf16_f32 v32, v36, v37
	v_cvt_pk_bf16_f32 v33, v38, v39
	s_nop 0
	v_cvt_pk_bf16_f32 v34, v34, v35
	v_cvt_pk_bf16_f32 v35, v40, v41
	ds_read_b128 v[36:39], v158 offset:2560
	global_store_dwordx4 v[48:49], v[32:35], off offset:256
	s_nop 1
	v_add_u32_e32 v34, 0xa0, v159
	s_waitcnt lgkmcnt(0)
	v_mov_b32_e32 v32, v37
	v_mov_b32_e32 v33, v38
	v_mov_b32_e32 v37, v39
	v_pk_add_f32 v[32:33], v[32:33], v[36:37]
	s_nop 0
	v_add_f32_e32 v32, v32, v33
	v_fmamk_f32 v32, v32, 0x3a800000, v171
	v_mul_f32_e32 v33, 0x4b800000, v32
	v_cmp_gt_f32_e32 vcc, s49, v32
	s_nop 1
	v_cndmask_b32_e32 v32, v32, v33, vcc
	v_rsq_f32_e32 v35, v32
	v_mad_i64_i32 v[32:33], s[10:11], v34, s48, v[142:143]
	v_lshl_add_u64 v[32:33], v[32:33], 0, v[156:157]
	v_mul_f32_e32 v34, 0x45800000, v35
	v_cndmask_b32_e32 v34, v35, v34, vcc
	v_pk_mul_f32 v[30:31], v[30:31], v[34:35] op_sel_hi:[1,0]
	v_pk_mul_f32 v[28:29], v[28:29], v[34:35] op_sel_hi:[1,0]
	v_pk_mul_f32 v[36:37], v[26:27], v[34:35] op_sel_hi:[1,0]
	v_pk_mul_f32 v[26:27], v[24:25], v[34:35] op_sel_hi:[1,0]
	v_cvt_pk_bf16_f32 v24, v28, v29
	v_cvt_pk_bf16_f32 v25, v30, v31
	v_pk_mul_f32 v[22:23], v[22:23], v[34:35] op_sel_hi:[1,0]
	v_cvt_pk_bf16_f32 v26, v26, v27
	v_cvt_pk_bf16_f32 v27, v36, v37
	global_store_dwordx4 v[32:33], v[24:27], off
	v_pk_mul_f32 v[20:21], v[20:21], v[34:35] op_sel_hi:[1,0]
	s_nop 0
	v_pk_mul_f32 v[24:25], v[18:19], v[34:35] op_sel_hi:[1,0]
	v_pk_mul_f32 v[18:19], v[16:17], v[34:35] op_sel_hi:[1,0]
	v_cvt_pk_bf16_f32 v16, v20, v21
	v_cvt_pk_bf16_f32 v17, v22, v23
	s_nop 0
	v_cvt_pk_bf16_f32 v18, v18, v19
	v_cvt_pk_bf16_f32 v19, v24, v25
	ds_read_b128 v[20:23], v158 offset:2816
	global_store_dwordx4 v[32:33], v[16:19], off offset:256
	s_nop 1
	v_add_u32_e32 v18, 0xb0, v159
	s_waitcnt lgkmcnt(0)
	v_mov_b32_e32 v16, v21
	v_mov_b32_e32 v17, v22
	v_mov_b32_e32 v21, v23
	v_pk_add_f32 v[16:17], v[16:17], v[20:21]
	s_nop 0
	v_add_f32_e32 v16, v16, v17
	v_fmamk_f32 v16, v16, 0x3a800000, v171
	v_mul_f32_e32 v17, 0x4b800000, v16
	v_cmp_gt_f32_e32 vcc, s49, v16
	s_nop 1
	v_cndmask_b32_e32 v16, v16, v17, vcc
	v_rsq_f32_e32 v19, v16
	v_mad_i64_i32 v[16:17], s[10:11], v18, s48, v[142:143]
	v_lshl_add_u64 v[16:17], v[16:17], 0, v[156:157]
	v_mul_f32_e32 v18, 0x45800000, v19
	v_cndmask_b32_e32 v18, v19, v18, vcc
	v_pk_mul_f32 v[14:15], v[14:15], v[18:19] op_sel_hi:[1,0]
	v_pk_mul_f32 v[12:13], v[12:13], v[18:19] op_sel_hi:[1,0]
	v_pk_mul_f32 v[20:21], v[10:11], v[18:19] op_sel_hi:[1,0]
	v_pk_mul_f32 v[10:11], v[8:9], v[18:19] op_sel_hi:[1,0]
	v_cvt_pk_bf16_f32 v8, v12, v13
	v_cvt_pk_bf16_f32 v9, v14, v15
	s_andn2_b64 vcc, exec, s[8:9]
	v_cvt_pk_bf16_f32 v10, v10, v11
	v_cvt_pk_bf16_f32 v11, v20, v21
	global_store_dwordx4 v[16:17], v[8:11], off
	s_mov_b64 s[8:9], -1
	v_pk_mul_f32 v[6:7], v[6:7], v[18:19] op_sel_hi:[1,0]
	v_pk_mul_f32 v[8:9], v[2:3], v[18:19] op_sel_hi:[1,0]
	v_pk_mul_f32 v[2:3], v[0:1], v[18:19] op_sel_hi:[1,0]
	v_pk_mul_f32 v[4:5], v[4:5], v[18:19] op_sel_hi:[1,0]
	s_nop 0
	v_cvt_pk_bf16_f32 v0, v4, v5
	v_cvt_pk_bf16_f32 v1, v6, v7
	v_cvt_pk_bf16_f32 v2, v2, v3
	v_cvt_pk_bf16_f32 v3, v8, v9
	global_store_dwordx4 v[16:17], v[0:3], off offset:256
	s_mov_b32 s100, 1
	s_cbranch_vccnz .LBB0_991
	s_andn2_b64 vcc, exec, s[14:15]
	s_cbranch_vccnz .LBB0_990
	s_barrier
	s_branch .LBB0_990

.LBB0_1350:
	s_mov_b64 s[14:15], 0x80
	s_add_i32 m0, s31, 0x18000
	v_lshl_add_u64 v[6:7], v[6:7], 0, s[14:15]
	s_waitcnt vmcnt(2)
	s_barrier
	global_load_lds_dwordx4 v[6:7], off
	v_lshl_add_u64 v[6:7], v[8:9], 0, s[14:15]
	s_add_i32 m0, s31, 0x1a000
	s_add_i32 s38, s31, 0x8000
	global_load_lds_dwordx4 v[6:7], off
	v_lshl_add_u64 v[6:7], v[10:11], 0, s[14:15]
	s_mov_b32 m0, s38
	s_add_i32 s39, s31, 0xa000
	global_load_lds_dwordx4 v[6:7], off
	v_lshl_add_u64 v[6:7], v[12:13], 0, s[14:15]
	s_mov_b32 m0, s39
	s_mov_b64 s[16:17], 0x40080
	global_load_lds_dwordx4 v[6:7], off
	v_lshl_add_u64 v[6:7], v[2:3], 0, s[16:17]
	s_add_i32 m0, s31, 0x1c000
	v_lshl_add_u64 v[8:9], v[6:7], 0, v[136:137]
	global_load_lds_dwordx4 v[8:9], off
	v_lshl_add_u64 v[6:7], v[6:7], 0, v[140:141]
	s_add_i32 m0, s31, 0x1e000
	s_mov_b64 s[18:19], 0xd000000
	global_load_lds_dwordx4 v[6:7], off
	v_lshl_add_u64 v[142:143], v[4:5], 0, s[18:19]
	v_lshrrev_b32_e32 v5, 1, v14
	v_and_b32_e32 v5, 24, v5
	v_and_b32_e32 v4, 15, v14
	v_lshlrev_b32_e32 v6, 1, v5
	v_lshl_or_b32 v166, s8, 6, v4
	v_lshl_or_b32 v4, v4, 6, v6
	v_lshlrev_b32_e32 v6, 2, v14
	s_lshl_b32 s7, s7, 5
	s_lshl_b32 s8, s8, 13
	v_and_b32_e32 v6, 32, v6
	s_and_b32 s7, s7, 0x60
	v_bitop3_b32 v7, v4, s8, v6 bitop3:0xde
	s_lshl_b32 s8, s7, 7
	v_bitop3_b32 v167, v4, s8, v6 bitop3:0xde
	v_lshlrev_b32_e32 v4, 14, v18
	v_and_b32_e32 v4, 0xffff8000, v4
	v_or_b32_e32 v169, s7, v5
	v_lshl_add_u32 v4, v19, 11, v4
	v_and_b32_e32 v5, 1, v18
	v_lshl_or_b32 v4, v5, 6, v4
	v_lshl_add_u32 v144, v20, 1, v4
	v_lshlrev_b32_e32 v4, 14, v15
	v_and_b32_e32 v4, 0xffff8000, v4
	s_waitcnt vmcnt(6)
	s_cmpk_lt_u32 s6, 0x100
	v_lshl_add_u32 v4, v16, 11, v4
	v_and_b32_e32 v5, 1, v15
	s_cselect_b64 s[18:19], -1, 0
	s_add_i32 s6, 0, 0x21c00
	v_lshl_or_b32 v4, v5, 6, v4
	s_mov_b32 s22, 0xfffc0080
	s_mov_b32 s51, 0
	v_lshl_add_u32 v168, v166, 4, s6
	v_mov_b32_e32 v145, v137
	v_lshl_add_u32 v146, v17, 1, v4
	v_mov_b32_e32 v147, v137
	v_mov_b64_e32 v[148:149], 0xb00
	v_mov_b64_e32 v[150:151], 0xaff
	s_movk_i32 s40, 0x161
	s_mov_b64 s[20:21], 0x100
	s_mov_b32 s23, -1
	s_add_i32 s41, 0, 0x10000
	s_add_i32 s42, 0, 0x14000
	v_add_u32_e32 v170, 0, v7
	s_add_i32 s43, s31, 0xc000
	s_add_i32 s44, s31, 0xe000
	s_movk_i32 s45, 0x1600
	v_mov_b32_e32 v171, 0x358637bd
	s_mov_b32 s48, 0x800000
	s_mov_b32 s49, 0
	s_barrier
	s_mov_b32 s100, 0
	s_branch .LBB0_1353

.LBB0_1356:
	v_add_u32_e32 v186, s41, v167
	v_add_u32_e32 v202, s42, v167
	ds_read_b128 v[172:175], v186
	ds_read_b128 v[178:181], v186 offset:1024
	ds_read_b128 v[182:185], v186 offset:2048
	ds_read_b128 v[186:189], v186 offset:3072
	ds_read_b128 v[190:193], v202
	ds_read_b128 v[194:197], v202 offset:1024
	ds_read_b128 v[198:201], v202 offset:2048
	ds_read_b128 v[202:205], v202 offset:3072
	v_lshl_add_u64 v[206:207], v[164:165], 0, s[22:23]
	v_cndmask_b32_e64 v215, v207, v157, s[8:9]
	v_cndmask_b32_e64 v214, v206, v156, s[8:9]
	v_cndmask_b32_e64 v243, v163, v159, s[8:9]
	v_cndmask_b32_e64 v242, v162, v158, s[8:9]
	s_mov_b32 m0, s43
	v_lshl_add_u64 v[244:245], v[164:165], 0, v[146:147]
	ds_read_b128 v[206:209], v170
	ds_read_b128 v[210:213], v170 offset:1024
	ds_read_b128 v[218:221], v170 offset:2048
	ds_read_b128 v[222:225], v170 offset:3072
	ds_read_b128 v[226:229], v170 offset:4096
	ds_read_b128 v[230:233], v170 offset:5120
	ds_read_b128 v[234:237], v170 offset:6144
	ds_read_b128 v[238:241], v170 offset:7168
	global_load_lds_dwordx4 v[244:245], off
	v_lshl_add_u64 v[244:245], v[164:165], 0, v[144:145]
	s_mov_b32 m0, s44
	s_nop 0
	global_load_lds_dwordx4 v[244:245], off
	s_cmp_eq_u32 s100, 0
	s_cbranch_scc1 .Lgw8_42504_0
	s_waitcnt vmcnt(16)
	s_branch .Lgwd_42504_0

.Lgwd_42504_0:
	s_waitcnt lgkmcnt(0)
	s_barrier
	s_setprio 1
	s_waitcnt lgkmcnt(0)
	v_mfma_f32_16x16x32_bf16 v[124:127], v[172:175], v[206:209], v[124:127]
	v_mfma_f32_16x16x32_bf16 v[116:119], v[182:185], v[206:209], v[116:119]
	v_mfma_f32_16x16x32_bf16 v[108:111], v[172:175], v[218:221], v[108:111]
	v_mfma_f32_16x16x32_bf16 v[100:103], v[182:185], v[218:221], v[100:103]
	v_mfma_f32_16x16x32_bf16 v[92:95], v[172:175], v[226:229], v[92:95]
	v_mfma_f32_16x16x32_bf16 v[84:87], v[182:185], v[226:229], v[84:87]
	v_mfma_f32_16x16x32_bf16 v[76:79], v[172:175], v[234:237], v[76:79]
	v_mfma_f32_16x16x32_bf16 v[68:71], v[182:185], v[234:237], v[68:71]
	v_mfma_f32_16x16x32_bf16 v[124:127], v[178:181], v[210:213], v[124:127]
	v_mfma_f32_16x16x32_bf16 v[116:119], v[186:189], v[210:213], v[116:119]
	v_mfma_f32_16x16x32_bf16 v[108:111], v[178:181], v[222:225], v[108:111]
	v_mfma_f32_16x16x32_bf16 v[100:103], v[186:189], v[222:225], v[100:103]
	v_mfma_f32_16x16x32_bf16 v[92:95], v[178:181], v[230:233], v[92:95]
	v_mfma_f32_16x16x32_bf16 v[84:87], v[186:189], v[230:233], v[84:87]
	v_mfma_f32_16x16x32_bf16 v[76:79], v[178:181], v[238:241], v[76:79]
	v_mfma_f32_16x16x32_bf16 v[68:71], v[186:189], v[238:241], v[68:71]
	s_setprio 0
	s_setprio 1
	v_mfma_f32_16x16x32_bf16 v[120:123], v[190:193], v[206:209], v[120:123]
	v_mfma_f32_16x16x32_bf16 v[112:115], v[198:201], v[206:209], v[112:115]
	v_mfma_f32_16x16x32_bf16 v[104:107], v[190:193], v[218:221], v[104:107]
	v_mfma_f32_16x16x32_bf16 v[96:99], v[198:201], v[218:221], v[96:99]
	v_mfma_f32_16x16x32_bf16 v[88:91], v[190:193], v[226:229], v[88:91]
	v_mfma_f32_16x16x32_bf16 v[80:83], v[198:201], v[226:229], v[80:83]
	v_mfma_f32_16x16x32_bf16 v[72:75], v[190:193], v[234:237], v[72:75]
	v_mfma_f32_16x16x32_bf16 v[64:67], v[198:201], v[234:237], v[64:67]
	v_mfma_f32_16x16x32_bf16 v[120:123], v[194:197], v[210:213], v[120:123]
	v_mfma_f32_16x16x32_bf16 v[112:115], v[202:205], v[210:213], v[112:115]
	v_mfma_f32_16x16x32_bf16 v[104:107], v[194:197], v[222:225], v[104:107]
	v_mfma_f32_16x16x32_bf16 v[96:99], v[202:205], v[222:225], v[96:99]
	v_mfma_f32_16x16x32_bf16 v[88:91], v[194:197], v[230:233], v[88:91]
	v_mfma_f32_16x16x32_bf16 v[80:83], v[202:205], v[230:233], v[80:83]
	v_mfma_f32_16x16x32_bf16 v[72:75], v[194:197], v[238:241], v[72:75]
	v_mfma_f32_16x16x32_bf16 v[64:67], v[202:205], v[238:241], v[64:67]
	s_setprio 0
	s_barrier
	s_add_i32 s8, s41, s3
	v_lshl_add_u64 v[244:245], v[242:243], 0, v[136:137]
	s_mov_b32 m0, s8
	ds_read_b128 v[206:209], v170 offset:16384
	ds_read_b128 v[210:213], v170 offset:17408
	ds_read_b128 v[218:221], v170 offset:18432
	ds_read_b128 v[222:225], v170 offset:19456
	ds_read_b128 v[226:229], v170 offset:20480
	ds_read_b128 v[230:233], v170 offset:21504
	ds_read_b128 v[234:237], v170 offset:22528
	ds_read_b128 v[238:241], v170 offset:23552
	global_load_lds_dwordx4 v[244:245], off
	v_lshl_add_u64 v[246:247], v[242:243], 0, v[140:141]
	s_add_i32 m0, s8, 0x2000
	v_lshl_add_u64 v[248:249], v[242:243], 0, s[10:11]
	s_add_i32 s8, s42, s3
	global_load_lds_dwordx4 v[246:247], off
	v_lshl_add_u64 v[250:251], v[248:249], 0, v[136:137]
	s_mov_b32 m0, s8
	v_lshl_add_u64 v[248:249], v[248:249], 0, v[140:141]
	global_load_lds_dwordx4 v[250:251], off
	s_add_i32 m0, s8, 0x2000
	v_lshl_add_u64 v[250:251], v[214:215], 0, v[138:139]
	global_load_lds_dwordx4 v[248:249], off
	v_lshl_add_u64 v[248:249], v[214:215], 0, v[134:135]
	s_mov_b32 m0, s31
	s_nop 0
	global_load_lds_dwordx4 v[248:249], off
	s_mov_b32 m0, s35
	s_nop 0
	global_load_lds_dwordx4 v[250:251], off
	s_cmp_eq_u32 s100, 0
	s_cbranch_scc1 .Lgw8_42504_1
	s_waitcnt vmcnt(16)
	s_mov_b32 s100, 0
	s_branch .Lgwd_42504_1

.Lgwd_42504_1:
	s_waitcnt lgkmcnt(0)
	s_barrier
	s_setprio 1
	s_waitcnt lgkmcnt(0)
	v_mfma_f32_16x16x32_bf16 v[60:63], v[172:175], v[206:209], v[60:63]
	v_mfma_f32_16x16x32_bf16 v[52:55], v[182:185], v[206:209], v[52:55]
	v_mfma_f32_16x16x32_bf16 v[44:47], v[172:175], v[218:221], v[44:47]
	v_mfma_f32_16x16x32_bf16 v[36:39], v[182:185], v[218:221], v[36:39]
	v_mfma_f32_16x16x32_bf16 v[28:31], v[172:175], v[226:229], v[28:31]
	v_mfma_f32_16x16x32_bf16 v[20:23], v[182:185], v[226:229], v[20:23]
	v_mfma_f32_16x16x32_bf16 v[12:15], v[172:175], v[234:237], v[12:15]
	v_mfma_f32_16x16x32_bf16 v[4:7], v[182:185], v[234:237], v[4:7]
	v_mfma_f32_16x16x32_bf16 v[60:63], v[178:181], v[210:213], v[60:63]
	v_mfma_f32_16x16x32_bf16 v[52:55], v[186:189], v[210:213], v[52:55]
	v_mfma_f32_16x16x32_bf16 v[44:47], v[178:181], v[222:225], v[44:47]
	v_mfma_f32_16x16x32_bf16 v[36:39], v[186:189], v[222:225], v[36:39]
	v_mfma_f32_16x16x32_bf16 v[28:31], v[178:181], v[230:233], v[28:31]
	v_mfma_f32_16x16x32_bf16 v[20:23], v[186:189], v[230:233], v[20:23]
	v_mfma_f32_16x16x32_bf16 v[12:15], v[178:181], v[238:241], v[12:15]
	v_mfma_f32_16x16x32_bf16 v[4:7], v[186:189], v[238:241], v[4:7]
	s_setprio 0
	s_setprio 1
	v_mfma_f32_16x16x32_bf16 v[56:59], v[190:193], v[206:209], v[56:59]
	v_mfma_f32_16x16x32_bf16 v[48:51], v[198:201], v[206:209], v[48:51]
	v_mfma_f32_16x16x32_bf16 v[40:43], v[190:193], v[218:221], v[40:43]
	v_mfma_f32_16x16x32_bf16 v[32:35], v[198:201], v[218:221], v[32:35]
	v_mfma_f32_16x16x32_bf16 v[24:27], v[190:193], v[226:229], v[24:27]
	v_mfma_f32_16x16x32_bf16 v[16:19], v[198:201], v[226:229], v[16:19]
	v_mfma_f32_16x16x32_bf16 v[8:11], v[190:193], v[234:237], v[8:11]
	v_mfma_f32_16x16x32_bf16 v[0:3], v[198:201], v[234:237], v[0:3]
	v_mfma_f32_16x16x32_bf16 v[56:59], v[194:197], v[210:213], v[56:59]
	v_mfma_f32_16x16x32_bf16 v[48:51], v[202:205], v[210:213], v[48:51]
	v_mfma_f32_16x16x32_bf16 v[40:43], v[194:197], v[222:225], v[40:43]
	v_mfma_f32_16x16x32_bf16 v[32:35], v[202:205], v[222:225], v[32:35]
	v_mfma_f32_16x16x32_bf16 v[24:27], v[194:197], v[230:233], v[24:27]
	v_mfma_f32_16x16x32_bf16 v[16:19], v[202:205], v[230:233], v[16:19]
	v_mfma_f32_16x16x32_bf16 v[8:11], v[194:197], v[238:241], v[8:11]
	v_mfma_f32_16x16x32_bf16 v[0:3], v[202:205], v[238:241], v[0:3]
	s_setprio 0
	s_barrier
	s_add_i32 s8, 0, 0x18000
	s_add_i32 s9, 0, 0x1c000
	v_add_u32_e32 v186, s8, v167
	v_add_u32_e32 v202, s9, v167
	ds_read_b128 v[172:175], v186
	ds_read_b128 v[178:181], v186 offset:1024
	ds_read_b128 v[182:185], v186 offset:2048
	ds_read_b128 v[186:189], v186 offset:3072
	ds_read_b128 v[190:193], v202
	ds_read_b128 v[194:197], v202 offset:1024
	ds_read_b128 v[198:201], v202 offset:2048
	ds_read_b128 v[202:205], v202 offset:3072
	v_lshl_add_u64 v[214:215], v[214:215], 0, s[10:11]
	s_mov_b32 m0, s36
	v_lshl_add_u64 v[252:253], v[214:215], 0, v[134:135]
	ds_read_b128 v[206:209], v170 offset:32768
	ds_read_b128 v[210:213], v170 offset:33792
	ds_read_b128 v[218:221], v170 offset:34816
	ds_read_b128 v[222:225], v170 offset:35840
	ds_read_b128 v[226:229], v170 offset:36864
	ds_read_b128 v[230:233], v170 offset:37888
	ds_read_b128 v[234:237], v170 offset:38912
	ds_read_b128 v[238:241], v170 offset:39936
	global_load_lds_dwordx4 v[252:253], off
	v_lshl_add_u64 v[214:215], v[214:215], 0, v[138:139]
	s_mov_b32 m0, s37
	s_nop 0
	global_load_lds_dwordx4 v[214:215], off
	s_waitcnt vmcnt(8)
	s_waitcnt lgkmcnt(0)
	s_barrier
	s_setprio 1
	s_waitcnt lgkmcnt(0)
	v_mfma_f32_16x16x32_bf16 v[124:127], v[172:175], v[206:209], v[124:127]
	v_mfma_f32_16x16x32_bf16 v[116:119], v[182:185], v[206:209], v[116:119]
	v_mfma_f32_16x16x32_bf16 v[108:111], v[172:175], v[218:221], v[108:111]
	v_mfma_f32_16x16x32_bf16 v[100:103], v[182:185], v[218:221], v[100:103]
	v_mfma_f32_16x16x32_bf16 v[92:95], v[172:175], v[226:229], v[92:95]
	v_mfma_f32_16x16x32_bf16 v[84:87], v[182:185], v[226:229], v[84:87]
	v_mfma_f32_16x16x32_bf16 v[76:79], v[172:175], v[234:237], v[76:79]
	v_mfma_f32_16x16x32_bf16 v[68:71], v[182:185], v[234:237], v[68:71]
	v_mfma_f32_16x16x32_bf16 v[124:127], v[178:181], v[210:213], v[124:127]
	v_mfma_f32_16x16x32_bf16 v[116:119], v[186:189], v[210:213], v[116:119]
	v_mfma_f32_16x16x32_bf16 v[108:111], v[178:181], v[222:225], v[108:111]
	v_mfma_f32_16x16x32_bf16 v[100:103], v[186:189], v[222:225], v[100:103]
	v_mfma_f32_16x16x32_bf16 v[92:95], v[178:181], v[230:233], v[92:95]
	v_mfma_f32_16x16x32_bf16 v[84:87], v[186:189], v[230:233], v[84:87]
	v_mfma_f32_16x16x32_bf16 v[76:79], v[178:181], v[238:241], v[76:79]
	v_mfma_f32_16x16x32_bf16 v[68:71], v[186:189], v[238:241], v[68:71]
	s_setprio 0
	s_setprio 1
	v_mfma_f32_16x16x32_bf16 v[120:123], v[190:193], v[206:209], v[120:123]
	v_mfma_f32_16x16x32_bf16 v[112:115], v[198:201], v[206:209], v[112:115]
	v_mfma_f32_16x16x32_bf16 v[104:107], v[190:193], v[218:221], v[104:107]
	v_mfma_f32_16x16x32_bf16 v[96:99], v[198:201], v[218:221], v[96:99]
	v_mfma_f32_16x16x32_bf16 v[88:91], v[190:193], v[226:229], v[88:91]
	v_mfma_f32_16x16x32_bf16 v[80:83], v[198:201], v[226:229], v[80:83]
	v_mfma_f32_16x16x32_bf16 v[72:75], v[190:193], v[234:237], v[72:75]
	v_mfma_f32_16x16x32_bf16 v[64:67], v[198:201], v[234:237], v[64:67]
	v_mfma_f32_16x16x32_bf16 v[120:123], v[194:197], v[210:213], v[120:123]
	v_mfma_f32_16x16x32_bf16 v[112:115], v[202:205], v[210:213], v[112:115]
	v_mfma_f32_16x16x32_bf16 v[104:107], v[194:197], v[222:225], v[104:107]
	v_mfma_f32_16x16x32_bf16 v[96:99], v[202:205], v[222:225], v[96:99]
	v_mfma_f32_16x16x32_bf16 v[88:91], v[194:197], v[230:233], v[88:91]
	v_mfma_f32_16x16x32_bf16 v[80:83], v[202:205], v[230:233], v[80:83]
	v_mfma_f32_16x16x32_bf16 v[72:75], v[194:197], v[238:241], v[72:75]
	v_mfma_f32_16x16x32_bf16 v[64:67], v[202:205], v[238:241], v[64:67]
	s_setprio 0
	s_barrier
	s_add_i32 s8, s8, s3
	v_lshl_add_u64 v[214:215], v[244:245], 0, s[14:15]
	s_mov_b32 m0, s8
	ds_read_b128 v[206:209], v170 offset:49152
	ds_read_b128 v[210:213], v170 offset:50176
	ds_read_b128 v[218:221], v170 offset:51200
	ds_read_b128 v[222:225], v170 offset:52224
	ds_read_b128 v[226:229], v170 offset:53248
	ds_read_b128 v[230:233], v170 offset:54272
	ds_read_b128 v[234:237], v170 offset:55296
	ds_read_b128 v[238:241], v170 offset:56320
	global_load_lds_dwordx4 v[214:215], off
	v_lshl_add_u64 v[214:215], v[246:247], 0, s[14:15]
	s_add_i32 m0, s8, 0x2000
	s_add_i32 s8, s9, s3
	global_load_lds_dwordx4 v[214:215], off
	v_lshl_add_u64 v[214:215], v[242:243], 0, s[16:17]
	v_lshl_add_u64 v[242:243], v[214:215], 0, v[136:137]
	s_mov_b32 m0, s8
	v_lshl_add_u64 v[214:215], v[214:215], 0, v[140:141]
	global_load_lds_dwordx4 v[242:243], off
	s_add_i32 m0, s8, 0x2000
	s_nop 0
	global_load_lds_dwordx4 v[214:215], off
	v_lshl_add_u64 v[214:215], v[248:249], 0, s[14:15]
	s_mov_b32 m0, s38
	s_nop 0
	global_load_lds_dwordx4 v[214:215], off
	v_lshl_add_u64 v[214:215], v[250:251], 0, s[14:15]
	s_mov_b32 m0, s39
	s_nop 0
	global_load_lds_dwordx4 v[214:215], off
	s_waitcnt vmcnt(8)
	s_waitcnt lgkmcnt(0)
	s_barrier
	s_setprio 1
	s_waitcnt lgkmcnt(0)
	v_mfma_f32_16x16x32_bf16 v[60:63], v[172:175], v[206:209], v[60:63]
	v_mfma_f32_16x16x32_bf16 v[52:55], v[182:185], v[206:209], v[52:55]
	v_mfma_f32_16x16x32_bf16 v[44:47], v[172:175], v[218:221], v[44:47]
	v_mfma_f32_16x16x32_bf16 v[36:39], v[182:185], v[218:221], v[36:39]
	v_mfma_f32_16x16x32_bf16 v[28:31], v[172:175], v[226:229], v[28:31]
	v_mfma_f32_16x16x32_bf16 v[20:23], v[182:185], v[226:229], v[20:23]
	v_mfma_f32_16x16x32_bf16 v[12:15], v[172:175], v[234:237], v[12:15]
	v_mfma_f32_16x16x32_bf16 v[4:7], v[182:185], v[234:237], v[4:7]
	v_mfma_f32_16x16x32_bf16 v[60:63], v[178:181], v[210:213], v[60:63]
	v_mfma_f32_16x16x32_bf16 v[52:55], v[186:189], v[210:213], v[52:55]
	v_mfma_f32_16x16x32_bf16 v[44:47], v[178:181], v[222:225], v[44:47]
	v_mfma_f32_16x16x32_bf16 v[36:39], v[186:189], v[222:225], v[36:39]
	v_mfma_f32_16x16x32_bf16 v[28:31], v[178:181], v[230:233], v[28:31]
	v_mfma_f32_16x16x32_bf16 v[20:23], v[186:189], v[230:233], v[20:23]
	v_mfma_f32_16x16x32_bf16 v[12:15], v[178:181], v[238:241], v[12:15]
	v_mfma_f32_16x16x32_bf16 v[4:7], v[186:189], v[238:241], v[4:7]
	s_setprio 0
	s_setprio 1
	v_mfma_f32_16x16x32_bf16 v[56:59], v[190:193], v[206:209], v[56:59]
	v_mfma_f32_16x16x32_bf16 v[48:51], v[198:201], v[206:209], v[48:51]
	v_mfma_f32_16x16x32_bf16 v[40:43], v[190:193], v[218:221], v[40:43]
	v_mfma_f32_16x16x32_bf16 v[32:35], v[198:201], v[218:221], v[32:35]
	v_mfma_f32_16x16x32_bf16 v[24:27], v[190:193], v[226:229], v[24:27]
	v_mfma_f32_16x16x32_bf16 v[16:19], v[198:201], v[226:229], v[16:19]
	v_mfma_f32_16x16x32_bf16 v[8:11], v[190:193], v[234:237], v[8:11]
	v_mfma_f32_16x16x32_bf16 v[0:3], v[198:201], v[234:237], v[0:3]
	v_mfma_f32_16x16x32_bf16 v[56:59], v[194:197], v[210:213], v[56:59]
	v_mfma_f32_16x16x32_bf16 v[48:51], v[202:205], v[210:213], v[48:51]
	v_mfma_f32_16x16x32_bf16 v[40:43], v[194:197], v[222:225], v[40:43]
	v_mfma_f32_16x16x32_bf16 v[32:35], v[202:205], v[222:225], v[32:35]
	v_mfma_f32_16x16x32_bf16 v[24:27], v[194:197], v[230:233], v[24:27]
	v_mfma_f32_16x16x32_bf16 v[16:19], v[202:205], v[230:233], v[16:19]
	v_mfma_f32_16x16x32_bf16 v[8:11], v[194:197], v[238:241], v[8:11]
	v_mfma_f32_16x16x32_bf16 v[0:3], v[202:205], v[238:241], v[0:3]
	s_setprio 0
	s_barrier
	s_add_i32 s29, s29, 2
	v_lshl_add_u64 v[162:163], v[162:163], 0, s[20:21]
	s_cmp_gt_u32 s29, 13
	v_lshl_add_u64 v[164:165], v[164:165], 0, s[20:21]
	s_cbranch_scc1 .LBB0_1360

.LBB0_1362:
	v_lshl_add_u32 v156, s51, 12, v168
	ds_read_b128 v[158:161], v156
	v_pk_mul_f32 v[120:121], v[124:125], v[120:121]
	v_pk_mul_f32 v[122:123], v[126:127], v[122:123]
	v_pk_mul_f32 v[112:113], v[116:117], v[112:113]
	v_pk_mul_f32 v[114:115], v[118:119], v[114:115]
	s_waitcnt lgkmcnt(0)
	v_mov_b32_e32 v162, v159
	v_mov_b32_e32 v163, v160
	v_mov_b32_e32 v159, v161
	v_pk_add_f32 v[158:159], v[162:163], v[158:159]
	v_pk_mul_f32 v[104:105], v[108:109], v[104:105]
	v_add_f32_e32 v157, v158, v159
	v_fmamk_f32 v157, v157, 0x3a800000, v171
	v_mul_f32_e32 v158, 0x4b800000, v157
	v_cmp_gt_f32_e32 vcc, s48, v157
	v_pk_mul_f32 v[106:107], v[110:111], v[106:107]
	v_pk_mul_f32 v[96:97], v[100:101], v[96:97]
	v_cndmask_b32_e32 v157, v157, v158, vcc
	v_rsq_f32_e32 v157, v157
	v_pk_mul_f32 v[98:99], v[102:103], v[98:99]
	v_pk_mul_f32 v[88:89], v[92:93], v[88:89]
	v_pk_mul_f32 v[90:91], v[94:95], v[90:91]
	v_mul_f32_e32 v158, 0x45800000, v157
	v_cndmask_b32_e32 v157, v157, v158, vcc
	v_mul_f32_e32 v158, 0xbfb8aa3b, v157
	v_pk_mul_f32 v[124:125], v[124:125], v[158:159] op_sel_hi:[1,0]
	v_pk_mul_f32 v[126:127], v[126:127], v[158:159] op_sel_hi:[1,0]
	v_exp_f32_e32 v124, v124
	v_exp_f32_e32 v125, v125
	v_exp_f32_e32 v126, v126
	v_exp_f32_e32 v127, v127
	v_mul_f32_e32 v160, v157, v157
	v_pk_add_f32 v[124:125], v[124:125], 1.0 op_sel_hi:[1,0]
	v_pk_mul_f32 v[120:121], v[120:121], v[160:161] op_sel_hi:[1,0]
	v_rcp_f32_e32 v124, v124
	v_rcp_f32_e32 v125, v125
	v_pk_add_f32 v[126:127], v[126:127], 1.0 op_sel_hi:[1,0]
	v_pk_mul_f32 v[122:123], v[122:123], v[160:161] op_sel_hi:[1,0]
	v_pk_mul_f32 v[112:113], v[112:113], v[160:161] op_sel_hi:[1,0]
	v_pk_mul_f32 v[120:121], v[120:121], v[124:125]
	v_rcp_f32_e32 v124, v126
	v_rcp_f32_e32 v125, v127
	v_pk_mul_f32 v[126:127], v[116:117], v[158:159] op_sel_hi:[1,0]
	v_cvt_pk_bf16_f32 v120, v120, v121
	v_pk_mul_f32 v[80:81], v[84:85], v[80:81]
	v_exp_f32_e32 v126, v126
	v_exp_f32_e32 v127, v127
	v_pk_mul_f32 v[122:123], v[122:123], v[124:125]
	v_pk_mul_f32 v[124:125], v[118:119], v[158:159] op_sel_hi:[1,0]
	v_cvt_pk_bf16_f32 v121, v122, v123
	v_pk_add_f32 v[122:123], v[126:127], 1.0 op_sel_hi:[1,0]
	v_exp_f32_e32 v124, v124
	v_exp_f32_e32 v125, v125
	v_rcp_f32_e32 v122, v122
	v_rcp_f32_e32 v123, v123
	v_pk_mul_f32 v[82:83], v[86:87], v[82:83]
	v_pk_add_f32 v[116:117], v[124:125], 1.0 op_sel_hi:[1,0]
	v_pk_mul_f32 v[72:73], v[76:77], v[72:73]
	v_rcp_f32_e32 v116, v116
	v_rcp_f32_e32 v117, v117
	v_pk_mul_f32 v[112:113], v[112:113], v[122:123]
	v_pk_mul_f32 v[74:75], v[78:79], v[74:75]
	v_cvt_pk_bf16_f32 v122, v112, v113
	v_pk_mul_f32 v[112:113], v[114:115], v[160:161] op_sel_hi:[1,0]
	v_lshl_add_u32 v114, s30, 8, v166
	v_pk_mul_f32 v[112:113], v[112:113], v[116:117]
	v_pk_mul_f32 v[64:65], v[68:69], v[64:65]
	v_cvt_pk_bf16_f32 v123, v112, v113
	ds_read_b128 v[116:119], v156 offset:256
	v_lshl_or_b32 v112, s34, 7, v169
	v_ashrrev_i32_e32 v113, 31, v112
	v_lshlrev_b64 v[112:113], 1, v[112:113]
	v_pk_mul_f32 v[66:67], v[70:71], v[66:67]
	s_waitcnt lgkmcnt(0)
	v_mov_b32_e32 v124, v117
	v_mov_b32_e32 v125, v118
	v_mov_b32_e32 v117, v119
	v_pk_add_f32 v[116:117], v[124:125], v[116:117]
	v_pk_mul_f32 v[56:57], v[60:61], v[56:57]
	v_add_f32_e32 v115, v116, v117
	v_fmamk_f32 v115, v115, 0x3a800000, v171
	v_mul_f32_e32 v116, 0x4b800000, v115
	v_cmp_gt_f32_e32 vcc, s48, v115
	v_pk_mul_f32 v[58:59], v[62:63], v[58:59]
	v_pk_mul_f32 v[48:49], v[52:53], v[48:49]
	v_cndmask_b32_e32 v115, v115, v116, vcc
	v_rsq_f32_e32 v115, v115
	v_mad_i64_i32 v[116:117], s[8:9], v114, s45, v[142:143]
	v_lshl_add_u64 v[116:117], v[116:117], 0, v[112:113]
	v_mul_f32_e32 v118, 0x45800000, v115
	v_cndmask_b32_e32 v115, v115, v118, vcc
	v_mul_f32_e32 v118, 0xbfb8aa3b, v115
	v_pk_mul_f32 v[124:125], v[108:109], v[118:119] op_sel_hi:[1,0]
	v_pk_mul_f32 v[108:109], v[110:111], v[118:119] op_sel_hi:[1,0]
	v_exp_f32_e32 v124, v124
	v_exp_f32_e32 v108, v108
	v_exp_f32_e32 v109, v109
	v_exp_f32_e32 v125, v125
	global_store_dwordx4 v[116:117], v[120:123], off
	v_mul_f32_e32 v116, v115, v115
	v_pk_add_f32 v[108:109], v[108:109], 1.0 op_sel_hi:[1,0]
	v_pk_add_f32 v[120:121], v[124:125], 1.0 op_sel_hi:[1,0]
	v_rcp_f32_e32 v108, v108
	v_rcp_f32_e32 v109, v109
	v_rcp_f32_e32 v120, v120
	v_rcp_f32_e32 v121, v121
	v_pk_mul_f32 v[110:111], v[100:101], v[118:119] op_sel_hi:[1,0]
	v_pk_mul_f32 v[106:107], v[106:107], v[116:117] op_sel_hi:[1,0]
	v_exp_f32_e32 v110, v110
	v_exp_f32_e32 v111, v111
	v_pk_mul_f32 v[106:107], v[106:107], v[108:109]
	v_pk_mul_f32 v[108:109], v[102:103], v[118:119] op_sel_hi:[1,0]
	v_pk_mul_f32 v[104:105], v[104:105], v[116:117] op_sel_hi:[1,0]
	v_exp_f32_e32 v108, v108
	v_exp_f32_e32 v109, v109
	v_pk_mul_f32 v[104:105], v[104:105], v[120:121]
	v_pk_mul_f32 v[96:97], v[96:97], v[116:117] op_sel_hi:[1,0]
	v_cvt_pk_bf16_f32 v104, v104, v105
	v_cvt_pk_bf16_f32 v105, v106, v107
	v_pk_add_f32 v[106:107], v[110:111], 1.0 op_sel_hi:[1,0]
	v_pk_add_f32 v[100:101], v[108:109], 1.0 op_sel_hi:[1,0]
	v_rcp_f32_e32 v106, v106
	v_rcp_f32_e32 v107, v107
	v_rcp_f32_e32 v100, v100
	v_rcp_f32_e32 v101, v101
	v_pk_mul_f32 v[50:51], v[54:55], v[50:51]
	v_pk_mul_f32 v[96:97], v[96:97], v[106:107]
	v_pk_mul_f32 v[40:41], v[44:45], v[40:41]
	v_cvt_pk_bf16_f32 v106, v96, v97
	v_pk_mul_f32 v[96:97], v[98:99], v[116:117] op_sel_hi:[1,0]
	v_pk_mul_f32 v[42:43], v[46:47], v[42:43]
	v_pk_mul_f32 v[96:97], v[96:97], v[100:101]
	v_pk_mul_f32 v[32:33], v[36:37], v[32:33]
	v_cvt_pk_bf16_f32 v107, v96, v97
	ds_read_b128 v[96:99], v156 offset:512
	v_pk_mul_f32 v[34:35], v[38:39], v[34:35]
	v_pk_mul_f32 v[24:25], v[28:29], v[24:25]
	v_pk_mul_f32 v[26:27], v[30:31], v[26:27]
	v_pk_mul_f32 v[16:17], v[20:21], v[16:17]
	s_waitcnt lgkmcnt(0)
	v_mov_b32_e32 v100, v97
	v_mov_b32_e32 v101, v98
	v_mov_b32_e32 v97, v99
	v_pk_add_f32 v[96:97], v[100:101], v[96:97]
	v_pk_mul_f32 v[18:19], v[22:23], v[18:19]
	v_add_f32_e32 v96, v96, v97
	v_fmamk_f32 v96, v96, 0x3a800000, v171
	v_mul_f32_e32 v97, 0x4b800000, v96
	v_cmp_gt_f32_e32 vcc, s48, v96
	v_pk_mul_f32 v[8:9], v[12:13], v[8:9]
	v_pk_mul_f32 v[10:11], v[14:15], v[10:11]
	v_cndmask_b32_e32 v96, v96, v97, vcc
	v_rsq_f32_e32 v98, v96
	v_or_b32_e32 v96, 16, v114
	v_mad_i64_i32 v[96:97], s[8:9], v96, s45, v[142:143]
	v_mul_f32_e32 v99, 0x45800000, v98
	v_cndmask_b32_e32 v99, v98, v99, vcc
	v_mul_f32_e32 v98, 0xbfb8aa3b, v99
	v_pk_mul_f32 v[100:101], v[92:93], v[98:99] op_sel_hi:[1,0]
	v_pk_mul_f32 v[92:93], v[94:95], v[98:99] op_sel_hi:[1,0]
	v_exp_f32_e32 v100, v100
	v_exp_f32_e32 v92, v92
	v_exp_f32_e32 v93, v93
	v_exp_f32_e32 v101, v101
	v_lshl_add_u64 v[96:97], v[96:97], 0, v[112:113]
	global_store_dwordx4 v[96:97], v[104:107], off
	v_pk_add_f32 v[92:93], v[92:93], 1.0 op_sel_hi:[1,0]
	v_pk_add_f32 v[100:101], v[100:101], 1.0 op_sel_hi:[1,0]
	v_rcp_f32_e32 v92, v92
	v_rcp_f32_e32 v93, v93
	v_mul_f32_e32 v96, v99, v99
	v_rcp_f32_e32 v100, v100
	v_rcp_f32_e32 v101, v101
	v_pk_mul_f32 v[94:95], v[84:85], v[98:99] op_sel_hi:[1,0]
	v_pk_mul_f32 v[90:91], v[90:91], v[96:97] op_sel_hi:[1,0]
	v_exp_f32_e32 v94, v94
	v_exp_f32_e32 v95, v95
	v_pk_mul_f32 v[90:91], v[90:91], v[92:93]
	v_pk_mul_f32 v[92:93], v[86:87], v[98:99] op_sel_hi:[1,0]
	v_pk_mul_f32 v[88:89], v[88:89], v[96:97] op_sel_hi:[1,0]
	v_exp_f32_e32 v92, v92
	v_exp_f32_e32 v93, v93
	v_pk_mul_f32 v[88:89], v[88:89], v[100:101]
	v_pk_mul_f32 v[80:81], v[80:81], v[96:97] op_sel_hi:[1,0]
	v_cvt_pk_bf16_f32 v88, v88, v89
	v_cvt_pk_bf16_f32 v89, v90, v91
	v_pk_add_f32 v[90:91], v[94:95], 1.0 op_sel_hi:[1,0]
	v_pk_add_f32 v[84:85], v[92:93], 1.0 op_sel_hi:[1,0]
	v_rcp_f32_e32 v90, v90
	v_rcp_f32_e32 v91, v91
	v_rcp_f32_e32 v84, v84
	v_rcp_f32_e32 v85, v85
	v_pk_mul_f32 v[0:1], v[4:5], v[0:1]
	v_pk_mul_f32 v[80:81], v[80:81], v[90:91]
	v_pk_mul_f32 v[2:3], v[6:7], v[2:3]
	v_cvt_pk_bf16_f32 v90, v80, v81
	v_pk_mul_f32 v[80:81], v[82:83], v[96:97] op_sel_hi:[1,0]
	s_nop 0
	v_pk_mul_f32 v[80:81], v[80:81], v[84:85]
	s_nop 0
	v_cvt_pk_bf16_f32 v91, v80, v81
	ds_read_b128 v[80:83], v156 offset:768
	s_waitcnt lgkmcnt(0)
	v_mov_b32_e32 v84, v81
	v_mov_b32_e32 v85, v82
	v_mov_b32_e32 v81, v83
	v_pk_add_f32 v[80:81], v[84:85], v[80:81]
	s_nop 0
	v_add_f32_e32 v80, v80, v81
	v_fmamk_f32 v80, v80, 0x3a800000, v171
	v_mul_f32_e32 v81, 0x4b800000, v80
	v_cmp_gt_f32_e32 vcc, s48, v80
	s_nop 1
	v_cndmask_b32_e32 v80, v80, v81, vcc
	v_rsq_f32_e32 v82, v80
	v_or_b32_e32 v80, 32, v114
	v_mad_i64_i32 v[80:81], s[8:9], v80, s45, v[142:143]
	v_mul_f32_e32 v83, 0x45800000, v82
	v_cndmask_b32_e32 v83, v82, v83, vcc
	v_mul_f32_e32 v82, 0xbfb8aa3b, v83
	v_pk_mul_f32 v[84:85], v[76:77], v[82:83] op_sel_hi:[1,0]
	v_pk_mul_f32 v[76:77], v[78:79], v[82:83] op_sel_hi:[1,0]
	v_exp_f32_e32 v84, v84
	v_exp_f32_e32 v76, v76
	v_exp_f32_e32 v77, v77
	v_exp_f32_e32 v85, v85
	v_lshl_add_u64 v[80:81], v[80:81], 0, v[112:113]
	global_store_dwordx4 v[80:81], v[88:91], off
	v_pk_add_f32 v[76:77], v[76:77], 1.0 op_sel_hi:[1,0]
	v_pk_add_f32 v[84:85], v[84:85], 1.0 op_sel_hi:[1,0]
	v_rcp_f32_e32 v76, v76
	v_rcp_f32_e32 v77, v77
	v_mul_f32_e32 v80, v83, v83
	v_rcp_f32_e32 v84, v84
	v_rcp_f32_e32 v85, v85
	v_pk_mul_f32 v[78:79], v[68:69], v[82:83] op_sel_hi:[1,0]
	v_pk_mul_f32 v[74:75], v[74:75], v[80:81] op_sel_hi:[1,0]
	v_exp_f32_e32 v78, v78
	v_exp_f32_e32 v79, v79
	v_pk_mul_f32 v[74:75], v[74:75], v[76:77]
	v_pk_mul_f32 v[76:77], v[70:71], v[82:83] op_sel_hi:[1,0]
	v_pk_mul_f32 v[72:73], v[72:73], v[80:81] op_sel_hi:[1,0]
	v_exp_f32_e32 v76, v76
	v_exp_f32_e32 v77, v77
	v_pk_mul_f32 v[72:73], v[72:73], v[84:85]
	v_pk_mul_f32 v[64:65], v[64:65], v[80:81] op_sel_hi:[1,0]
	v_cvt_pk_bf16_f32 v72, v72, v73
	v_cvt_pk_bf16_f32 v73, v74, v75
	v_pk_add_f32 v[74:75], v[78:79], 1.0 op_sel_hi:[1,0]
	v_pk_add_f32 v[68:69], v[76:77], 1.0 op_sel_hi:[1,0]
	v_rcp_f32_e32 v74, v74
	v_rcp_f32_e32 v75, v75
	v_rcp_f32_e32 v68, v68
	v_rcp_f32_e32 v69, v69
	v_pk_mul_f32 v[64:65], v[64:65], v[74:75]
	s_nop 0
	v_cvt_pk_bf16_f32 v74, v64, v65
	v_pk_mul_f32 v[64:65], v[66:67], v[80:81] op_sel_hi:[1,0]
	s_nop 0
	v_pk_mul_f32 v[64:65], v[64:65], v[68:69]
	s_nop 0
	v_cvt_pk_bf16_f32 v75, v64, v65
	ds_read_b128 v[64:67], v156 offset:2048
	s_waitcnt lgkmcnt(0)
	v_mov_b32_e32 v68, v65
	v_mov_b32_e32 v69, v66
	v_mov_b32_e32 v65, v67
	v_pk_add_f32 v[64:65], v[68:69], v[64:65]
	s_nop 0
	v_add_f32_e32 v64, v64, v65
	v_fmamk_f32 v64, v64, 0x3a800000, v171
	v_mul_f32_e32 v65, 0x4b800000, v64
	v_cmp_gt_f32_e32 vcc, s48, v64
	s_nop 1
	v_cndmask_b32_e32 v64, v64, v65, vcc
	v_rsq_f32_e32 v66, v64
	v_or_b32_e32 v64, 48, v114
	v_mad_i64_i32 v[64:65], s[8:9], v64, s45, v[142:143]
	v_mul_f32_e32 v67, 0x45800000, v66
	v_cndmask_b32_e32 v67, v66, v67, vcc
	v_mul_f32_e32 v66, 0xbfb8aa3b, v67
	v_pk_mul_f32 v[68:69], v[60:61], v[66:67] op_sel_hi:[1,0]
	v_pk_mul_f32 v[60:61], v[62:63], v[66:67] op_sel_hi:[1,0]
	v_exp_f32_e32 v68, v68
	v_exp_f32_e32 v60, v60
	v_exp_f32_e32 v61, v61
	v_exp_f32_e32 v69, v69
	v_lshl_add_u64 v[64:65], v[64:65], 0, v[112:113]
	global_store_dwordx4 v[64:65], v[72:75], off
	v_pk_add_f32 v[60:61], v[60:61], 1.0 op_sel_hi:[1,0]
	v_pk_add_f32 v[68:69], v[68:69], 1.0 op_sel_hi:[1,0]
	v_rcp_f32_e32 v60, v60
	v_rcp_f32_e32 v61, v61
	v_mul_f32_e32 v64, v67, v67
	v_rcp_f32_e32 v68, v68
	v_rcp_f32_e32 v69, v69
	v_pk_mul_f32 v[62:63], v[52:53], v[66:67] op_sel_hi:[1,0]
	v_pk_mul_f32 v[58:59], v[58:59], v[64:65] op_sel_hi:[1,0]
	v_exp_f32_e32 v62, v62
	v_exp_f32_e32 v63, v63
	v_pk_mul_f32 v[58:59], v[58:59], v[60:61]
	v_pk_mul_f32 v[60:61], v[54:55], v[66:67] op_sel_hi:[1,0]
	v_pk_mul_f32 v[56:57], v[56:57], v[64:65] op_sel_hi:[1,0]
	v_exp_f32_e32 v60, v60
	v_exp_f32_e32 v61, v61
	v_pk_mul_f32 v[56:57], v[56:57], v[68:69]
	v_pk_mul_f32 v[48:49], v[48:49], v[64:65] op_sel_hi:[1,0]
	v_cvt_pk_bf16_f32 v56, v56, v57
	v_cvt_pk_bf16_f32 v57, v58, v59
	v_pk_add_f32 v[58:59], v[62:63], 1.0 op_sel_hi:[1,0]
	v_pk_add_f32 v[52:53], v[60:61], 1.0 op_sel_hi:[1,0]
	v_rcp_f32_e32 v58, v58
	v_rcp_f32_e32 v59, v59
	v_rcp_f32_e32 v52, v52
	v_rcp_f32_e32 v53, v53
	v_pk_mul_f32 v[48:49], v[48:49], v[58:59]
	s_nop 0
	v_cvt_pk_bf16_f32 v58, v48, v49
	v_pk_mul_f32 v[48:49], v[50:51], v[64:65] op_sel_hi:[1,0]
	s_nop 0
	v_pk_mul_f32 v[48:49], v[48:49], v[52:53]
	s_nop 0
	v_cvt_pk_bf16_f32 v59, v48, v49
	ds_read_b128 v[48:51], v156 offset:2304
	s_waitcnt lgkmcnt(0)
	v_mov_b32_e32 v52, v49
	v_mov_b32_e32 v53, v50
	v_mov_b32_e32 v49, v51
	v_pk_add_f32 v[48:49], v[52:53], v[48:49]
	s_nop 0
	v_add_f32_e32 v48, v48, v49
	v_fmamk_f32 v48, v48, 0x3a800000, v171
	v_mul_f32_e32 v49, 0x4b800000, v48
	v_cmp_gt_f32_e32 vcc, s48, v48
	s_nop 1
	v_cndmask_b32_e32 v48, v48, v49, vcc
	v_rsq_f32_e32 v50, v48
	v_add_u32_e32 v48, 0x80, v114
	v_mad_i64_i32 v[48:49], s[8:9], v48, s45, v[142:143]
	v_mul_f32_e32 v51, 0x45800000, v50
	v_cndmask_b32_e32 v51, v50, v51, vcc
	v_mul_f32_e32 v50, 0xbfb8aa3b, v51
	v_pk_mul_f32 v[52:53], v[44:45], v[50:51] op_sel_hi:[1,0]
	v_pk_mul_f32 v[44:45], v[46:47], v[50:51] op_sel_hi:[1,0]
	v_exp_f32_e32 v52, v52
	v_exp_f32_e32 v44, v44
	v_exp_f32_e32 v45, v45
	v_exp_f32_e32 v53, v53
	v_lshl_add_u64 v[48:49], v[48:49], 0, v[112:113]
	global_store_dwordx4 v[48:49], v[56:59], off
	v_pk_add_f32 v[44:45], v[44:45], 1.0 op_sel_hi:[1,0]
	v_pk_add_f32 v[52:53], v[52:53], 1.0 op_sel_hi:[1,0]
	v_rcp_f32_e32 v44, v44
	v_rcp_f32_e32 v45, v45
	v_mul_f32_e32 v48, v51, v51
	v_rcp_f32_e32 v52, v52
	v_rcp_f32_e32 v53, v53
	v_pk_mul_f32 v[46:47], v[36:37], v[50:51] op_sel_hi:[1,0]
	v_pk_mul_f32 v[42:43], v[42:43], v[48:49] op_sel_hi:[1,0]
	v_exp_f32_e32 v46, v46
	v_exp_f32_e32 v47, v47
	v_pk_mul_f32 v[42:43], v[42:43], v[44:45]
	v_pk_mul_f32 v[44:45], v[38:39], v[50:51] op_sel_hi:[1,0]
	v_pk_mul_f32 v[40:41], v[40:41], v[48:49] op_sel_hi:[1,0]
	v_exp_f32_e32 v44, v44
	v_exp_f32_e32 v45, v45
	v_pk_mul_f32 v[40:41], v[40:41], v[52:53]
	v_pk_mul_f32 v[32:33], v[32:33], v[48:49] op_sel_hi:[1,0]
	v_cvt_pk_bf16_f32 v40, v40, v41
	v_cvt_pk_bf16_f32 v41, v42, v43
	v_pk_add_f32 v[42:43], v[46:47], 1.0 op_sel_hi:[1,0]
	v_pk_add_f32 v[36:37], v[44:45], 1.0 op_sel_hi:[1,0]
	v_rcp_f32_e32 v42, v42
	v_rcp_f32_e32 v43, v43
	v_rcp_f32_e32 v36, v36
	v_rcp_f32_e32 v37, v37
	v_pk_mul_f32 v[32:33], v[32:33], v[42:43]
	s_nop 0
	v_cvt_pk_bf16_f32 v42, v32, v33
	v_pk_mul_f32 v[32:33], v[34:35], v[48:49] op_sel_hi:[1,0]
	s_nop 0
	v_pk_mul_f32 v[32:33], v[32:33], v[36:37]
	s_nop 0
	v_cvt_pk_bf16_f32 v43, v32, v33
	ds_read_b128 v[32:35], v156 offset:2560
	s_waitcnt lgkmcnt(0)
	v_mov_b32_e32 v36, v33
	v_mov_b32_e32 v37, v34
	v_mov_b32_e32 v33, v35
	v_pk_add_f32 v[32:33], v[36:37], v[32:33]
	s_nop 0
	v_add_f32_e32 v32, v32, v33
	v_fmamk_f32 v32, v32, 0x3a800000, v171
	v_mul_f32_e32 v33, 0x4b800000, v32
	v_cmp_gt_f32_e32 vcc, s48, v32
	s_nop 1
	v_cndmask_b32_e32 v32, v32, v33, vcc
	v_rsq_f32_e32 v34, v32
	v_add_u32_e32 v32, 0x90, v114
	v_mad_i64_i32 v[32:33], s[8:9], v32, s45, v[142:143]
	v_mul_f32_e32 v35, 0x45800000, v34
	v_cndmask_b32_e32 v35, v34, v35, vcc
	v_mul_f32_e32 v34, 0xbfb8aa3b, v35
	v_pk_mul_f32 v[36:37], v[28:29], v[34:35] op_sel_hi:[1,0]
	v_pk_mul_f32 v[28:29], v[30:31], v[34:35] op_sel_hi:[1,0]
	v_exp_f32_e32 v36, v36
	v_exp_f32_e32 v28, v28
	v_exp_f32_e32 v29, v29
	v_exp_f32_e32 v37, v37
	v_lshl_add_u64 v[32:33], v[32:33], 0, v[112:113]
	global_store_dwordx4 v[32:33], v[40:43], off
	v_pk_add_f32 v[28:29], v[28:29], 1.0 op_sel_hi:[1,0]
	v_pk_add_f32 v[36:37], v[36:37], 1.0 op_sel_hi:[1,0]
	v_rcp_f32_e32 v28, v28
	v_rcp_f32_e32 v29, v29
	v_mul_f32_e32 v32, v35, v35
	v_rcp_f32_e32 v36, v36
	v_rcp_f32_e32 v37, v37
	v_pk_mul_f32 v[30:31], v[20:21], v[34:35] op_sel_hi:[1,0]
	v_pk_mul_f32 v[26:27], v[26:27], v[32:33] op_sel_hi:[1,0]
	v_exp_f32_e32 v30, v30
	v_exp_f32_e32 v31, v31
	v_pk_mul_f32 v[26:27], v[26:27], v[28:29]
	v_pk_mul_f32 v[28:29], v[22:23], v[34:35] op_sel_hi:[1,0]
	v_pk_mul_f32 v[24:25], v[24:25], v[32:33] op_sel_hi:[1,0]
	v_exp_f32_e32 v28, v28
	v_exp_f32_e32 v29, v29
	v_pk_mul_f32 v[24:25], v[24:25], v[36:37]
	v_pk_mul_f32 v[16:17], v[16:17], v[32:33] op_sel_hi:[1,0]
	v_cvt_pk_bf16_f32 v24, v24, v25
	v_cvt_pk_bf16_f32 v25, v26, v27
	v_pk_add_f32 v[26:27], v[30:31], 1.0 op_sel_hi:[1,0]
	v_pk_add_f32 v[20:21], v[28:29], 1.0 op_sel_hi:[1,0]
	v_rcp_f32_e32 v26, v26
	v_rcp_f32_e32 v27, v27
	v_rcp_f32_e32 v20, v20
	v_rcp_f32_e32 v21, v21
	v_pk_mul_f32 v[16:17], v[16:17], v[26:27]
	s_nop 0
	v_cvt_pk_bf16_f32 v26, v16, v17
	v_pk_mul_f32 v[16:17], v[18:19], v[32:33] op_sel_hi:[1,0]
	s_nop 0
	v_pk_mul_f32 v[16:17], v[16:17], v[20:21]
	v_add_u32_e32 v20, 0xa0, v114
	v_cvt_pk_bf16_f32 v27, v16, v17
	ds_read_b128 v[16:19], v156 offset:2816
	v_mad_i64_i32 v[20:21], s[8:9], v20, s45, v[142:143]
	s_waitcnt lgkmcnt(0)
	v_mov_b32_e32 v22, v17
	v_mov_b32_e32 v23, v18
	v_mov_b32_e32 v17, v19
	v_pk_add_f32 v[16:17], v[22:23], v[16:17]
	s_nop 0
	v_add_f32_e32 v16, v16, v17
	v_fmamk_f32 v16, v16, 0x3a800000, v171
	v_mul_f32_e32 v17, 0x4b800000, v16
	v_cmp_gt_f32_e32 vcc, s48, v16
	s_nop 1
	v_cndmask_b32_e32 v16, v16, v17, vcc
	v_rsq_f32_e32 v18, v16
	v_lshl_add_u64 v[16:17], v[20:21], 0, v[112:113]
	global_store_dwordx4 v[16:17], v[24:27], off
	v_add_u32_e32 v17, 0xb0, v114
	v_mul_f32_e32 v16, 0x45800000, v18
	v_cndmask_b32_e32 v22, v18, v16, vcc
	v_mul_f32_e32 v16, 0xbfb8aa3b, v22
	v_pk_mul_f32 v[18:19], v[12:13], v[16:17] op_sel_hi:[1,0]
	v_pk_mul_f32 v[12:13], v[14:15], v[16:17] op_sel_hi:[1,0]
	v_exp_f32_e32 v18, v18
	v_exp_f32_e32 v12, v12
	v_exp_f32_e32 v13, v13
	v_exp_f32_e32 v19, v19
	v_mul_f32_e32 v22, v22, v22
	v_pk_mul_f32 v[14:15], v[4:5], v[16:17] op_sel_hi:[1,0]
	v_pk_add_f32 v[12:13], v[12:13], 1.0 op_sel_hi:[1,0]
	v_pk_add_f32 v[18:19], v[18:19], 1.0 op_sel_hi:[1,0]
	v_rcp_f32_e32 v12, v12
	v_rcp_f32_e32 v13, v13
	v_rcp_f32_e32 v18, v18
	v_rcp_f32_e32 v19, v19
	v_exp_f32_e32 v14, v14
	v_exp_f32_e32 v15, v15
	v_pk_mul_f32 v[10:11], v[10:11], v[22:23] op_sel_hi:[1,0]
	v_pk_mul_f32 v[8:9], v[8:9], v[22:23] op_sel_hi:[1,0]
	v_pk_mul_f32 v[10:11], v[10:11], v[12:13]
	v_pk_mul_f32 v[12:13], v[6:7], v[16:17] op_sel_hi:[1,0]
	v_pk_mul_f32 v[8:9], v[8:9], v[18:19]
	v_exp_f32_e32 v12, v12
	v_exp_f32_e32 v13, v13
	v_cvt_pk_bf16_f32 v8, v8, v9
	v_cvt_pk_bf16_f32 v9, v10, v11
	v_pk_add_f32 v[10:11], v[14:15], 1.0 op_sel_hi:[1,0]
	v_pk_add_f32 v[4:5], v[12:13], 1.0 op_sel_hi:[1,0]
	v_rcp_f32_e32 v10, v10
	v_rcp_f32_e32 v11, v11
	v_rcp_f32_e32 v4, v4
	v_rcp_f32_e32 v5, v5
	v_pk_mul_f32 v[0:1], v[0:1], v[22:23] op_sel_hi:[1,0]
	v_mad_i64_i32 v[20:21], s[8:9], v17, s45, v[142:143]
	v_pk_mul_f32 v[0:1], v[0:1], v[10:11]
	s_andn2_b64 vcc, exec, s[6:7]
	v_cvt_pk_bf16_f32 v10, v0, v1
	v_pk_mul_f32 v[0:1], v[2:3], v[22:23] op_sel_hi:[1,0]
	s_mov_b64 s[6:7], -1
	v_pk_mul_f32 v[0:1], v[0:1], v[4:5]
	s_nop 0
	v_cvt_pk_bf16_f32 v11, v0, v1
	v_lshl_add_u64 v[0:1], v[20:21], 0, v[112:113]
	global_store_dwordx4 v[0:1], v[8:11], off
	s_mov_b32 s100, 1
	s_cbranch_vccnz .LBB0_1352
	s_andn2_b64 vcc, exec, s[12:13]
	s_cbranch_vccnz .LBB0_1351
	s_barrier
	s_branch .LBB0_1351
